# all three residual/RMSNorm elementwise phases fused into the preceding GEMM epilogues (P2,P7,P10: hand-written two-stage epilogues with per-unit team barrier, next phase's row scales from partial sums
# speedup vs baseline: 1.0170x; 1.0044x over previous
; __device__ __forceinline__ unsigned pk2(float lo, float hi) { bf16x2_t r = __builtin_convertvector((f32x2_t){lo, hi}, bf16x2_t); return __builtin_bit_cast(unsigned, r); }
;     __device__ __forceinline__ void operator()(const pg8::f32x4 (&acc)[2][2][4][2], const pg8::Unit& u, int wr, int wc, int fr, int fq) const {
;     ...
;                     if (PART) {
; #pragma unroll
;                         for (int j = 0; j < 8; ++j) s += r[j] * r[j];
;                     }
;                     v4u w; w.x = pk2(r[0], r[1]); w.y = pk2(r[2], r[3]); w.z = pk2(r[4], r[5]); w.w = pk2(r[6], r[7]);
;                     st16_wt(O + off + bj * 128, w);
;                 }
;                 if (PART) { s += __shfl_xor(s, 16); s += __shfl_xor(s, 32); st4_wt(part + (size_t)row * 16 + u.pn * 4 + wc, s); }
.LBB0_332:
	s_waitcnt lgkmcnt(0)
	v_lshl_or_b32 v242, s62, 8, v148
	v_lshl_add_u32 v243, s61, 8, v146
	v_lshlrev_b32_e32 v246, 2, v242
	v_lshlrev_b32_e32 v153, 1, v242
	v_lshl_add_u32 v153, v243, 11, v153
	v_xor_b32_e32 v166, 16, v152
	v_lshlrev_b32_e32 v166, 2, v166
	v_xor_b32_e32 v168, 32, v152
	v_lshlrev_b32_e32 v168, 2, v168
	v_lshrrev_b32_e32 v161, 4, v152
	v_and_b32_e32 v161, 3, v161
	v_lshlrev_b32_e32 v161, 4, v161
	v_lshl_add_u32 v161, v243, 6, v161
	s_lshl_b32 s95, s62, 4
	s_add_u32 s95, s95, s14
	v_lshl_add_u32 v157, v243, 6, s95
	v_pk_mul_f32 v[242:243], v[124:125], v[124:125]
	v_pk_fma_f32 v[242:243], v[126:127], v[126:127], v[242:243]
	v_pk_fma_f32 v[242:243], v[120:121], v[120:121], v[242:243]
	v_pk_fma_f32 v[242:243], v[122:123], v[122:123], v[242:243]
	v_pk_fma_f32 v[242:243], v[116:117], v[116:117], v[242:243]
	v_pk_fma_f32 v[242:243], v[118:119], v[118:119], v[242:243]
	v_pk_fma_f32 v[242:243], v[112:113], v[112:113], v[242:243]
	v_pk_fma_f32 v[242:243], v[114:115], v[114:115], v[242:243]
	v_add_f32_e32 v145, v242, v243
	v_pk_mul_f32 v[244:245], v[108:109], v[108:109]
	v_pk_fma_f32 v[244:245], v[110:111], v[110:111], v[244:245]
	v_pk_fma_f32 v[244:245], v[104:105], v[104:105], v[244:245]
	v_pk_fma_f32 v[244:245], v[106:107], v[106:107], v[244:245]
	v_pk_fma_f32 v[244:245], v[100:101], v[100:101], v[244:245]
	v_pk_fma_f32 v[244:245], v[102:103], v[102:103], v[244:245]
	v_pk_fma_f32 v[244:245], v[96:97], v[96:97], v[244:245]
	v_pk_fma_f32 v[244:245], v[98:99], v[98:99], v[244:245]
	v_add_f32_e32 v155, v244, v245
	v_pk_mul_f32 v[242:243], v[92:93], v[92:93]
	v_pk_fma_f32 v[242:243], v[94:95], v[94:95], v[242:243]
	v_pk_fma_f32 v[242:243], v[88:89], v[88:89], v[242:243]
	v_pk_fma_f32 v[242:243], v[90:91], v[90:91], v[242:243]
	v_pk_fma_f32 v[242:243], v[84:85], v[84:85], v[242:243]
	v_pk_fma_f32 v[242:243], v[86:87], v[86:87], v[242:243]
	v_pk_fma_f32 v[242:243], v[80:81], v[80:81], v[242:243]
	v_pk_fma_f32 v[242:243], v[82:83], v[82:83], v[242:243]
	v_add_f32_e32 v159, v242, v243
	v_pk_mul_f32 v[244:245], v[76:77], v[76:77]
	v_pk_fma_f32 v[244:245], v[78:79], v[78:79], v[244:245]
	v_pk_fma_f32 v[244:245], v[72:73], v[72:73], v[244:245]
	v_pk_fma_f32 v[244:245], v[74:75], v[74:75], v[244:245]
	v_pk_fma_f32 v[244:245], v[68:69], v[68:69], v[244:245]
	v_pk_fma_f32 v[244:245], v[70:71], v[70:71], v[244:245]
	v_pk_fma_f32 v[244:245], v[64:65], v[64:65], v[244:245]
	v_pk_fma_f32 v[244:245], v[66:67], v[66:67], v[244:245]
	v_add_f32_e32 v163, v244, v245
	v_pk_mul_f32 v[242:243], v[60:61], v[60:61]
	v_pk_fma_f32 v[242:243], v[62:63], v[62:63], v[242:243]
	v_pk_fma_f32 v[242:243], v[56:57], v[56:57], v[242:243]
	v_pk_fma_f32 v[242:243], v[58:59], v[58:59], v[242:243]
	v_pk_fma_f32 v[242:243], v[52:53], v[52:53], v[242:243]
	v_pk_fma_f32 v[242:243], v[54:55], v[54:55], v[242:243]
	v_pk_fma_f32 v[242:243], v[48:49], v[48:49], v[242:243]
	v_pk_fma_f32 v[242:243], v[50:51], v[50:51], v[242:243]
	v_add_f32_e32 v165, v242, v243
	v_pk_mul_f32 v[244:245], v[44:45], v[44:45]
	v_pk_fma_f32 v[244:245], v[46:47], v[46:47], v[244:245]
	v_pk_fma_f32 v[244:245], v[40:41], v[40:41], v[244:245]
	v_pk_fma_f32 v[244:245], v[42:43], v[42:43], v[244:245]
	v_pk_fma_f32 v[244:245], v[36:37], v[36:37], v[244:245]
	v_pk_fma_f32 v[244:245], v[38:39], v[38:39], v[244:245]
	v_pk_fma_f32 v[244:245], v[32:33], v[32:33], v[244:245]
	v_pk_fma_f32 v[244:245], v[34:35], v[34:35], v[244:245]
	v_add_f32_e32 v171, v244, v245
	v_pk_mul_f32 v[242:243], v[28:29], v[28:29]
	v_pk_fma_f32 v[242:243], v[30:31], v[30:31], v[242:243]
	v_pk_fma_f32 v[242:243], v[24:25], v[24:25], v[242:243]
	v_pk_fma_f32 v[242:243], v[26:27], v[26:27], v[242:243]
	v_pk_fma_f32 v[242:243], v[20:21], v[20:21], v[242:243]
	v_pk_fma_f32 v[242:243], v[22:23], v[22:23], v[242:243]
	v_pk_fma_f32 v[242:243], v[16:17], v[16:17], v[242:243]
	v_pk_fma_f32 v[242:243], v[18:19], v[18:19], v[242:243]
	v_add_f32_e32 v193, v242, v243
	v_pk_mul_f32 v[244:245], v[12:13], v[12:13]
	v_pk_fma_f32 v[244:245], v[14:15], v[14:15], v[244:245]
	v_pk_fma_f32 v[244:245], v[8:9], v[8:9], v[244:245]
	v_pk_fma_f32 v[244:245], v[10:11], v[10:11], v[244:245]
	v_pk_fma_f32 v[244:245], v[4:5], v[4:5], v[244:245]
	v_pk_fma_f32 v[244:245], v[6:7], v[6:7], v[244:245]
	v_pk_fma_f32 v[244:245], v[0:1], v[0:1], v[244:245]
	v_pk_fma_f32 v[244:245], v[2:3], v[2:3], v[244:245]
	v_add_f32_e32 v241, v244, v245
	s_nop 1
	ds_bpermute_b32 v188, v166, v145
	ds_bpermute_b32 v196, v166, v155
	ds_bpermute_b32 v200, v166, v159
	ds_bpermute_b32 v204, v166, v163
	ds_bpermute_b32 v208, v166, v165
	ds_bpermute_b32 v212, v166, v171
	ds_bpermute_b32 v216, v166, v193
	ds_bpermute_b32 v220, v166, v241
	s_waitcnt lgkmcnt(0)
	v_add_f32_e32 v145, v145, v188
	v_add_f32_e32 v155, v155, v196
	v_add_f32_e32 v159, v159, v200
	v_add_f32_e32 v163, v163, v204
	v_add_f32_e32 v165, v165, v208
	v_add_f32_e32 v171, v171, v212
	v_add_f32_e32 v193, v193, v216
	v_add_f32_e32 v241, v241, v220
	s_nop 1
	ds_bpermute_b32 v188, v168, v145
	ds_bpermute_b32 v196, v168, v155
	ds_bpermute_b32 v200, v168, v159
	ds_bpermute_b32 v204, v168, v163
	ds_bpermute_b32 v208, v168, v165
	ds_bpermute_b32 v212, v168, v171
	ds_bpermute_b32 v216, v168, v193
	ds_bpermute_b32 v220, v168, v241
	s_waitcnt lgkmcnt(0)
	v_add_f32_e32 v145, v145, v188
	v_add_f32_e32 v155, v155, v196
	v_add_f32_e32 v159, v159, v200
	v_add_f32_e32 v163, v163, v204
	v_add_f32_e32 v165, v165, v208
	v_add_f32_e32 v171, v171, v212
	v_add_f32_e32 v193, v193, v216
	v_add_f32_e32 v241, v241, v220
	global_store_dword v157, v145, s[20:21]
	v_add_u32_e32 v196, 0x400, v157
	global_store_dword v196, v155, s[20:21]
	v_add_u32_e32 v200, 0x800, v157
	global_store_dword v200, v159, s[20:21]
	v_add_u32_e32 v204, 0xc00, v157
	global_store_dword v204, v163, s[20:21]
	v_add_u32_e32 v208, 0x2000, v157
	global_store_dword v208, v165, s[20:21]
	v_add_u32_e32 v212, 0x2400, v157
	global_store_dword v212, v171, s[20:21]
	v_add_u32_e32 v216, 0x2800, v157
	global_store_dword v216, v193, s[20:21]
	v_add_u32_e32 v220, 0x2c00, v157
	global_store_dword v220, v241, s[20:21]
	s_waitcnt vmcnt(0)
	s_barrier
	v_readfirstlane_b32 s94, v195
	s_cmp_lg_u32 s94, 0
	s_cbranch_scc1 .Lfe0_bskip
	s_mov_b64 exec, 1
	s_and_b32 s94, s2, 7
	s_lshl_b32 s94, s94, 3
	s_bfe_u32 s96, s2, 0x30003
	s_or_b32 s94, s94, s96
	s_lshl_b32 s94, s94, 5
	s_add_u32 s62, s28, 0x3903600
	s_addc_u32 s63, s29, 0
	v_mov_b32_e32 v242, s94
	v_mov_b32_e32 v243, 1
	s_cmp_eq_u32 s99, 1
	s_cbranch_scc1 .Lfe0_bfast
	buffer_wbl2 sc1
	s_waitcnt vmcnt(0)
.Lfe0_bfast:
	global_atomic_add v244, v242, v243, s[62:63] offset:8 sc0
	buffer_inv sc1
	s_waitcnt vmcnt(0)
	v_lshrrev_b32_e32 v244, 2, v244
	v_add_u32_e32 v244, 1, v244
	v_lshlrev_b32_e32 v244, 2, v244
	s_mov_b32 s94, 0
.Lfe0_bspin:
	global_load_dword v245, v242, s[62:63] offset:8 sc1
	s_waitcnt vmcnt(0)
	v_cmp_ge_u32_e32 vcc, v245, v244
	s_cbranch_vccnz .Lfe0_bdone
	s_sleep 1
	s_add_u32 s94, s94, 1
	s_cmp_lt_u32 s94, 0x400000
	s_cbranch_scc1 .Lfe0_bspin

; template <bool SRC_F32, int R> __device__ __forceinline__ void ew_load(EwSet<SRC_F32, R>& S, int rb, const float* hsrc32, const bf16* hsrcb, const bf16* f, const float* part, int lane) {
;     ...
;     for (int i = 0; i < R; ++i) S.p[i] = (lane < 16) ? part[(size_t)(rb + i) * 16 + lane] : 0.f;
; #pragma unroll
;     for (int i = 0; i < R; ++i)
; #pragma unroll
;         for (int j = 0; j < 4; ++j) {
;             S.fw[i][j] = ((const v2u*)(f + (size_t)(rb + i) * D) + lane)[64 * j];
;             if constexpr (SRC_F32) S.h32[i][j] = __builtin_nontemporal_load((const f32x4*)(hsrc32 + (size_t)(rb + i) * D) + lane + 64 * j);
;             else S.hb[i][j] = ((const v2u*)(hsrcb + (size_t)(rb + i) * D) + lane)[64 * j];
;         }
; }
; template <bool SRC_F32, bool FINAL, int R> __device__ __forceinline__ void ew_compute(const EwSet<SRC_F32, R>& S, int rb, const f32x4 (&g)[4], bf16* hb_out, float* out32, float scale, float* rs_out, int lane) {
; #pragma unroll
;     for (int i = 0; i < R; ++i) {
;         float q = S.p[i];
;         q += __shfl_xor(q, 1); q += __shfl_xor(q, 2); q += __shfl_xor(q, 4); q += __shfl_xor(q, 8);
;         const float ss = __shfl(q, 0);
;         const float rs = scale / sqrtf(ss * (1.f / D) + EPS);
.Lfe0_bskip:
	s_barrier
	s_add_u32 s62, s84, 0xffffff10
	s_addc_u32 s63, s85, -1
	s_load_dwordx2 s[64:65], s[62:63], 0x30
	s_add_u32 s66, s28, 0x5000000
	s_addc_u32 s67, s29, 0
	s_add_u32 s78, s28, 0x4c00000
	s_addc_u32 s79, s29, 0
	global_load_dwordx4 v[188:191], v161, s[20:21]
	v_add_u32_e32 v244, 0x400, v161
	global_load_dwordx4 v[196:199], v244, s[20:21]
	v_add_u32_e32 v244, 0x800, v161
	global_load_dwordx4 v[200:203], v244, s[20:21]
	v_add_u32_e32 v244, 0xc00, v161
	global_load_dwordx4 v[204:207], v244, s[20:21]
	v_add_u32_e32 v244, 0x2000, v161
	global_load_dwordx4 v[208:211], v244, s[20:21]
	v_add_u32_e32 v244, 0x2400, v161
	global_load_dwordx4 v[212:215], v244, s[20:21]
	v_add_u32_e32 v244, 0x2800, v161
	global_load_dwordx4 v[216:219], v244, s[20:21]
	v_add_u32_e32 v244, 0x2c00, v161
	global_load_dwordx4 v[220:223], v244, s[20:21]
	global_load_dwordx4 v[224:227], v153, s[66:67]
	global_load_dwordx4 v[228:231], v153, s[66:67] offset:256
	v_add_u32_e32 v244, 0x8000, v153
	global_load_dwordx4 v[232:235], v244, s[66:67]
	global_load_dwordx4 v[236:239], v244, s[66:67] offset:256
	s_waitcnt lgkmcnt(0)
	global_load_dwordx4 v[172:175], v246, s[64:65]
	global_load_dwordx4 v[176:179], v246, s[64:65] offset:16
	global_load_dwordx4 v[180:183], v246, s[64:65] offset:512
	global_load_dwordx4 v[184:187], v246, s[64:65] offset:528
	s_waitcnt vmcnt(8)
	v_add_f32_e32 v145, v188, v189
	v_add_f32_e32 v145, v190, v145
	v_add_f32_e32 v145, v191, v145
	v_add_f32_e32 v155, v196, v197
	v_add_f32_e32 v155, v198, v155
	v_add_f32_e32 v155, v199, v155
	v_add_f32_e32 v159, v200, v201
	v_add_f32_e32 v159, v202, v159
	v_add_f32_e32 v159, v203, v159
	v_add_f32_e32 v163, v204, v205
	v_add_f32_e32 v163, v206, v163
	v_add_f32_e32 v163, v207, v163
	v_add_f32_e32 v165, v208, v209
	v_add_f32_e32 v165, v210, v165
	v_add_f32_e32 v165, v211, v165
	v_add_f32_e32 v171, v212, v213
	v_add_f32_e32 v171, v214, v171
	v_add_f32_e32 v171, v215, v171
	v_add_f32_e32 v193, v216, v217
	v_add_f32_e32 v193, v218, v193
	v_add_f32_e32 v193, v219, v193
	v_add_f32_e32 v241, v220, v221
	v_add_f32_e32 v241, v222, v241
	v_add_f32_e32 v241, v223, v241
	s_nop 1
	ds_bpermute_b32 v188, v166, v145
	ds_bpermute_b32 v196, v166, v155
	ds_bpermute_b32 v200, v166, v159
	ds_bpermute_b32 v204, v166, v163
	ds_bpermute_b32 v208, v166, v165
	ds_bpermute_b32 v212, v166, v171
	ds_bpermute_b32 v216, v166, v193
	ds_bpermute_b32 v220, v166, v241
	s_waitcnt lgkmcnt(0)
	v_add_f32_e32 v145, v145, v188
	v_add_f32_e32 v155, v155, v196
	v_add_f32_e32 v159, v159, v200
	v_add_f32_e32 v163, v163, v204
	v_add_f32_e32 v165, v165, v208
	v_add_f32_e32 v171, v171, v212
	v_add_f32_e32 v193, v193, v216
	v_add_f32_e32 v241, v241, v220
	s_nop 1
	ds_bpermute_b32 v188, v168, v145
	ds_bpermute_b32 v196, v168, v155
	ds_bpermute_b32 v200, v168, v159
	ds_bpermute_b32 v204, v168, v163
	ds_bpermute_b32 v208, v168, v165
	ds_bpermute_b32 v212, v168, v171
	ds_bpermute_b32 v216, v168, v193
	ds_bpermute_b32 v220, v168, v241
	s_waitcnt lgkmcnt(0)
	v_add_f32_e32 v145, v145, v188
	v_add_f32_e32 v155, v155, v196
	v_add_f32_e32 v159, v159, v200
	v_add_f32_e32 v163, v163, v204
	v_add_f32_e32 v165, v165, v208
	v_add_f32_e32 v171, v171, v212
	v_add_f32_e32 v193, v193, v216
	v_add_f32_e32 v241, v241, v220
	v_mul_f32_e32 v145, 0x3a800000, v145
	v_mul_f32_e32 v155, 0x3a800000, v155
	v_mul_f32_e32 v159, 0x3a800000, v159
	v_mul_f32_e32 v163, 0x3a800000, v163
	v_mul_f32_e32 v165, 0x3a800000, v165
	v_mul_f32_e32 v171, 0x3a800000, v171
	v_mul_f32_e32 v193, 0x3a800000, v193
	v_mul_f32_e32 v241, 0x3a800000, v241
	v_add_f32_e32 v145, 0x358637bd, v145
	v_add_f32_e32 v155, 0x358637bd, v155
	v_add_f32_e32 v159, 0x358637bd, v159
	v_add_f32_e32 v163, 0x358637bd, v163
	v_add_f32_e32 v165, 0x358637bd, v165
	v_add_f32_e32 v171, 0x358637bd, v171
	v_add_f32_e32 v193, 0x358637bd, v193
	v_add_f32_e32 v241, 0x358637bd, v241
	v_rsq_f32_e32 v144, v145
	v_rsq_f32_e32 v154, v155
	v_rsq_f32_e32 v158, v159
	v_rsq_f32_e32 v162, v163
	v_rsq_f32_e32 v164, v165
	v_rsq_f32_e32 v170, v171
	v_rsq_f32_e32 v192, v193
	v_rsq_f32_e32 v240, v241
	s_nop 0
	v_mul_f32_e32 v144, 0x3f000000, v144
	v_mul_f32_e32 v154, 0x3f000000, v154
	v_mul_f32_e32 v158, 0x3f000000, v158
	v_mul_f32_e32 v162, 0x3f000000, v162
	v_mul_f32_e32 v164, 0x3f000000, v164
	v_mul_f32_e32 v170, 0x3f000000, v170
	v_mul_f32_e32 v192, 0x3f000000, v192
	v_mul_f32_e32 v240, 0x3f000000, v240
	v_add_u32_e32 v244, 0x10000, v153
	global_load_dwordx4 v[188:191], v244, s[66:67]
	global_load_dwordx4 v[196:199], v244, s[66:67] offset:256
	v_add_u32_e32 v244, 0x18000, v153
	global_load_dwordx4 v[200:203], v244, s[66:67]
	global_load_dwordx4 v[204:207], v244, s[66:67] offset:256
	v_add_u32_e32 v244, 0x40000, v153
	global_load_dwordx4 v[208:211], v244, s[66:67]
	global_load_dwordx4 v[212:215], v244, s[66:67] offset:256
	v_add_u32_e32 v244, 0x48000, v153
	global_load_dwordx4 v[216:219], v244, s[66:67]
	global_load_dwordx4 v[220:223], v244, s[66:67] offset:256
	s_waitcnt vmcnt(8)
; __device__ __forceinline__ float bf_lo(unsigned w) { return __uint_as_float(w << 16); }
; __device__ __forceinline__ float bf_hi(unsigned w) { return __uint_as_float(w & 0xffff0000u); }
; __device__ __forceinline__ unsigned pk2(float lo, float hi) { bf16x2_t r = __builtin_convertvector((f32x2_t){lo, hi}, bf16x2_t); return __builtin_bit_cast(unsigned, r); }
; template <bool SRC_F32, bool FINAL, int R> __device__ __forceinline__ void ew_compute(const EwSet<SRC_F32, R>& S, int rb, const f32x4 (&g)[4], bf16* hb_out, float* out32, float scale, float* rs_out, int lane) {
;     ...
; #pragma unroll
;         for (int j = 0; j < 4; ++j) {
;             f32x4 h;
;             if constexpr (SRC_F32) h = S.h32[i][j];
;             else { const v2u hw = S.hb[i][j]; h.x = bf_lo(hw.x); h.y = bf_hi(hw.x); h.z = bf_lo(hw.y); h.w = bf_hi(hw.y); }
;             const v2u fw = S.fw[i][j];
;             f32x4 v; v.x = h.x + bf_lo(fw.x) * rs * g[j].x; v.y = h.y + bf_hi(fw.x) * rs * g[j].y; v.z = h.z + bf_lo(fw.y) * rs * g[j].z; v.w = h.w + bf_hi(fw.y) * rs * g[j].w;
;             if (FINAL) __builtin_nontemporal_store(v, (f32x4*)(out32 + (size_t)(rb + i) * D) + lane + 64 * j);
;             else { v2u o; o.x = pk2(v.x, v.y); o.y = pk2(v.z, v.w); ((v2u*)(hb_out + (size_t)(rb + i) * D) + lane)[64 * j] = o; s2 += (v.x * v.x + v.y * v.y) + (v.z * v.z + v.w * v.w); }
;         }
;         if (!FINAL) { const float tot = wave_sum(s2); if (lane == 0) rs_out[rb + i] = 1.0f / sqrtf(tot * (1.f / D) + EPS); }
	v_lshlrev_b32_e32 v242, 16, v224
	v_and_b32_e32 v243, 0xffff0000, v224
	v_pk_mul_f32 v[124:125], v[124:125], v[144:145] op_sel_hi:[1,0]
	v_pk_fma_f32 v[124:125], v[124:125], v[172:173], v[242:243]
	v_lshlrev_b32_e32 v244, 16, v225
	v_and_b32_e32 v245, 0xffff0000, v225
	v_pk_mul_f32 v[126:127], v[126:127], v[144:145] op_sel_hi:[1,0]
	v_pk_fma_f32 v[126:127], v[126:127], v[174:175], v[244:245]
	v_lshlrev_b32_e32 v242, 16, v226
	v_and_b32_e32 v243, 0xffff0000, v226
	v_pk_mul_f32 v[120:121], v[120:121], v[144:145] op_sel_hi:[1,0]
	v_pk_fma_f32 v[120:121], v[120:121], v[176:177], v[242:243]
	v_lshlrev_b32_e32 v244, 16, v227
	v_and_b32_e32 v245, 0xffff0000, v227
	v_pk_mul_f32 v[122:123], v[122:123], v[144:145] op_sel_hi:[1,0]
	v_pk_fma_f32 v[122:123], v[122:123], v[178:179], v[244:245]
	v_lshlrev_b32_e32 v242, 16, v228
	v_and_b32_e32 v243, 0xffff0000, v228
	v_pk_mul_f32 v[116:117], v[116:117], v[144:145] op_sel_hi:[1,0]
	v_pk_fma_f32 v[116:117], v[116:117], v[180:181], v[242:243]
	v_lshlrev_b32_e32 v244, 16, v229
	v_and_b32_e32 v245, 0xffff0000, v229
	v_pk_mul_f32 v[118:119], v[118:119], v[144:145] op_sel_hi:[1,0]
	v_pk_fma_f32 v[118:119], v[118:119], v[182:183], v[244:245]
	v_lshlrev_b32_e32 v242, 16, v230
	v_and_b32_e32 v243, 0xffff0000, v230
	v_pk_mul_f32 v[112:113], v[112:113], v[144:145] op_sel_hi:[1,0]
	v_pk_fma_f32 v[112:113], v[112:113], v[184:185], v[242:243]
	v_lshlrev_b32_e32 v244, 16, v231
	v_and_b32_e32 v245, 0xffff0000, v231
	v_pk_mul_f32 v[114:115], v[114:115], v[144:145] op_sel_hi:[1,0]
	v_pk_fma_f32 v[114:115], v[114:115], v[186:187], v[244:245]
	v_pk_mul_f32 v[242:243], v[124:125], v[124:125]
	v_pk_fma_f32 v[242:243], v[126:127], v[126:127], v[242:243]
	v_pk_fma_f32 v[242:243], v[120:121], v[120:121], v[242:243]
	v_pk_fma_f32 v[242:243], v[122:123], v[122:123], v[242:243]
	v_pk_fma_f32 v[242:243], v[116:117], v[116:117], v[242:243]
	v_pk_fma_f32 v[242:243], v[118:119], v[118:119], v[242:243]
	v_pk_fma_f32 v[242:243], v[112:113], v[112:113], v[242:243]
	v_pk_fma_f32 v[242:243], v[114:115], v[114:115], v[242:243]
	v_add_f32_e32 v145, v242, v243
	v_cvt_pk_bf16_f32 v224, v124, v125
	v_cvt_pk_bf16_f32 v225, v126, v127
	v_cvt_pk_bf16_f32 v226, v120, v121
	v_cvt_pk_bf16_f32 v227, v122, v123
	v_cvt_pk_bf16_f32 v228, v116, v117
	v_cvt_pk_bf16_f32 v229, v118, v119
	v_cvt_pk_bf16_f32 v230, v112, v113
	v_cvt_pk_bf16_f32 v231, v114, v115
	s_nop 0
	global_store_dwordx4 v153, v[224:227], s[66:67]
	global_store_dwordx4 v153, v[228:231], s[66:67] offset:256
	s_waitcnt vmcnt(10)
	v_lshlrev_b32_e32 v242, 16, v232
	v_and_b32_e32 v243, 0xffff0000, v232
	v_pk_mul_f32 v[108:109], v[108:109], v[154:155] op_sel_hi:[1,0]
	v_pk_fma_f32 v[108:109], v[108:109], v[172:173], v[242:243]
	v_lshlrev_b32_e32 v244, 16, v233
	v_and_b32_e32 v245, 0xffff0000, v233
	v_pk_mul_f32 v[110:111], v[110:111], v[154:155] op_sel_hi:[1,0]
	v_pk_fma_f32 v[110:111], v[110:111], v[174:175], v[244:245]
	v_lshlrev_b32_e32 v242, 16, v234
	v_and_b32_e32 v243, 0xffff0000, v234
	v_pk_mul_f32 v[104:105], v[104:105], v[154:155] op_sel_hi:[1,0]
	v_pk_fma_f32 v[104:105], v[104:105], v[176:177], v[242:243]
	v_lshlrev_b32_e32 v244, 16, v235
	v_and_b32_e32 v245, 0xffff0000, v235
	v_pk_mul_f32 v[106:107], v[106:107], v[154:155] op_sel_hi:[1,0]
	v_pk_fma_f32 v[106:107], v[106:107], v[178:179], v[244:245]
	v_lshlrev_b32_e32 v242, 16, v236
	v_and_b32_e32 v243, 0xffff0000, v236
	v_pk_mul_f32 v[100:101], v[100:101], v[154:155] op_sel_hi:[1,0]
	v_pk_fma_f32 v[100:101], v[100:101], v[180:181], v[242:243]
	v_lshlrev_b32_e32 v244, 16, v237
	v_and_b32_e32 v245, 0xffff0000, v237
	v_pk_mul_f32 v[102:103], v[102:103], v[154:155] op_sel_hi:[1,0]
	v_pk_fma_f32 v[102:103], v[102:103], v[182:183], v[244:245]
	v_lshlrev_b32_e32 v242, 16, v238
	v_and_b32_e32 v243, 0xffff0000, v238
	v_pk_mul_f32 v[96:97], v[96:97], v[154:155] op_sel_hi:[1,0]
	v_pk_fma_f32 v[96:97], v[96:97], v[184:185], v[242:243]
	v_lshlrev_b32_e32 v244, 16, v239
	v_and_b32_e32 v245, 0xffff0000, v239
	v_pk_mul_f32 v[98:99], v[98:99], v[154:155] op_sel_hi:[1,0]
	v_pk_fma_f32 v[98:99], v[98:99], v[186:187], v[244:245]
	v_pk_mul_f32 v[242:243], v[108:109], v[108:109]
	v_pk_fma_f32 v[242:243], v[110:111], v[110:111], v[242:243]
	v_pk_fma_f32 v[242:243], v[104:105], v[104:105], v[242:243]
	v_pk_fma_f32 v[242:243], v[106:107], v[106:107], v[242:243]
	v_pk_fma_f32 v[242:243], v[100:101], v[100:101], v[242:243]
	v_pk_fma_f32 v[242:243], v[102:103], v[102:103], v[242:243]
	v_pk_fma_f32 v[242:243], v[96:97], v[96:97], v[242:243]
	v_pk_fma_f32 v[242:243], v[98:99], v[98:99], v[242:243]
	v_add_f32_e32 v155, v242, v243
	v_cvt_pk_bf16_f32 v232, v108, v109
	v_cvt_pk_bf16_f32 v233, v110, v111
	v_cvt_pk_bf16_f32 v234, v104, v105
	v_cvt_pk_bf16_f32 v235, v106, v107
	v_cvt_pk_bf16_f32 v236, v100, v101
	v_cvt_pk_bf16_f32 v237, v102, v103
	v_cvt_pk_bf16_f32 v238, v96, v97
	v_cvt_pk_bf16_f32 v239, v98, v99
	v_add_u32_e32 v244, 0x8000, v153
	s_nop 0
	global_store_dwordx4 v244, v[232:235], s[66:67]
	global_store_dwordx4 v244, v[236:239], s[66:67] offset:256
	s_nop 1
	v_add_u32_e32 v244, 0x50000, v153
	global_load_dwordx4 v[224:227], v244, s[66:67]
	global_load_dwordx4 v[228:231], v244, s[66:67] offset:256
	v_add_u32_e32 v244, 0x58000, v153
	global_load_dwordx4 v[232:235], v244, s[66:67]
	global_load_dwordx4 v[236:239], v244, s[66:67] offset:256
	s_waitcnt vmcnt(14)
; __device__ __forceinline__ float bf_lo(unsigned w) { return __uint_as_float(w << 16); }
; __device__ __forceinline__ float bf_hi(unsigned w) { return __uint_as_float(w & 0xffff0000u); }
; __device__ __forceinline__ unsigned pk2(float lo, float hi) { bf16x2_t r = __builtin_convertvector((f32x2_t){lo, hi}, bf16x2_t); return __builtin_bit_cast(unsigned, r); }
; template <bool SRC_F32, bool FINAL, int R> __device__ __forceinline__ void ew_compute(const EwSet<SRC_F32, R>& S, int rb, const f32x4 (&g)[4], bf16* hb_out, float* out32, float scale, float* rs_out, int lane) {
;     ...
; #pragma unroll
;         for (int j = 0; j < 4; ++j) {
;             f32x4 h;
;             if constexpr (SRC_F32) h = S.h32[i][j];
;             else { const v2u hw = S.hb[i][j]; h.x = bf_lo(hw.x); h.y = bf_hi(hw.x); h.z = bf_lo(hw.y); h.w = bf_hi(hw.y); }
;             const v2u fw = S.fw[i][j];
;             f32x4 v; v.x = h.x + bf_lo(fw.x) * rs * g[j].x; v.y = h.y + bf_hi(fw.x) * rs * g[j].y; v.z = h.z + bf_lo(fw.y) * rs * g[j].z; v.w = h.w + bf_hi(fw.y) * rs * g[j].w;
;             if (FINAL) __builtin_nontemporal_store(v, (f32x4*)(out32 + (size_t)(rb + i) * D) + lane + 64 * j);
;             else { v2u o; o.x = pk2(v.x, v.y); o.y = pk2(v.z, v.w); ((v2u*)(hb_out + (size_t)(rb + i) * D) + lane)[64 * j] = o; s2 += (v.x * v.x + v.y * v.y) + (v.z * v.z + v.w * v.w); }
;         }
;         if (!FINAL) { const float tot = wave_sum(s2); if (lane == 0) rs_out[rb + i] = 1.0f / sqrtf(tot * (1.f / D) + EPS); }
	v_lshlrev_b32_e32 v242, 16, v188
	v_and_b32_e32 v243, 0xffff0000, v188
	v_pk_mul_f32 v[92:93], v[92:93], v[158:159] op_sel_hi:[1,0]
	v_pk_fma_f32 v[92:93], v[92:93], v[172:173], v[242:243]
	v_lshlrev_b32_e32 v244, 16, v189
	v_and_b32_e32 v245, 0xffff0000, v189
	v_pk_mul_f32 v[94:95], v[94:95], v[158:159] op_sel_hi:[1,0]
	v_pk_fma_f32 v[94:95], v[94:95], v[174:175], v[244:245]
	v_lshlrev_b32_e32 v242, 16, v190
	v_and_b32_e32 v243, 0xffff0000, v190
	v_pk_mul_f32 v[88:89], v[88:89], v[158:159] op_sel_hi:[1,0]
	v_pk_fma_f32 v[88:89], v[88:89], v[176:177], v[242:243]
	v_lshlrev_b32_e32 v244, 16, v191
	v_and_b32_e32 v245, 0xffff0000, v191
	v_pk_mul_f32 v[90:91], v[90:91], v[158:159] op_sel_hi:[1,0]
	v_pk_fma_f32 v[90:91], v[90:91], v[178:179], v[244:245]
	v_lshlrev_b32_e32 v242, 16, v196
	v_and_b32_e32 v243, 0xffff0000, v196
	v_pk_mul_f32 v[84:85], v[84:85], v[158:159] op_sel_hi:[1,0]
	v_pk_fma_f32 v[84:85], v[84:85], v[180:181], v[242:243]
	v_lshlrev_b32_e32 v244, 16, v197
	v_and_b32_e32 v245, 0xffff0000, v197
	v_pk_mul_f32 v[86:87], v[86:87], v[158:159] op_sel_hi:[1,0]
	v_pk_fma_f32 v[86:87], v[86:87], v[182:183], v[244:245]
	v_lshlrev_b32_e32 v242, 16, v198
	v_and_b32_e32 v243, 0xffff0000, v198
	v_pk_mul_f32 v[80:81], v[80:81], v[158:159] op_sel_hi:[1,0]
	v_pk_fma_f32 v[80:81], v[80:81], v[184:185], v[242:243]
	v_lshlrev_b32_e32 v244, 16, v199
	v_and_b32_e32 v245, 0xffff0000, v199
	v_pk_mul_f32 v[82:83], v[82:83], v[158:159] op_sel_hi:[1,0]
	v_pk_fma_f32 v[82:83], v[82:83], v[186:187], v[244:245]
	v_pk_mul_f32 v[242:243], v[92:93], v[92:93]
	v_pk_fma_f32 v[242:243], v[94:95], v[94:95], v[242:243]
	v_pk_fma_f32 v[242:243], v[88:89], v[88:89], v[242:243]
	v_pk_fma_f32 v[242:243], v[90:91], v[90:91], v[242:243]
	v_pk_fma_f32 v[242:243], v[84:85], v[84:85], v[242:243]
	v_pk_fma_f32 v[242:243], v[86:87], v[86:87], v[242:243]
	v_pk_fma_f32 v[242:243], v[80:81], v[80:81], v[242:243]
	v_pk_fma_f32 v[242:243], v[82:83], v[82:83], v[242:243]
	v_add_f32_e32 v159, v242, v243
	v_cvt_pk_bf16_f32 v188, v92, v93
	v_cvt_pk_bf16_f32 v189, v94, v95
	v_cvt_pk_bf16_f32 v190, v88, v89
	v_cvt_pk_bf16_f32 v191, v90, v91
	v_cvt_pk_bf16_f32 v196, v84, v85
	v_cvt_pk_bf16_f32 v197, v86, v87
	v_cvt_pk_bf16_f32 v198, v80, v81
	v_cvt_pk_bf16_f32 v199, v82, v83
	v_add_u32_e32 v244, 0x10000, v153
	s_nop 0
	global_store_dwordx4 v244, v[188:191], s[66:67]
	global_store_dwordx4 v244, v[196:199], s[66:67] offset:256
	s_waitcnt vmcnt(14)
	v_lshlrev_b32_e32 v242, 16, v200
	v_and_b32_e32 v243, 0xffff0000, v200
	v_pk_mul_f32 v[76:77], v[76:77], v[162:163] op_sel_hi:[1,0]
	v_pk_fma_f32 v[76:77], v[76:77], v[172:173], v[242:243]
	v_lshlrev_b32_e32 v244, 16, v201
	v_and_b32_e32 v245, 0xffff0000, v201
	v_pk_mul_f32 v[78:79], v[78:79], v[162:163] op_sel_hi:[1,0]
	v_pk_fma_f32 v[78:79], v[78:79], v[174:175], v[244:245]
	v_lshlrev_b32_e32 v242, 16, v202
	v_and_b32_e32 v243, 0xffff0000, v202
	v_pk_mul_f32 v[72:73], v[72:73], v[162:163] op_sel_hi:[1,0]
	v_pk_fma_f32 v[72:73], v[72:73], v[176:177], v[242:243]
	v_lshlrev_b32_e32 v244, 16, v203
	v_and_b32_e32 v245, 0xffff0000, v203
	v_pk_mul_f32 v[74:75], v[74:75], v[162:163] op_sel_hi:[1,0]
	v_pk_fma_f32 v[74:75], v[74:75], v[178:179], v[244:245]
	v_lshlrev_b32_e32 v242, 16, v204
	v_and_b32_e32 v243, 0xffff0000, v204
	v_pk_mul_f32 v[68:69], v[68:69], v[162:163] op_sel_hi:[1,0]
	v_pk_fma_f32 v[68:69], v[68:69], v[180:181], v[242:243]
	v_lshlrev_b32_e32 v244, 16, v205
	v_and_b32_e32 v245, 0xffff0000, v205
	v_pk_mul_f32 v[70:71], v[70:71], v[162:163] op_sel_hi:[1,0]
	v_pk_fma_f32 v[70:71], v[70:71], v[182:183], v[244:245]
	v_lshlrev_b32_e32 v242, 16, v206
	v_and_b32_e32 v243, 0xffff0000, v206
	v_pk_mul_f32 v[64:65], v[64:65], v[162:163] op_sel_hi:[1,0]
	v_pk_fma_f32 v[64:65], v[64:65], v[184:185], v[242:243]
	v_lshlrev_b32_e32 v244, 16, v207
	v_and_b32_e32 v245, 0xffff0000, v207
	v_pk_mul_f32 v[66:67], v[66:67], v[162:163] op_sel_hi:[1,0]
	v_pk_fma_f32 v[66:67], v[66:67], v[186:187], v[244:245]
	v_pk_mul_f32 v[242:243], v[76:77], v[76:77]
	v_pk_fma_f32 v[242:243], v[78:79], v[78:79], v[242:243]
	v_pk_fma_f32 v[242:243], v[72:73], v[72:73], v[242:243]
	v_pk_fma_f32 v[242:243], v[74:75], v[74:75], v[242:243]
	v_pk_fma_f32 v[242:243], v[68:69], v[68:69], v[242:243]
	v_pk_fma_f32 v[242:243], v[70:71], v[70:71], v[242:243]
	v_pk_fma_f32 v[242:243], v[64:65], v[64:65], v[242:243]
	v_pk_fma_f32 v[242:243], v[66:67], v[66:67], v[242:243]
	v_add_f32_e32 v163, v242, v243
	v_cvt_pk_bf16_f32 v200, v76, v77
	v_cvt_pk_bf16_f32 v201, v78, v79
	v_cvt_pk_bf16_f32 v202, v72, v73
	v_cvt_pk_bf16_f32 v203, v74, v75
	v_cvt_pk_bf16_f32 v204, v68, v69
	v_cvt_pk_bf16_f32 v205, v70, v71
	v_cvt_pk_bf16_f32 v206, v64, v65
	v_cvt_pk_bf16_f32 v207, v66, v67
	v_add_u32_e32 v244, 0x18000, v153
	s_nop 0
	global_store_dwordx4 v244, v[200:203], s[66:67]
	global_store_dwordx4 v244, v[204:207], s[66:67] offset:256
	s_waitcnt vmcnt(14)
; __device__ __forceinline__ float bf_lo(unsigned w) { return __uint_as_float(w << 16); }
; __device__ __forceinline__ float bf_hi(unsigned w) { return __uint_as_float(w & 0xffff0000u); }
; __device__ __forceinline__ unsigned pk2(float lo, float hi) { bf16x2_t r = __builtin_convertvector((f32x2_t){lo, hi}, bf16x2_t); return __builtin_bit_cast(unsigned, r); }
; template <bool SRC_F32, bool FINAL, int R> __device__ __forceinline__ void ew_compute(const EwSet<SRC_F32, R>& S, int rb, const f32x4 (&g)[4], bf16* hb_out, float* out32, float scale, float* rs_out, int lane) {
;     ...
; #pragma unroll
;         for (int j = 0; j < 4; ++j) {
;             f32x4 h;
;             if constexpr (SRC_F32) h = S.h32[i][j];
;             else { const v2u hw = S.hb[i][j]; h.x = bf_lo(hw.x); h.y = bf_hi(hw.x); h.z = bf_lo(hw.y); h.w = bf_hi(hw.y); }
;             const v2u fw = S.fw[i][j];
;             f32x4 v; v.x = h.x + bf_lo(fw.x) * rs * g[j].x; v.y = h.y + bf_hi(fw.x) * rs * g[j].y; v.z = h.z + bf_lo(fw.y) * rs * g[j].z; v.w = h.w + bf_hi(fw.y) * rs * g[j].w;
;             if (FINAL) __builtin_nontemporal_store(v, (f32x4*)(out32 + (size_t)(rb + i) * D) + lane + 64 * j);
;             else { v2u o; o.x = pk2(v.x, v.y); o.y = pk2(v.z, v.w); ((v2u*)(hb_out + (size_t)(rb + i) * D) + lane)[64 * j] = o; s2 += (v.x * v.x + v.y * v.y) + (v.z * v.z + v.w * v.w); }
;         }
;         if (!FINAL) { const float tot = wave_sum(s2); if (lane == 0) rs_out[rb + i] = 1.0f / sqrtf(tot * (1.f / D) + EPS); }
	v_lshlrev_b32_e32 v242, 16, v208
	v_and_b32_e32 v243, 0xffff0000, v208
	v_pk_mul_f32 v[60:61], v[60:61], v[164:165] op_sel_hi:[1,0]
	v_pk_fma_f32 v[60:61], v[60:61], v[172:173], v[242:243]
	v_lshlrev_b32_e32 v244, 16, v209
	v_and_b32_e32 v245, 0xffff0000, v209
	v_pk_mul_f32 v[62:63], v[62:63], v[164:165] op_sel_hi:[1,0]
	v_pk_fma_f32 v[62:63], v[62:63], v[174:175], v[244:245]
	v_lshlrev_b32_e32 v242, 16, v210
	v_and_b32_e32 v243, 0xffff0000, v210
	v_pk_mul_f32 v[56:57], v[56:57], v[164:165] op_sel_hi:[1,0]
	v_pk_fma_f32 v[56:57], v[56:57], v[176:177], v[242:243]
	v_lshlrev_b32_e32 v244, 16, v211
	v_and_b32_e32 v245, 0xffff0000, v211
	v_pk_mul_f32 v[58:59], v[58:59], v[164:165] op_sel_hi:[1,0]
	v_pk_fma_f32 v[58:59], v[58:59], v[178:179], v[244:245]
	v_lshlrev_b32_e32 v242, 16, v212
	v_and_b32_e32 v243, 0xffff0000, v212
	v_pk_mul_f32 v[52:53], v[52:53], v[164:165] op_sel_hi:[1,0]
	v_pk_fma_f32 v[52:53], v[52:53], v[180:181], v[242:243]
	v_lshlrev_b32_e32 v244, 16, v213
	v_and_b32_e32 v245, 0xffff0000, v213
	v_pk_mul_f32 v[54:55], v[54:55], v[164:165] op_sel_hi:[1,0]
	v_pk_fma_f32 v[54:55], v[54:55], v[182:183], v[244:245]
	v_lshlrev_b32_e32 v242, 16, v214
	v_and_b32_e32 v243, 0xffff0000, v214
	v_pk_mul_f32 v[48:49], v[48:49], v[164:165] op_sel_hi:[1,0]
	v_pk_fma_f32 v[48:49], v[48:49], v[184:185], v[242:243]
	v_lshlrev_b32_e32 v244, 16, v215
	v_and_b32_e32 v245, 0xffff0000, v215
	v_pk_mul_f32 v[50:51], v[50:51], v[164:165] op_sel_hi:[1,0]
	v_pk_fma_f32 v[50:51], v[50:51], v[186:187], v[244:245]
	v_pk_mul_f32 v[242:243], v[60:61], v[60:61]
	v_pk_fma_f32 v[242:243], v[62:63], v[62:63], v[242:243]
	v_pk_fma_f32 v[242:243], v[56:57], v[56:57], v[242:243]
	v_pk_fma_f32 v[242:243], v[58:59], v[58:59], v[242:243]
	v_pk_fma_f32 v[242:243], v[52:53], v[52:53], v[242:243]
	v_pk_fma_f32 v[242:243], v[54:55], v[54:55], v[242:243]
	v_pk_fma_f32 v[242:243], v[48:49], v[48:49], v[242:243]
	v_pk_fma_f32 v[242:243], v[50:51], v[50:51], v[242:243]
	v_add_f32_e32 v165, v242, v243
	v_cvt_pk_bf16_f32 v208, v60, v61
	v_cvt_pk_bf16_f32 v209, v62, v63
	v_cvt_pk_bf16_f32 v210, v56, v57
	v_cvt_pk_bf16_f32 v211, v58, v59
	v_cvt_pk_bf16_f32 v212, v52, v53
	v_cvt_pk_bf16_f32 v213, v54, v55
	v_cvt_pk_bf16_f32 v214, v48, v49
	v_cvt_pk_bf16_f32 v215, v50, v51
	v_add_u32_e32 v244, 0x40000, v153
	s_nop 0
	global_store_dwordx4 v244, v[208:211], s[66:67]
	global_store_dwordx4 v244, v[212:215], s[66:67] offset:256
	s_waitcnt vmcnt(14)
	v_lshlrev_b32_e32 v242, 16, v216
	v_and_b32_e32 v243, 0xffff0000, v216
	v_pk_mul_f32 v[44:45], v[44:45], v[170:171] op_sel_hi:[1,0]
	v_pk_fma_f32 v[44:45], v[44:45], v[172:173], v[242:243]
	v_lshlrev_b32_e32 v244, 16, v217
	v_and_b32_e32 v245, 0xffff0000, v217
	v_pk_mul_f32 v[46:47], v[46:47], v[170:171] op_sel_hi:[1,0]
	v_pk_fma_f32 v[46:47], v[46:47], v[174:175], v[244:245]
	v_lshlrev_b32_e32 v242, 16, v218
	v_and_b32_e32 v243, 0xffff0000, v218
	v_pk_mul_f32 v[40:41], v[40:41], v[170:171] op_sel_hi:[1,0]
	v_pk_fma_f32 v[40:41], v[40:41], v[176:177], v[242:243]
	v_lshlrev_b32_e32 v244, 16, v219
	v_and_b32_e32 v245, 0xffff0000, v219
	v_pk_mul_f32 v[42:43], v[42:43], v[170:171] op_sel_hi:[1,0]
	v_pk_fma_f32 v[42:43], v[42:43], v[178:179], v[244:245]
	v_lshlrev_b32_e32 v242, 16, v220
	v_and_b32_e32 v243, 0xffff0000, v220
	v_pk_mul_f32 v[36:37], v[36:37], v[170:171] op_sel_hi:[1,0]
	v_pk_fma_f32 v[36:37], v[36:37], v[180:181], v[242:243]
	v_lshlrev_b32_e32 v244, 16, v221
	v_and_b32_e32 v245, 0xffff0000, v221
	v_pk_mul_f32 v[38:39], v[38:39], v[170:171] op_sel_hi:[1,0]
	v_pk_fma_f32 v[38:39], v[38:39], v[182:183], v[244:245]
	v_lshlrev_b32_e32 v242, 16, v222
	v_and_b32_e32 v243, 0xffff0000, v222
	v_pk_mul_f32 v[32:33], v[32:33], v[170:171] op_sel_hi:[1,0]
	v_pk_fma_f32 v[32:33], v[32:33], v[184:185], v[242:243]
	v_lshlrev_b32_e32 v244, 16, v223
	v_and_b32_e32 v245, 0xffff0000, v223
	v_pk_mul_f32 v[34:35], v[34:35], v[170:171] op_sel_hi:[1,0]
	v_pk_fma_f32 v[34:35], v[34:35], v[186:187], v[244:245]
	v_pk_mul_f32 v[242:243], v[44:45], v[44:45]
	v_pk_fma_f32 v[242:243], v[46:47], v[46:47], v[242:243]
	v_pk_fma_f32 v[242:243], v[40:41], v[40:41], v[242:243]
	v_pk_fma_f32 v[242:243], v[42:43], v[42:43], v[242:243]
	v_pk_fma_f32 v[242:243], v[36:37], v[36:37], v[242:243]
	v_pk_fma_f32 v[242:243], v[38:39], v[38:39], v[242:243]
	v_pk_fma_f32 v[242:243], v[32:33], v[32:33], v[242:243]
	v_pk_fma_f32 v[242:243], v[34:35], v[34:35], v[242:243]
	v_add_f32_e32 v171, v242, v243
	v_cvt_pk_bf16_f32 v216, v44, v45
	v_cvt_pk_bf16_f32 v217, v46, v47
	v_cvt_pk_bf16_f32 v218, v40, v41
	v_cvt_pk_bf16_f32 v219, v42, v43
	v_cvt_pk_bf16_f32 v220, v36, v37
	v_cvt_pk_bf16_f32 v221, v38, v39
	v_cvt_pk_bf16_f32 v222, v32, v33
	v_cvt_pk_bf16_f32 v223, v34, v35
	v_add_u32_e32 v244, 0x48000, v153
	s_nop 0
	global_store_dwordx4 v244, v[216:219], s[66:67]
	global_store_dwordx4 v244, v[220:223], s[66:67] offset:256
	s_waitcnt vmcnt(10)
; __device__ __forceinline__ float bf_lo(unsigned w) { return __uint_as_float(w << 16); }
; __device__ __forceinline__ float bf_hi(unsigned w) { return __uint_as_float(w & 0xffff0000u); }
; __device__ __forceinline__ unsigned pk2(float lo, float hi) { bf16x2_t r = __builtin_convertvector((f32x2_t){lo, hi}, bf16x2_t); return __builtin_bit_cast(unsigned, r); }
;     __device__ __forceinline__ void operator()(const pg8::f32x4 (&acc)[2][2][4][2], const pg8::Unit& u, int wr, int wc, int fr, int fq) const {
;     ...
;                     if (PART) {
; #pragma unroll
;                         for (int j = 0; j < 8; ++j) s += r[j] * r[j];
;                     }
;                     v4u w; w.x = pk2(r[0], r[1]); w.y = pk2(r[2], r[3]); w.z = pk2(r[4], r[5]); w.w = pk2(r[6], r[7]);
;                     st16_wt(O + off + bj * 128, w);
;                 }
;                 if (PART) { s += __shfl_xor(s, 16); s += __shfl_xor(s, 32); st4_wt(part + (size_t)row * 16 + u.pn * 4 + wc, s); }
; template <bool SRC_F32, bool FINAL, int R> __device__ __forceinline__ void ew_compute(const EwSet<SRC_F32, R>& S, int rb, const f32x4 (&g)[4], bf16* hb_out, float* out32, float scale, float* rs_out, int lane) {
;     ...
; #pragma unroll
;         for (int j = 0; j < 4; ++j) {
;             f32x4 h;
;             if constexpr (SRC_F32) h = S.h32[i][j];
;             else { const v2u hw = S.hb[i][j]; h.x = bf_lo(hw.x); h.y = bf_hi(hw.x); h.z = bf_lo(hw.y); h.w = bf_hi(hw.y); }
;             const v2u fw = S.fw[i][j];
;             f32x4 v; v.x = h.x + bf_lo(fw.x) * rs * g[j].x; v.y = h.y + bf_hi(fw.x) * rs * g[j].y; v.z = h.z + bf_lo(fw.y) * rs * g[j].z; v.w = h.w + bf_hi(fw.y) * rs * g[j].w;
;             if (FINAL) __builtin_nontemporal_store(v, (f32x4*)(out32 + (size_t)(rb + i) * D) + lane + 64 * j);
;             else { v2u o; o.x = pk2(v.x, v.y); o.y = pk2(v.z, v.w); ((v2u*)(hb_out + (size_t)(rb + i) * D) + lane)[64 * j] = o; s2 += (v.x * v.x + v.y * v.y) + (v.z * v.z + v.w * v.w); }
;         }
;         if (!FINAL) { const float tot = wave_sum(s2); if (lane == 0) rs_out[rb + i] = 1.0f / sqrtf(tot * (1.f / D) + EPS); }
	v_lshlrev_b32_e32 v242, 16, v224
	v_and_b32_e32 v243, 0xffff0000, v224
	v_pk_mul_f32 v[28:29], v[28:29], v[192:193] op_sel_hi:[1,0]
	v_pk_fma_f32 v[28:29], v[28:29], v[172:173], v[242:243]
	v_lshlrev_b32_e32 v244, 16, v225
	v_and_b32_e32 v245, 0xffff0000, v225
	v_pk_mul_f32 v[30:31], v[30:31], v[192:193] op_sel_hi:[1,0]
	v_pk_fma_f32 v[30:31], v[30:31], v[174:175], v[244:245]
	v_lshlrev_b32_e32 v242, 16, v226
	v_and_b32_e32 v243, 0xffff0000, v226
	v_pk_mul_f32 v[24:25], v[24:25], v[192:193] op_sel_hi:[1,0]
	v_pk_fma_f32 v[24:25], v[24:25], v[176:177], v[242:243]
	v_lshlrev_b32_e32 v244, 16, v227
	v_and_b32_e32 v245, 0xffff0000, v227
	v_pk_mul_f32 v[26:27], v[26:27], v[192:193] op_sel_hi:[1,0]
	v_pk_fma_f32 v[26:27], v[26:27], v[178:179], v[244:245]
	v_lshlrev_b32_e32 v242, 16, v228
	v_and_b32_e32 v243, 0xffff0000, v228
	v_pk_mul_f32 v[20:21], v[20:21], v[192:193] op_sel_hi:[1,0]
	v_pk_fma_f32 v[20:21], v[20:21], v[180:181], v[242:243]
	v_lshlrev_b32_e32 v244, 16, v229
	v_and_b32_e32 v245, 0xffff0000, v229
	v_pk_mul_f32 v[22:23], v[22:23], v[192:193] op_sel_hi:[1,0]
	v_pk_fma_f32 v[22:23], v[22:23], v[182:183], v[244:245]
	v_lshlrev_b32_e32 v242, 16, v230
	v_and_b32_e32 v243, 0xffff0000, v230
	v_pk_mul_f32 v[16:17], v[16:17], v[192:193] op_sel_hi:[1,0]
	v_pk_fma_f32 v[16:17], v[16:17], v[184:185], v[242:243]
	v_lshlrev_b32_e32 v244, 16, v231
	v_and_b32_e32 v245, 0xffff0000, v231
	v_pk_mul_f32 v[18:19], v[18:19], v[192:193] op_sel_hi:[1,0]
	v_pk_fma_f32 v[18:19], v[18:19], v[186:187], v[244:245]
	v_pk_mul_f32 v[242:243], v[28:29], v[28:29]
	v_pk_fma_f32 v[242:243], v[30:31], v[30:31], v[242:243]
	v_pk_fma_f32 v[242:243], v[24:25], v[24:25], v[242:243]
	v_pk_fma_f32 v[242:243], v[26:27], v[26:27], v[242:243]
	v_pk_fma_f32 v[242:243], v[20:21], v[20:21], v[242:243]
	v_pk_fma_f32 v[242:243], v[22:23], v[22:23], v[242:243]
	v_pk_fma_f32 v[242:243], v[16:17], v[16:17], v[242:243]
	v_pk_fma_f32 v[242:243], v[18:19], v[18:19], v[242:243]
	v_add_f32_e32 v193, v242, v243
	v_cvt_pk_bf16_f32 v224, v28, v29
	v_cvt_pk_bf16_f32 v225, v30, v31
	v_cvt_pk_bf16_f32 v226, v24, v25
	v_cvt_pk_bf16_f32 v227, v26, v27
	v_cvt_pk_bf16_f32 v228, v20, v21
	v_cvt_pk_bf16_f32 v229, v22, v23
	v_cvt_pk_bf16_f32 v230, v16, v17
	v_cvt_pk_bf16_f32 v231, v18, v19
	v_add_u32_e32 v244, 0x50000, v153
	s_nop 0
	global_store_dwordx4 v244, v[224:227], s[66:67]
	global_store_dwordx4 v244, v[228:231], s[66:67] offset:256
	s_waitcnt vmcnt(10)
	v_lshlrev_b32_e32 v242, 16, v232
	v_and_b32_e32 v243, 0xffff0000, v232
	v_pk_mul_f32 v[12:13], v[12:13], v[240:241] op_sel_hi:[1,0]
	v_pk_fma_f32 v[12:13], v[12:13], v[172:173], v[242:243]
	v_lshlrev_b32_e32 v244, 16, v233
	v_and_b32_e32 v245, 0xffff0000, v233
	v_pk_mul_f32 v[14:15], v[14:15], v[240:241] op_sel_hi:[1,0]
	v_pk_fma_f32 v[14:15], v[14:15], v[174:175], v[244:245]
	v_lshlrev_b32_e32 v242, 16, v234
	v_and_b32_e32 v243, 0xffff0000, v234
	v_pk_mul_f32 v[8:9], v[8:9], v[240:241] op_sel_hi:[1,0]
	v_pk_fma_f32 v[8:9], v[8:9], v[176:177], v[242:243]
	v_lshlrev_b32_e32 v244, 16, v235
	v_and_b32_e32 v245, 0xffff0000, v235
	v_pk_mul_f32 v[10:11], v[10:11], v[240:241] op_sel_hi:[1,0]
	v_pk_fma_f32 v[10:11], v[10:11], v[178:179], v[244:245]
	v_lshlrev_b32_e32 v242, 16, v236
	v_and_b32_e32 v243, 0xffff0000, v236
	v_pk_mul_f32 v[4:5], v[4:5], v[240:241] op_sel_hi:[1,0]
	v_pk_fma_f32 v[4:5], v[4:5], v[180:181], v[242:243]
	v_lshlrev_b32_e32 v244, 16, v237
	v_and_b32_e32 v245, 0xffff0000, v237
	v_pk_mul_f32 v[6:7], v[6:7], v[240:241] op_sel_hi:[1,0]
	v_pk_fma_f32 v[6:7], v[6:7], v[182:183], v[244:245]
	v_lshlrev_b32_e32 v242, 16, v238
	v_and_b32_e32 v243, 0xffff0000, v238
	v_pk_mul_f32 v[0:1], v[0:1], v[240:241] op_sel_hi:[1,0]
	v_pk_fma_f32 v[0:1], v[0:1], v[184:185], v[242:243]
	v_lshlrev_b32_e32 v244, 16, v239
	v_and_b32_e32 v245, 0xffff0000, v239
	v_pk_mul_f32 v[2:3], v[2:3], v[240:241] op_sel_hi:[1,0]
	v_pk_fma_f32 v[2:3], v[2:3], v[186:187], v[244:245]
	v_pk_mul_f32 v[242:243], v[12:13], v[12:13]
	v_pk_fma_f32 v[242:243], v[14:15], v[14:15], v[242:243]
	v_pk_fma_f32 v[242:243], v[8:9], v[8:9], v[242:243]
	v_pk_fma_f32 v[242:243], v[10:11], v[10:11], v[242:243]
	v_pk_fma_f32 v[242:243], v[4:5], v[4:5], v[242:243]
	v_pk_fma_f32 v[242:243], v[6:7], v[6:7], v[242:243]
	v_pk_fma_f32 v[242:243], v[0:1], v[0:1], v[242:243]
	v_pk_fma_f32 v[242:243], v[2:3], v[2:3], v[242:243]
	v_add_f32_e32 v241, v242, v243
	v_cvt_pk_bf16_f32 v232, v12, v13
	v_cvt_pk_bf16_f32 v233, v14, v15
	v_cvt_pk_bf16_f32 v234, v8, v9
	v_cvt_pk_bf16_f32 v235, v10, v11
	v_cvt_pk_bf16_f32 v236, v4, v5
	v_cvt_pk_bf16_f32 v237, v6, v7
	v_cvt_pk_bf16_f32 v238, v0, v1
	v_cvt_pk_bf16_f32 v239, v2, v3
	v_add_u32_e32 v244, 0x58000, v153
	s_nop 0
	global_store_dwordx4 v244, v[232:235], s[66:67]
	global_store_dwordx4 v244, v[236:239], s[66:67] offset:256
	s_nop 1
	ds_bpermute_b32 v172, v166, v145
	ds_bpermute_b32 v173, v166, v155
	ds_bpermute_b32 v174, v166, v159
	ds_bpermute_b32 v175, v166, v163
	ds_bpermute_b32 v176, v166, v165
	ds_bpermute_b32 v177, v166, v171
	ds_bpermute_b32 v178, v166, v193
	ds_bpermute_b32 v179, v166, v241
	s_waitcnt lgkmcnt(0)
	v_add_f32_e32 v145, v145, v172
	v_add_f32_e32 v155, v155, v173
	v_add_f32_e32 v159, v159, v174
	v_add_f32_e32 v163, v163, v175
	v_add_f32_e32 v165, v165, v176
	v_add_f32_e32 v171, v171, v177
	v_add_f32_e32 v193, v193, v178
	v_add_f32_e32 v241, v241, v179
	s_nop 1
	ds_bpermute_b32 v172, v168, v145
	ds_bpermute_b32 v173, v168, v155
	ds_bpermute_b32 v174, v168, v159
	ds_bpermute_b32 v175, v168, v163
	ds_bpermute_b32 v176, v168, v165
	ds_bpermute_b32 v177, v168, v171
	ds_bpermute_b32 v178, v168, v193
	ds_bpermute_b32 v179, v168, v241
	s_waitcnt lgkmcnt(0)
	v_add_f32_e32 v145, v145, v172
	v_add_f32_e32 v155, v155, v173
	v_add_f32_e32 v159, v159, v174
	v_add_f32_e32 v163, v163, v175
	v_add_f32_e32 v165, v165, v176
	v_add_f32_e32 v171, v171, v177
	v_add_f32_e32 v193, v193, v178
	v_add_f32_e32 v241, v241, v179
	global_store_dword v157, v145, s[78:79]
	v_add_u32_e32 v173, 0x400, v157
	global_store_dword v173, v155, s[78:79]
	v_add_u32_e32 v174, 0x800, v157
	global_store_dword v174, v159, s[78:79]
	v_add_u32_e32 v175, 0xc00, v157
	global_store_dword v175, v163, s[78:79]
	v_add_u32_e32 v176, 0x2000, v157
	global_store_dword v176, v165, s[78:79]
	v_add_u32_e32 v177, 0x2400, v157
	global_store_dword v177, v171, s[78:79]
	v_add_u32_e32 v178, 0x2800, v157
	global_store_dword v178, v193, s[78:79]
	v_add_u32_e32 v179, 0x2c00, v157
	global_store_dword v179, v241, s[78:79]
	s_and_b64 vcc, exec, s[0:1]
	s_mov_b64 s[0:1], -1
	s_cbranch_vccnz .LBB0_317
	s_andn2_b64 vcc, exec, s[22:23]
	s_cbranch_vccnz .LBB0_316
	s_barrier
	s_branch .LBB0_316

; #define SEAM(k) do { if (IN(k) && IN((k) + 1)) { xcd_barrier(xbar); } } while (0)
; __global__ void __launch_bounds__(NWAVES * 64, 2) mk_fwd(Args a) {
;     ...
;     SEAM(2);
;     if (IN(3)) ew_phase<false, false>(nullptr, HB, HB, nullptr, FB, PART, a.in[I_F1POST], 0.5f, RS, gw, NGW, lane);
;     SEAM(3);
.LBB0_336:
	s_cmp_gt_i32 s31, 3
	s_cselect_b64 s[0:1], -1, 0
	s_and_b64 s[4:5], s[12:13], s[0:1]
	s_andn2_b64 vcc, exec, s[4:5]
	s_cbranch_vccnz .LBB0_386
.LBB0_386:
	s_cmp_lt_i32 s30, 4
	s_cselect_b64 s[4:5], -1, 0
	s_and_b64 s[12:13], s[4:5], s[0:1]
	s_andn2_b64 vcc, exec, s[12:13]
	s_cbranch_vccnz .LBB0_432
.LBB0_432:
	s_cmp_gt_i32 s31, 4
	s_cselect_b64 s[0:1], -1, 0
	s_and_b64 s[4:5], s[12:13], s[0:1]
	s_andn2_b64 vcc, exec, s[4:5]
	s_cbranch_vccnz .LBB0_482
	s_waitcnt vmcnt(0)
	s_barrier
	v_cmp_eq_u32_e32 vcc, 0, v195
	s_and_saveexec_b64 s[4:5], vcc
	s_cbranch_execz .Ltb482_done
	s_and_b32 s3, s2, 7
	s_lshl_b32 s3, s3, 3
	s_bfe_u32 s13, s2, 0x30003
	s_or_b32 s3, s3, s13
	s_lshl_b32 s3, s3, 5
	s_add_u32 s8, s28, 0x3903600
	s_addc_u32 s9, s29, 0
	v_mov_b32_e32 v0, s3
	v_mov_b32_e32 v1, 1
	v_mov_b32_e32 v2, 8
	s_mov_b32 s15, 0
	s_cmp_eq_u32 s99, 1
	s_cbranch_scc1 .Ltb482_fast
	buffer_wbl2 sc1
	s_waitcnt vmcnt(0)
	global_atomic_add v0, v1, s[8:9]

; __device__ __forceinline__ void rs_table_fill(LAS unsigned char* lds, const pg8::StaticOrder& S, const float* rs) {
;     ...
;     if (tid < 256) {
;         if (k0 >= 0) tab[tid] = rs[k0 * 256 + tid];
;         if (k1 >= 0) tab[256 + tid] = rs[k1 * 256 + tid];
;         if (k2 >= 0) tab[512 + tid] = rs[k2 * 256 + tid];
;         if (k3 >= 0) tab[768 + tid] = rs[k3 * 256 + tid];
;     }
.LBB0_494:
	s_movk_i32 s0, 0x100
	v_cmp_gt_u32_e32 vcc, s0, v195
	s_and_saveexec_b64 s[0:1], vcc
	s_cbranch_execz .LBB0_503
	s_cmp_lt_i32 s14, 0
	s_cbranch_scc1 .LBB0_497
	v_lshl_or_b32 v0, s14, 8, v195
	v_mov_b32_e32 v1, 0
	s_add_u32 s80, s28, 0x4c00000
	s_addc_u32 s81, s29, 0
	v_lshlrev_b32_e32 v2, 6, v0
	v_lshlrev_b32_e32 v3, 2, v0
	global_load_dwordx4 v[4:7], v2, s[80:81]
	global_load_dwordx4 v[8:11], v2, s[80:81] offset:16
	global_load_dwordx4 v[12:15], v2, s[80:81] offset:32
	global_load_dwordx4 v[16:19], v2, s[80:81] offset:48
	v_lshl_add_u32 v1, v195, 2, 0
	v_add_u32_e32 v1, 0x20000, v1
	s_waitcnt vmcnt(0)
	v_add_f32_e32 v0, v4, v5
	v_add_f32_e32 v0, v6, v0
	v_add_f32_e32 v0, v7, v0
	v_add_f32_e32 v0, v8, v0
	v_add_f32_e32 v0, v9, v0
	v_add_f32_e32 v0, v10, v0
	v_add_f32_e32 v0, v11, v0
	v_add_f32_e32 v0, v12, v0
	v_add_f32_e32 v0, v13, v0
	v_add_f32_e32 v0, v14, v0
	v_add_f32_e32 v0, v15, v0
	v_add_f32_e32 v0, v16, v0
	v_add_f32_e32 v0, v17, v0
	v_add_f32_e32 v0, v18, v0
	v_add_f32_e32 v0, v19, v0
	v_mul_f32_e32 v0, 0x3a800000, v0
	v_add_f32_e32 v0, 0x358637bd, v0
	v_rsq_f32_e32 v0, v0
	s_nop 0
	global_store_dword v3, v0, s[92:93]
	ds_write_b32 v1, v0
.LBB0_497:
	s_cmp_lt_i32 s15, 0
	s_cbranch_scc1 .LBB0_499
	v_lshl_or_b32 v0, s15, 8, v195
	v_mov_b32_e32 v1, 0
	v_lshlrev_b32_e32 v2, 6, v0
	v_lshlrev_b32_e32 v3, 2, v0
	global_load_dwordx4 v[4:7], v2, s[80:81]
	global_load_dwordx4 v[8:11], v2, s[80:81] offset:16
	global_load_dwordx4 v[12:15], v2, s[80:81] offset:32
	global_load_dwordx4 v[16:19], v2, s[80:81] offset:48
	s_add_i32 s4, 0, 0x20000
	v_lshl_add_u32 v1, v195, 2, s4
	s_waitcnt vmcnt(0)
	v_add_f32_e32 v0, v4, v5
	v_add_f32_e32 v0, v6, v0
	v_add_f32_e32 v0, v7, v0
	v_add_f32_e32 v0, v8, v0
	v_add_f32_e32 v0, v9, v0
	v_add_f32_e32 v0, v10, v0
	v_add_f32_e32 v0, v11, v0
	v_add_f32_e32 v0, v12, v0
	v_add_f32_e32 v0, v13, v0
	v_add_f32_e32 v0, v14, v0
	v_add_f32_e32 v0, v15, v0
	v_add_f32_e32 v0, v16, v0
	v_add_f32_e32 v0, v17, v0
	v_add_f32_e32 v0, v18, v0
	v_add_f32_e32 v0, v19, v0
	v_mul_f32_e32 v0, 0x3a800000, v0
	v_add_f32_e32 v0, 0x358637bd, v0
	v_rsq_f32_e32 v0, v0
	s_nop 0
	global_store_dword v3, v0, s[92:93]
	ds_write_b32 v1, v0 offset:1024
.LBB0_499:
	s_cmp_lt_i32 s8, 0
	s_cbranch_scc1 .LBB0_501
	v_lshl_or_b32 v0, s8, 8, v195
	v_mov_b32_e32 v1, 0
	v_lshlrev_b32_e32 v2, 6, v0
	v_lshlrev_b32_e32 v3, 2, v0
	global_load_dwordx4 v[4:7], v2, s[80:81]
	global_load_dwordx4 v[8:11], v2, s[80:81] offset:16
	global_load_dwordx4 v[12:15], v2, s[80:81] offset:32
	global_load_dwordx4 v[16:19], v2, s[80:81] offset:48
	s_add_i32 s4, 0, 0x20000
	v_lshl_add_u32 v1, v195, 2, s4
	s_waitcnt vmcnt(0)
	v_add_f32_e32 v0, v4, v5
	v_add_f32_e32 v0, v6, v0
	v_add_f32_e32 v0, v7, v0
	v_add_f32_e32 v0, v8, v0
	v_add_f32_e32 v0, v9, v0
	v_add_f32_e32 v0, v10, v0
	v_add_f32_e32 v0, v11, v0
	v_add_f32_e32 v0, v12, v0
	v_add_f32_e32 v0, v13, v0
	v_add_f32_e32 v0, v14, v0
	v_add_f32_e32 v0, v15, v0
	v_add_f32_e32 v0, v16, v0
	v_add_f32_e32 v0, v17, v0
	v_add_f32_e32 v0, v18, v0
	v_add_f32_e32 v0, v19, v0
	v_mul_f32_e32 v0, 0x3a800000, v0
	v_add_f32_e32 v0, 0x358637bd, v0
	v_rsq_f32_e32 v0, v0
	s_nop 0
	global_store_dword v3, v0, s[92:93]
	ds_write_b32 v1, v0 offset:2048
.LBB0_501:
	s_cmp_lt_i32 s6, 0
	s_cbranch_scc1 .LBB0_503
	v_lshl_or_b32 v0, s6, 8, v195
	v_mov_b32_e32 v1, 0
	v_lshlrev_b32_e32 v2, 6, v0
	v_lshlrev_b32_e32 v3, 2, v0
	global_load_dwordx4 v[4:7], v2, s[80:81]
	global_load_dwordx4 v[8:11], v2, s[80:81] offset:16
	global_load_dwordx4 v[12:15], v2, s[80:81] offset:32
	global_load_dwordx4 v[16:19], v2, s[80:81] offset:48
	s_add_i32 s4, 0, 0x20000
	v_lshl_add_u32 v1, v195, 2, s4
	s_waitcnt vmcnt(0)
	v_add_f32_e32 v0, v4, v5
	v_add_f32_e32 v0, v6, v0
	v_add_f32_e32 v0, v7, v0
	v_add_f32_e32 v0, v8, v0
	v_add_f32_e32 v0, v9, v0
	v_add_f32_e32 v0, v10, v0
	v_add_f32_e32 v0, v11, v0
	v_add_f32_e32 v0, v12, v0
	v_add_f32_e32 v0, v13, v0
	v_add_f32_e32 v0, v14, v0
	v_add_f32_e32 v0, v15, v0
	v_add_f32_e32 v0, v16, v0
	v_add_f32_e32 v0, v17, v0
	v_add_f32_e32 v0, v18, v0
	v_add_f32_e32 v0, v19, v0
	v_mul_f32_e32 v0, 0x3a800000, v0
	v_add_f32_e32 v0, 0x358637bd, v0
	v_rsq_f32_e32 v0, v0
	s_nop 0
	global_store_dword v3, v0, s[92:93]
	ds_write_b32 v1, v0 offset:3072

; #define SEAM(k) do { if (IN(k) && IN((k) + 1)) { xcd_barrier(xbar); } } while (0)
; __global__ void __launch_bounds__(NWAVES * 64, 2) mk_fwd(Args a) {
;     ...
;     SEAM(4);
.LBB0_625:
	s_cmp_gt_i32 s31, 5
	s_cselect_b64 s[0:1], -1, 0
	s_and_b64 s[4:5], s[12:13], s[0:1]
	s_andn2_b64 vcc, exec, s[4:5]
	s_cbranch_vccnz .LBB0_675
	s_waitcnt vmcnt(0)
	s_barrier
	v_cmp_eq_u32_e32 vcc, 0, v195
	s_and_saveexec_b64 s[4:5], vcc
	s_cbranch_execz .Ltb675_done
	s_and_b32 s3, s2, 7
	s_lshl_b32 s3, s3, 3
	s_bfe_u32 s13, s2, 0x30003
	s_or_b32 s3, s3, s13
	s_lshl_b32 s3, s3, 5
	s_add_u32 s8, s28, 0x3903600
	s_addc_u32 s9, s29, 0
	v_mov_b32_e32 v0, s3
	v_mov_b32_e32 v1, 1
	v_mov_b32_e32 v2, 12
	s_mov_b32 s15, 0
	s_cmp_eq_u32 s99, 1
	s_cbranch_scc1 .Ltb675_fast
	buffer_wbl2 sc1
	s_waitcnt vmcnt(0)
	global_atomic_add v0, v1, s[8:9]

; __device__ __forceinline__ unsigned pk2(float lo, float hi) { bf16x2_t r = __builtin_convertvector((f32x2_t){lo, hi}, bf16x2_t); return __builtin_bit_cast(unsigned, r); }
;     __device__ __forceinline__ void operator()(const pg8::f32x4 (&acc)[2][2][4][2], const pg8::Unit& u, int wr, int wc, int fr, int fq) const {
;     ...
;                     if (PART) {
; #pragma unroll
;                         for (int j = 0; j < 8; ++j) s += r[j] * r[j];
;                     }
;                     v4u w; w.x = pk2(r[0], r[1]); w.y = pk2(r[2], r[3]); w.z = pk2(r[4], r[5]); w.w = pk2(r[6], r[7]);
;                     st16_wt(O + off + bj * 128, w);
;                 }
;                 if (PART) { s += __shfl_xor(s, 16); s += __shfl_xor(s, 32); st4_wt(part + (size_t)row * 16 + u.pn * 4 + wc, s); }
.LBB0_889:
	s_waitcnt lgkmcnt(0)
	v_lshl_or_b32 v242, s41, 8, v148
	v_lshl_add_u32 v243, s40, 8, v146
	v_lshlrev_b32_e32 v194, 2, v242
	v_lshlrev_b32_e32 v153, 1, v242
	v_lshl_add_u32 v153, v243, 11, v153
	v_xor_b32_e32 v166, 16, v152
	v_lshlrev_b32_e32 v166, 2, v166
	v_xor_b32_e32 v168, 32, v152
	v_lshlrev_b32_e32 v168, 2, v168
	v_lshrrev_b32_e32 v161, 4, v152
	v_and_b32_e32 v161, 3, v161
	v_lshlrev_b32_e32 v161, 4, v161
	v_lshl_add_u32 v161, v243, 6, v161
	s_lshl_b32 s95, s41, 4
	s_add_u32 s95, s95, s6
	v_lshl_add_u32 v157, v243, 6, s95
	v_pk_mul_f32 v[242:243], v[124:125], v[124:125]
	v_pk_fma_f32 v[242:243], v[126:127], v[126:127], v[242:243]
	v_pk_fma_f32 v[242:243], v[120:121], v[120:121], v[242:243]
	v_pk_fma_f32 v[242:243], v[122:123], v[122:123], v[242:243]
	v_pk_fma_f32 v[242:243], v[116:117], v[116:117], v[242:243]
	v_pk_fma_f32 v[242:243], v[118:119], v[118:119], v[242:243]
	v_pk_fma_f32 v[242:243], v[112:113], v[112:113], v[242:243]
	v_pk_fma_f32 v[242:243], v[114:115], v[114:115], v[242:243]
	v_add_f32_e32 v145, v242, v243
	v_pk_mul_f32 v[244:245], v[108:109], v[108:109]
	v_pk_fma_f32 v[244:245], v[110:111], v[110:111], v[244:245]
	v_pk_fma_f32 v[244:245], v[104:105], v[104:105], v[244:245]
	v_pk_fma_f32 v[244:245], v[106:107], v[106:107], v[244:245]
	v_pk_fma_f32 v[244:245], v[100:101], v[100:101], v[244:245]
	v_pk_fma_f32 v[244:245], v[102:103], v[102:103], v[244:245]
	v_pk_fma_f32 v[244:245], v[96:97], v[96:97], v[244:245]
	v_pk_fma_f32 v[244:245], v[98:99], v[98:99], v[244:245]
	v_add_f32_e32 v155, v244, v245
	v_pk_mul_f32 v[242:243], v[92:93], v[92:93]
	v_pk_fma_f32 v[242:243], v[94:95], v[94:95], v[242:243]
	v_pk_fma_f32 v[242:243], v[88:89], v[88:89], v[242:243]
	v_pk_fma_f32 v[242:243], v[90:91], v[90:91], v[242:243]
	v_pk_fma_f32 v[242:243], v[84:85], v[84:85], v[242:243]
	v_pk_fma_f32 v[242:243], v[86:87], v[86:87], v[242:243]
	v_pk_fma_f32 v[242:243], v[80:81], v[80:81], v[242:243]
	v_pk_fma_f32 v[242:243], v[82:83], v[82:83], v[242:243]
	v_add_f32_e32 v159, v242, v243
	v_pk_mul_f32 v[244:245], v[76:77], v[76:77]
	v_pk_fma_f32 v[244:245], v[78:79], v[78:79], v[244:245]
	v_pk_fma_f32 v[244:245], v[72:73], v[72:73], v[244:245]
	v_pk_fma_f32 v[244:245], v[74:75], v[74:75], v[244:245]
	v_pk_fma_f32 v[244:245], v[68:69], v[68:69], v[244:245]
	v_pk_fma_f32 v[244:245], v[70:71], v[70:71], v[244:245]
	v_pk_fma_f32 v[244:245], v[64:65], v[64:65], v[244:245]
	v_pk_fma_f32 v[244:245], v[66:67], v[66:67], v[244:245]
	v_add_f32_e32 v163, v244, v245
	v_pk_mul_f32 v[242:243], v[60:61], v[60:61]
	v_pk_fma_f32 v[242:243], v[62:63], v[62:63], v[242:243]
	v_pk_fma_f32 v[242:243], v[56:57], v[56:57], v[242:243]
	v_pk_fma_f32 v[242:243], v[58:59], v[58:59], v[242:243]
	v_pk_fma_f32 v[242:243], v[52:53], v[52:53], v[242:243]
	v_pk_fma_f32 v[242:243], v[54:55], v[54:55], v[242:243]
	v_pk_fma_f32 v[242:243], v[48:49], v[48:49], v[242:243]
	v_pk_fma_f32 v[242:243], v[50:51], v[50:51], v[242:243]
	v_add_f32_e32 v165, v242, v243
	v_pk_mul_f32 v[244:245], v[44:45], v[44:45]
	v_pk_fma_f32 v[244:245], v[46:47], v[46:47], v[244:245]
	v_pk_fma_f32 v[244:245], v[40:41], v[40:41], v[244:245]
	v_pk_fma_f32 v[244:245], v[42:43], v[42:43], v[244:245]
	v_pk_fma_f32 v[244:245], v[36:37], v[36:37], v[244:245]
	v_pk_fma_f32 v[244:245], v[38:39], v[38:39], v[244:245]
	v_pk_fma_f32 v[244:245], v[32:33], v[32:33], v[244:245]
	v_pk_fma_f32 v[244:245], v[34:35], v[34:35], v[244:245]
	v_add_f32_e32 v171, v244, v245
	v_pk_mul_f32 v[242:243], v[28:29], v[28:29]
	v_pk_fma_f32 v[242:243], v[30:31], v[30:31], v[242:243]
	v_pk_fma_f32 v[242:243], v[24:25], v[24:25], v[242:243]
	v_pk_fma_f32 v[242:243], v[26:27], v[26:27], v[242:243]
	v_pk_fma_f32 v[242:243], v[20:21], v[20:21], v[242:243]
	v_pk_fma_f32 v[242:243], v[22:23], v[22:23], v[242:243]
	v_pk_fma_f32 v[242:243], v[16:17], v[16:17], v[242:243]
	v_pk_fma_f32 v[242:243], v[18:19], v[18:19], v[242:243]
	v_add_f32_e32 v193, v242, v243
	v_pk_mul_f32 v[244:245], v[12:13], v[12:13]
	v_pk_fma_f32 v[244:245], v[14:15], v[14:15], v[244:245]
	v_pk_fma_f32 v[244:245], v[8:9], v[8:9], v[244:245]
	v_pk_fma_f32 v[244:245], v[10:11], v[10:11], v[244:245]
	v_pk_fma_f32 v[244:245], v[4:5], v[4:5], v[244:245]
	v_pk_fma_f32 v[244:245], v[6:7], v[6:7], v[244:245]
	v_pk_fma_f32 v[244:245], v[0:1], v[0:1], v[244:245]
	v_pk_fma_f32 v[244:245], v[2:3], v[2:3], v[244:245]
	v_add_f32_e32 v241, v244, v245
	s_nop 1
	ds_bpermute_b32 v188, v166, v145
	ds_bpermute_b32 v196, v166, v155
	ds_bpermute_b32 v200, v166, v159
	ds_bpermute_b32 v204, v166, v163
	ds_bpermute_b32 v208, v166, v165
	ds_bpermute_b32 v212, v166, v171
	ds_bpermute_b32 v216, v166, v193
	ds_bpermute_b32 v220, v166, v241
	s_waitcnt lgkmcnt(0)
	v_add_f32_e32 v145, v145, v188
	v_add_f32_e32 v155, v155, v196
	v_add_f32_e32 v159, v159, v200
	v_add_f32_e32 v163, v163, v204
	v_add_f32_e32 v165, v165, v208
	v_add_f32_e32 v171, v171, v212
	v_add_f32_e32 v193, v193, v216
	v_add_f32_e32 v241, v241, v220
	s_nop 1
	ds_bpermute_b32 v188, v168, v145
	ds_bpermute_b32 v196, v168, v155
	ds_bpermute_b32 v200, v168, v159
	ds_bpermute_b32 v204, v168, v163
	ds_bpermute_b32 v208, v168, v165
	ds_bpermute_b32 v212, v168, v171
	ds_bpermute_b32 v216, v168, v193
	ds_bpermute_b32 v220, v168, v241
	s_waitcnt lgkmcnt(0)
	v_add_f32_e32 v145, v145, v188
	v_add_f32_e32 v155, v155, v196
	v_add_f32_e32 v159, v159, v200
	v_add_f32_e32 v163, v163, v204
	v_add_f32_e32 v165, v165, v208
	v_add_f32_e32 v171, v171, v212
	v_add_f32_e32 v193, v193, v216
	v_add_f32_e32 v241, v241, v220
	global_store_dword v157, v145, s[20:21]
	v_add_u32_e32 v196, 0x400, v157
	global_store_dword v196, v155, s[20:21]
	v_add_u32_e32 v200, 0x800, v157
	global_store_dword v200, v159, s[20:21]
	v_add_u32_e32 v204, 0xc00, v157
	global_store_dword v204, v163, s[20:21]
	v_add_u32_e32 v208, 0x2000, v157
	global_store_dword v208, v165, s[20:21]
	v_add_u32_e32 v212, 0x2400, v157
	global_store_dword v212, v171, s[20:21]
	v_add_u32_e32 v216, 0x2800, v157
	global_store_dword v216, v193, s[20:21]
	v_add_u32_e32 v220, 0x2c00, v157
	global_store_dword v220, v241, s[20:21]
	s_waitcnt vmcnt(0)
	s_barrier
	v_readfirstlane_b32 s94, v195
	s_cmp_lg_u32 s94, 0
	s_cbranch_scc1 .Lfe1_bskip
	s_mov_b64 exec, 1
	s_and_b32 s94, s2, 7
	s_lshl_b32 s94, s94, 3
	s_bfe_u32 s96, s2, 0x30003
	s_or_b32 s94, s94, s96
	s_lshl_b32 s94, s94, 5
	s_add_u32 s62, s28, 0x3903600
	s_addc_u32 s63, s29, 0
	v_mov_b32_e32 v242, s94
	v_mov_b32_e32 v243, 1
	s_cmp_eq_u32 s99, 1
	s_cbranch_scc1 .Lfe1_bfast
	buffer_wbl2 sc1
	s_waitcnt vmcnt(0)

; template <bool SRC_F32, int R> __device__ __forceinline__ void ew_load(EwSet<SRC_F32, R>& S, int rb, const float* hsrc32, const bf16* hsrcb, const bf16* f, const float* part, int lane) {
;     ...
;     for (int i = 0; i < R; ++i) S.p[i] = (lane < 16) ? part[(size_t)(rb + i) * 16 + lane] : 0.f;
; #pragma unroll
;     for (int i = 0; i < R; ++i)
; #pragma unroll
;         for (int j = 0; j < 4; ++j) {
;             S.fw[i][j] = ((const v2u*)(f + (size_t)(rb + i) * D) + lane)[64 * j];
;             if constexpr (SRC_F32) S.h32[i][j] = __builtin_nontemporal_load((const f32x4*)(hsrc32 + (size_t)(rb + i) * D) + lane + 64 * j);
;             else S.hb[i][j] = ((const v2u*)(hsrcb + (size_t)(rb + i) * D) + lane)[64 * j];
;         }
; }
; template <bool SRC_F32, bool FINAL, int R> __device__ __forceinline__ void ew_compute(const EwSet<SRC_F32, R>& S, int rb, const f32x4 (&g)[4], bf16* hb_out, float* out32, float scale, float* rs_out, int lane) {
; #pragma unroll
;     for (int i = 0; i < R; ++i) {
;         float q = S.p[i];
;         q += __shfl_xor(q, 1); q += __shfl_xor(q, 2); q += __shfl_xor(q, 4); q += __shfl_xor(q, 8);
;         const float ss = __shfl(q, 0);
;         const float rs = scale / sqrtf(ss * (1.f / D) + EPS);
.Lfe1_bskip:
	s_barrier
	s_add_u32 s62, s84, 0xffffff10
	s_addc_u32 s63, s85, -1
	s_load_dwordx2 s[64:65], s[62:63], 0x88
	s_add_u32 s66, s28, 0x5000000
	s_addc_u32 s67, s29, 0
	s_add_u32 s78, s28, 0x4c00000
	s_addc_u32 s79, s29, 0
	global_load_dwordx4 v[188:191], v161, s[20:21]
	v_add_u32_e32 v244, 0x400, v161
	global_load_dwordx4 v[196:199], v244, s[20:21]
	v_add_u32_e32 v244, 0x800, v161
	global_load_dwordx4 v[200:203], v244, s[20:21]
	v_add_u32_e32 v244, 0xc00, v161
	global_load_dwordx4 v[204:207], v244, s[20:21]
	v_add_u32_e32 v244, 0x2000, v161
	global_load_dwordx4 v[208:211], v244, s[20:21]
	v_add_u32_e32 v244, 0x2400, v161
	global_load_dwordx4 v[212:215], v244, s[20:21]
	v_add_u32_e32 v244, 0x2800, v161
	global_load_dwordx4 v[216:219], v244, s[20:21]
	v_add_u32_e32 v244, 0x2c00, v161
	global_load_dwordx4 v[220:223], v244, s[20:21]
	global_load_dwordx4 v[224:227], v153, s[66:67]
	global_load_dwordx4 v[228:231], v153, s[66:67] offset:256
	v_add_u32_e32 v244, 0x8000, v153
	global_load_dwordx4 v[232:235], v244, s[66:67]
	global_load_dwordx4 v[236:239], v244, s[66:67] offset:256
	s_waitcnt lgkmcnt(0)
	global_load_dwordx4 v[172:175], v194, s[64:65]
	global_load_dwordx4 v[176:179], v194, s[64:65] offset:16
	global_load_dwordx4 v[180:183], v194, s[64:65] offset:512
	global_load_dwordx4 v[184:187], v194, s[64:65] offset:528
	s_waitcnt vmcnt(8)
	v_add_f32_e32 v145, v188, v189
	v_add_f32_e32 v145, v190, v145
	v_add_f32_e32 v145, v191, v145
	v_add_f32_e32 v155, v196, v197
	v_add_f32_e32 v155, v198, v155
	v_add_f32_e32 v155, v199, v155
	v_add_f32_e32 v159, v200, v201
	v_add_f32_e32 v159, v202, v159
	v_add_f32_e32 v159, v203, v159
	v_add_f32_e32 v163, v204, v205
	v_add_f32_e32 v163, v206, v163
	v_add_f32_e32 v163, v207, v163
	v_add_f32_e32 v165, v208, v209
	v_add_f32_e32 v165, v210, v165
	v_add_f32_e32 v165, v211, v165
	v_add_f32_e32 v171, v212, v213
	v_add_f32_e32 v171, v214, v171
	v_add_f32_e32 v171, v215, v171
	v_add_f32_e32 v193, v216, v217
	v_add_f32_e32 v193, v218, v193
	v_add_f32_e32 v193, v219, v193
	v_add_f32_e32 v241, v220, v221
	v_add_f32_e32 v241, v222, v241
	v_add_f32_e32 v241, v223, v241
	s_nop 1
	ds_bpermute_b32 v188, v166, v145
	ds_bpermute_b32 v196, v166, v155
	ds_bpermute_b32 v200, v166, v159
	ds_bpermute_b32 v204, v166, v163
	ds_bpermute_b32 v208, v166, v165
	ds_bpermute_b32 v212, v166, v171
	ds_bpermute_b32 v216, v166, v193
	ds_bpermute_b32 v220, v166, v241
	s_waitcnt lgkmcnt(0)
	v_add_f32_e32 v145, v145, v188
	v_add_f32_e32 v155, v155, v196
	v_add_f32_e32 v159, v159, v200
	v_add_f32_e32 v163, v163, v204
	v_add_f32_e32 v165, v165, v208
	v_add_f32_e32 v171, v171, v212
	v_add_f32_e32 v193, v193, v216
	v_add_f32_e32 v241, v241, v220
	s_nop 1
	ds_bpermute_b32 v188, v168, v145
	ds_bpermute_b32 v196, v168, v155
	ds_bpermute_b32 v200, v168, v159
	ds_bpermute_b32 v204, v168, v163
	ds_bpermute_b32 v208, v168, v165
	ds_bpermute_b32 v212, v168, v171
	ds_bpermute_b32 v216, v168, v193
	ds_bpermute_b32 v220, v168, v241
	s_waitcnt lgkmcnt(0)
	v_add_f32_e32 v145, v145, v188
	v_add_f32_e32 v155, v155, v196
	v_add_f32_e32 v159, v159, v200
	v_add_f32_e32 v163, v163, v204
	v_add_f32_e32 v165, v165, v208
	v_add_f32_e32 v171, v171, v212
	v_add_f32_e32 v193, v193, v216
	v_add_f32_e32 v241, v241, v220
	v_mul_f32_e32 v145, 0x3a800000, v145
	v_mul_f32_e32 v155, 0x3a800000, v155
	v_mul_f32_e32 v159, 0x3a800000, v159
	v_mul_f32_e32 v163, 0x3a800000, v163
	v_mul_f32_e32 v165, 0x3a800000, v165
	v_mul_f32_e32 v171, 0x3a800000, v171
	v_mul_f32_e32 v193, 0x3a800000, v193
	v_mul_f32_e32 v241, 0x3a800000, v241
	v_add_f32_e32 v145, 0x358637bd, v145
	v_add_f32_e32 v155, 0x358637bd, v155
	v_add_f32_e32 v159, 0x358637bd, v159
	v_add_f32_e32 v163, 0x358637bd, v163
	v_add_f32_e32 v165, 0x358637bd, v165
	v_add_f32_e32 v171, 0x358637bd, v171
	v_add_f32_e32 v193, 0x358637bd, v193
	v_add_f32_e32 v241, 0x358637bd, v241
	v_rsq_f32_e32 v144, v145
	v_rsq_f32_e32 v154, v155
	v_rsq_f32_e32 v158, v159
	v_rsq_f32_e32 v162, v163
	v_rsq_f32_e32 v164, v165
	v_rsq_f32_e32 v170, v171
	v_rsq_f32_e32 v192, v193
	v_rsq_f32_e32 v240, v241
	s_nop 0
	v_add_u32_e32 v244, 0x10000, v153
	global_load_dwordx4 v[188:191], v244, s[66:67]
	global_load_dwordx4 v[196:199], v244, s[66:67] offset:256
	v_add_u32_e32 v244, 0x18000, v153
	global_load_dwordx4 v[200:203], v244, s[66:67]
	global_load_dwordx4 v[204:207], v244, s[66:67] offset:256
	v_add_u32_e32 v244, 0x40000, v153
	global_load_dwordx4 v[208:211], v244, s[66:67]
	global_load_dwordx4 v[212:215], v244, s[66:67] offset:256
	v_add_u32_e32 v244, 0x48000, v153
	global_load_dwordx4 v[216:219], v244, s[66:67]
	global_load_dwordx4 v[220:223], v244, s[66:67] offset:256
	s_waitcnt vmcnt(8)
; __device__ __forceinline__ float bf_lo(unsigned w) { return __uint_as_float(w << 16); }
; __device__ __forceinline__ float bf_hi(unsigned w) { return __uint_as_float(w & 0xffff0000u); }
; __device__ __forceinline__ unsigned pk2(float lo, float hi) { bf16x2_t r = __builtin_convertvector((f32x2_t){lo, hi}, bf16x2_t); return __builtin_bit_cast(unsigned, r); }
; template <bool SRC_F32, bool FINAL, int R> __device__ __forceinline__ void ew_compute(const EwSet<SRC_F32, R>& S, int rb, const f32x4 (&g)[4], bf16* hb_out, float* out32, float scale, float* rs_out, int lane) {
;     ...
; #pragma unroll
;         for (int j = 0; j < 4; ++j) {
;             f32x4 h;
;             if constexpr (SRC_F32) h = S.h32[i][j];
;             else { const v2u hw = S.hb[i][j]; h.x = bf_lo(hw.x); h.y = bf_hi(hw.x); h.z = bf_lo(hw.y); h.w = bf_hi(hw.y); }
;             const v2u fw = S.fw[i][j];
;             f32x4 v; v.x = h.x + bf_lo(fw.x) * rs * g[j].x; v.y = h.y + bf_hi(fw.x) * rs * g[j].y; v.z = h.z + bf_lo(fw.y) * rs * g[j].z; v.w = h.w + bf_hi(fw.y) * rs * g[j].w;
;             if (FINAL) __builtin_nontemporal_store(v, (f32x4*)(out32 + (size_t)(rb + i) * D) + lane + 64 * j);
;             else { v2u o; o.x = pk2(v.x, v.y); o.y = pk2(v.z, v.w); ((v2u*)(hb_out + (size_t)(rb + i) * D) + lane)[64 * j] = o; s2 += (v.x * v.x + v.y * v.y) + (v.z * v.z + v.w * v.w); }
;         }
;         if (!FINAL) { const float tot = wave_sum(s2); if (lane == 0) rs_out[rb + i] = 1.0f / sqrtf(tot * (1.f / D) + EPS); }
	v_lshlrev_b32_e32 v242, 16, v224
	v_and_b32_e32 v243, 0xffff0000, v224
	v_pk_mul_f32 v[124:125], v[124:125], v[144:145] op_sel_hi:[1,0]
	v_pk_fma_f32 v[124:125], v[124:125], v[172:173], v[242:243]
	v_lshlrev_b32_e32 v244, 16, v225
	v_and_b32_e32 v245, 0xffff0000, v225
	v_pk_mul_f32 v[126:127], v[126:127], v[144:145] op_sel_hi:[1,0]
	v_pk_fma_f32 v[126:127], v[126:127], v[174:175], v[244:245]
	v_lshlrev_b32_e32 v242, 16, v226
	v_and_b32_e32 v243, 0xffff0000, v226
	v_pk_mul_f32 v[120:121], v[120:121], v[144:145] op_sel_hi:[1,0]
	v_pk_fma_f32 v[120:121], v[120:121], v[176:177], v[242:243]
	v_lshlrev_b32_e32 v244, 16, v227
	v_and_b32_e32 v245, 0xffff0000, v227
	v_pk_mul_f32 v[122:123], v[122:123], v[144:145] op_sel_hi:[1,0]
	v_pk_fma_f32 v[122:123], v[122:123], v[178:179], v[244:245]
	v_lshlrev_b32_e32 v242, 16, v228
	v_and_b32_e32 v243, 0xffff0000, v228
	v_pk_mul_f32 v[116:117], v[116:117], v[144:145] op_sel_hi:[1,0]
	v_pk_fma_f32 v[116:117], v[116:117], v[180:181], v[242:243]
	v_lshlrev_b32_e32 v244, 16, v229
	v_and_b32_e32 v245, 0xffff0000, v229
	v_pk_mul_f32 v[118:119], v[118:119], v[144:145] op_sel_hi:[1,0]
	v_pk_fma_f32 v[118:119], v[118:119], v[182:183], v[244:245]
	v_lshlrev_b32_e32 v242, 16, v230
	v_and_b32_e32 v243, 0xffff0000, v230
	v_pk_mul_f32 v[112:113], v[112:113], v[144:145] op_sel_hi:[1,0]
	v_pk_fma_f32 v[112:113], v[112:113], v[184:185], v[242:243]
	v_lshlrev_b32_e32 v244, 16, v231
	v_and_b32_e32 v245, 0xffff0000, v231
	v_pk_mul_f32 v[114:115], v[114:115], v[144:145] op_sel_hi:[1,0]
	v_pk_fma_f32 v[114:115], v[114:115], v[186:187], v[244:245]
	v_pk_mul_f32 v[242:243], v[124:125], v[124:125]
	v_pk_fma_f32 v[242:243], v[126:127], v[126:127], v[242:243]
	v_pk_fma_f32 v[242:243], v[120:121], v[120:121], v[242:243]
	v_pk_fma_f32 v[242:243], v[122:123], v[122:123], v[242:243]
	v_pk_fma_f32 v[242:243], v[116:117], v[116:117], v[242:243]
	v_pk_fma_f32 v[242:243], v[118:119], v[118:119], v[242:243]
	v_pk_fma_f32 v[242:243], v[112:113], v[112:113], v[242:243]
	v_pk_fma_f32 v[242:243], v[114:115], v[114:115], v[242:243]
	v_add_f32_e32 v145, v242, v243
	v_cvt_pk_bf16_f32 v224, v124, v125
	v_cvt_pk_bf16_f32 v225, v126, v127
	v_cvt_pk_bf16_f32 v226, v120, v121
	v_cvt_pk_bf16_f32 v227, v122, v123
	v_cvt_pk_bf16_f32 v228, v116, v117
	v_cvt_pk_bf16_f32 v229, v118, v119
	v_cvt_pk_bf16_f32 v230, v112, v113
	v_cvt_pk_bf16_f32 v231, v114, v115
	s_nop 0
	global_store_dwordx4 v153, v[224:227], s[66:67]
	global_store_dwordx4 v153, v[228:231], s[66:67] offset:256
	s_waitcnt vmcnt(10)
	v_lshlrev_b32_e32 v242, 16, v232
	v_and_b32_e32 v243, 0xffff0000, v232
	v_pk_mul_f32 v[108:109], v[108:109], v[154:155] op_sel_hi:[1,0]
	v_pk_fma_f32 v[108:109], v[108:109], v[172:173], v[242:243]
	v_lshlrev_b32_e32 v244, 16, v233
	v_and_b32_e32 v245, 0xffff0000, v233
	v_pk_mul_f32 v[110:111], v[110:111], v[154:155] op_sel_hi:[1,0]
	v_pk_fma_f32 v[110:111], v[110:111], v[174:175], v[244:245]
	v_lshlrev_b32_e32 v242, 16, v234
	v_and_b32_e32 v243, 0xffff0000, v234
	v_pk_mul_f32 v[104:105], v[104:105], v[154:155] op_sel_hi:[1,0]
	v_pk_fma_f32 v[104:105], v[104:105], v[176:177], v[242:243]
	v_lshlrev_b32_e32 v244, 16, v235
	v_and_b32_e32 v245, 0xffff0000, v235
	v_pk_mul_f32 v[106:107], v[106:107], v[154:155] op_sel_hi:[1,0]
	v_pk_fma_f32 v[106:107], v[106:107], v[178:179], v[244:245]
	v_lshlrev_b32_e32 v242, 16, v236
	v_and_b32_e32 v243, 0xffff0000, v236
	v_pk_mul_f32 v[100:101], v[100:101], v[154:155] op_sel_hi:[1,0]
	v_pk_fma_f32 v[100:101], v[100:101], v[180:181], v[242:243]
	v_lshlrev_b32_e32 v244, 16, v237
	v_and_b32_e32 v245, 0xffff0000, v237
	v_pk_mul_f32 v[102:103], v[102:103], v[154:155] op_sel_hi:[1,0]
	v_pk_fma_f32 v[102:103], v[102:103], v[182:183], v[244:245]
	v_lshlrev_b32_e32 v242, 16, v238
	v_and_b32_e32 v243, 0xffff0000, v238
	v_pk_mul_f32 v[96:97], v[96:97], v[154:155] op_sel_hi:[1,0]
	v_pk_fma_f32 v[96:97], v[96:97], v[184:185], v[242:243]
	v_lshlrev_b32_e32 v244, 16, v239
	v_and_b32_e32 v245, 0xffff0000, v239
	v_pk_mul_f32 v[98:99], v[98:99], v[154:155] op_sel_hi:[1,0]
	v_pk_fma_f32 v[98:99], v[98:99], v[186:187], v[244:245]
	v_pk_mul_f32 v[242:243], v[108:109], v[108:109]
	v_pk_fma_f32 v[242:243], v[110:111], v[110:111], v[242:243]
	v_pk_fma_f32 v[242:243], v[104:105], v[104:105], v[242:243]
	v_pk_fma_f32 v[242:243], v[106:107], v[106:107], v[242:243]
	v_pk_fma_f32 v[242:243], v[100:101], v[100:101], v[242:243]
	v_pk_fma_f32 v[242:243], v[102:103], v[102:103], v[242:243]
	v_pk_fma_f32 v[242:243], v[96:97], v[96:97], v[242:243]
	v_pk_fma_f32 v[242:243], v[98:99], v[98:99], v[242:243]
	v_add_f32_e32 v155, v242, v243
	v_cvt_pk_bf16_f32 v232, v108, v109
	v_cvt_pk_bf16_f32 v233, v110, v111
	v_cvt_pk_bf16_f32 v234, v104, v105
	v_cvt_pk_bf16_f32 v235, v106, v107
	v_cvt_pk_bf16_f32 v236, v100, v101
	v_cvt_pk_bf16_f32 v237, v102, v103
	v_cvt_pk_bf16_f32 v238, v96, v97
	v_cvt_pk_bf16_f32 v239, v98, v99
	v_add_u32_e32 v244, 0x8000, v153
	s_nop 0
	global_store_dwordx4 v244, v[232:235], s[66:67]
	global_store_dwordx4 v244, v[236:239], s[66:67] offset:256
	s_nop 1
	v_add_u32_e32 v244, 0x50000, v153
	global_load_dwordx4 v[224:227], v244, s[66:67]
	global_load_dwordx4 v[228:231], v244, s[66:67] offset:256
	v_add_u32_e32 v244, 0x58000, v153
	global_load_dwordx4 v[232:235], v244, s[66:67]
	global_load_dwordx4 v[236:239], v244, s[66:67] offset:256
	s_waitcnt vmcnt(14)
; __device__ __forceinline__ float bf_lo(unsigned w) { return __uint_as_float(w << 16); }
; __device__ __forceinline__ float bf_hi(unsigned w) { return __uint_as_float(w & 0xffff0000u); }
; __device__ __forceinline__ unsigned pk2(float lo, float hi) { bf16x2_t r = __builtin_convertvector((f32x2_t){lo, hi}, bf16x2_t); return __builtin_bit_cast(unsigned, r); }
; template <bool SRC_F32, bool FINAL, int R> __device__ __forceinline__ void ew_compute(const EwSet<SRC_F32, R>& S, int rb, const f32x4 (&g)[4], bf16* hb_out, float* out32, float scale, float* rs_out, int lane) {
;     ...
; #pragma unroll
;         for (int j = 0; j < 4; ++j) {
;             f32x4 h;
;             if constexpr (SRC_F32) h = S.h32[i][j];
;             else { const v2u hw = S.hb[i][j]; h.x = bf_lo(hw.x); h.y = bf_hi(hw.x); h.z = bf_lo(hw.y); h.w = bf_hi(hw.y); }
;             const v2u fw = S.fw[i][j];
;             f32x4 v; v.x = h.x + bf_lo(fw.x) * rs * g[j].x; v.y = h.y + bf_hi(fw.x) * rs * g[j].y; v.z = h.z + bf_lo(fw.y) * rs * g[j].z; v.w = h.w + bf_hi(fw.y) * rs * g[j].w;
;             if (FINAL) __builtin_nontemporal_store(v, (f32x4*)(out32 + (size_t)(rb + i) * D) + lane + 64 * j);
;             else { v2u o; o.x = pk2(v.x, v.y); o.y = pk2(v.z, v.w); ((v2u*)(hb_out + (size_t)(rb + i) * D) + lane)[64 * j] = o; s2 += (v.x * v.x + v.y * v.y) + (v.z * v.z + v.w * v.w); }
;         }
;         if (!FINAL) { const float tot = wave_sum(s2); if (lane == 0) rs_out[rb + i] = 1.0f / sqrtf(tot * (1.f / D) + EPS); }
	v_lshlrev_b32_e32 v242, 16, v188
	v_and_b32_e32 v243, 0xffff0000, v188
	v_pk_mul_f32 v[92:93], v[92:93], v[158:159] op_sel_hi:[1,0]
	v_pk_fma_f32 v[92:93], v[92:93], v[172:173], v[242:243]
	v_lshlrev_b32_e32 v244, 16, v189
	v_and_b32_e32 v245, 0xffff0000, v189
	v_pk_mul_f32 v[94:95], v[94:95], v[158:159] op_sel_hi:[1,0]
	v_pk_fma_f32 v[94:95], v[94:95], v[174:175], v[244:245]
	v_lshlrev_b32_e32 v242, 16, v190
	v_and_b32_e32 v243, 0xffff0000, v190
	v_pk_mul_f32 v[88:89], v[88:89], v[158:159] op_sel_hi:[1,0]
	v_pk_fma_f32 v[88:89], v[88:89], v[176:177], v[242:243]
	v_lshlrev_b32_e32 v244, 16, v191
	v_and_b32_e32 v245, 0xffff0000, v191
	v_pk_mul_f32 v[90:91], v[90:91], v[158:159] op_sel_hi:[1,0]
	v_pk_fma_f32 v[90:91], v[90:91], v[178:179], v[244:245]
	v_lshlrev_b32_e32 v242, 16, v196
	v_and_b32_e32 v243, 0xffff0000, v196
	v_pk_mul_f32 v[84:85], v[84:85], v[158:159] op_sel_hi:[1,0]
	v_pk_fma_f32 v[84:85], v[84:85], v[180:181], v[242:243]
	v_lshlrev_b32_e32 v244, 16, v197
	v_and_b32_e32 v245, 0xffff0000, v197
	v_pk_mul_f32 v[86:87], v[86:87], v[158:159] op_sel_hi:[1,0]
	v_pk_fma_f32 v[86:87], v[86:87], v[182:183], v[244:245]
	v_lshlrev_b32_e32 v242, 16, v198
	v_and_b32_e32 v243, 0xffff0000, v198
	v_pk_mul_f32 v[80:81], v[80:81], v[158:159] op_sel_hi:[1,0]
	v_pk_fma_f32 v[80:81], v[80:81], v[184:185], v[242:243]
	v_lshlrev_b32_e32 v244, 16, v199
	v_and_b32_e32 v245, 0xffff0000, v199
	v_pk_mul_f32 v[82:83], v[82:83], v[158:159] op_sel_hi:[1,0]
	v_pk_fma_f32 v[82:83], v[82:83], v[186:187], v[244:245]
	v_pk_mul_f32 v[242:243], v[92:93], v[92:93]
	v_pk_fma_f32 v[242:243], v[94:95], v[94:95], v[242:243]
	v_pk_fma_f32 v[242:243], v[88:89], v[88:89], v[242:243]
	v_pk_fma_f32 v[242:243], v[90:91], v[90:91], v[242:243]
	v_pk_fma_f32 v[242:243], v[84:85], v[84:85], v[242:243]
	v_pk_fma_f32 v[242:243], v[86:87], v[86:87], v[242:243]
	v_pk_fma_f32 v[242:243], v[80:81], v[80:81], v[242:243]
	v_pk_fma_f32 v[242:243], v[82:83], v[82:83], v[242:243]
	v_add_f32_e32 v159, v242, v243
	v_cvt_pk_bf16_f32 v188, v92, v93
	v_cvt_pk_bf16_f32 v189, v94, v95
	v_cvt_pk_bf16_f32 v190, v88, v89
	v_cvt_pk_bf16_f32 v191, v90, v91
	v_cvt_pk_bf16_f32 v196, v84, v85
	v_cvt_pk_bf16_f32 v197, v86, v87
	v_cvt_pk_bf16_f32 v198, v80, v81
	v_cvt_pk_bf16_f32 v199, v82, v83
	v_add_u32_e32 v244, 0x10000, v153
	s_nop 0
	global_store_dwordx4 v244, v[188:191], s[66:67]
	global_store_dwordx4 v244, v[196:199], s[66:67] offset:256
	s_waitcnt vmcnt(14)
	v_lshlrev_b32_e32 v242, 16, v200
	v_and_b32_e32 v243, 0xffff0000, v200
	v_pk_mul_f32 v[76:77], v[76:77], v[162:163] op_sel_hi:[1,0]
	v_pk_fma_f32 v[76:77], v[76:77], v[172:173], v[242:243]
	v_lshlrev_b32_e32 v244, 16, v201
	v_and_b32_e32 v245, 0xffff0000, v201
	v_pk_mul_f32 v[78:79], v[78:79], v[162:163] op_sel_hi:[1,0]
	v_pk_fma_f32 v[78:79], v[78:79], v[174:175], v[244:245]
	v_lshlrev_b32_e32 v242, 16, v202
	v_and_b32_e32 v243, 0xffff0000, v202
	v_pk_mul_f32 v[72:73], v[72:73], v[162:163] op_sel_hi:[1,0]
	v_pk_fma_f32 v[72:73], v[72:73], v[176:177], v[242:243]
	v_lshlrev_b32_e32 v244, 16, v203
	v_and_b32_e32 v245, 0xffff0000, v203
	v_pk_mul_f32 v[74:75], v[74:75], v[162:163] op_sel_hi:[1,0]
	v_pk_fma_f32 v[74:75], v[74:75], v[178:179], v[244:245]
	v_lshlrev_b32_e32 v242, 16, v204
	v_and_b32_e32 v243, 0xffff0000, v204
	v_pk_mul_f32 v[68:69], v[68:69], v[162:163] op_sel_hi:[1,0]
	v_pk_fma_f32 v[68:69], v[68:69], v[180:181], v[242:243]
	v_lshlrev_b32_e32 v244, 16, v205
	v_and_b32_e32 v245, 0xffff0000, v205
	v_pk_mul_f32 v[70:71], v[70:71], v[162:163] op_sel_hi:[1,0]
	v_pk_fma_f32 v[70:71], v[70:71], v[182:183], v[244:245]
	v_lshlrev_b32_e32 v242, 16, v206
	v_and_b32_e32 v243, 0xffff0000, v206
	v_pk_mul_f32 v[64:65], v[64:65], v[162:163] op_sel_hi:[1,0]
	v_pk_fma_f32 v[64:65], v[64:65], v[184:185], v[242:243]
	v_lshlrev_b32_e32 v244, 16, v207
	v_and_b32_e32 v245, 0xffff0000, v207
	v_pk_mul_f32 v[66:67], v[66:67], v[162:163] op_sel_hi:[1,0]
	v_pk_fma_f32 v[66:67], v[66:67], v[186:187], v[244:245]
	v_pk_mul_f32 v[242:243], v[76:77], v[76:77]
	v_pk_fma_f32 v[242:243], v[78:79], v[78:79], v[242:243]
	v_pk_fma_f32 v[242:243], v[72:73], v[72:73], v[242:243]
	v_pk_fma_f32 v[242:243], v[74:75], v[74:75], v[242:243]
	v_pk_fma_f32 v[242:243], v[68:69], v[68:69], v[242:243]
	v_pk_fma_f32 v[242:243], v[70:71], v[70:71], v[242:243]
	v_pk_fma_f32 v[242:243], v[64:65], v[64:65], v[242:243]
	v_pk_fma_f32 v[242:243], v[66:67], v[66:67], v[242:243]
	v_add_f32_e32 v163, v242, v243
	v_cvt_pk_bf16_f32 v200, v76, v77
	v_cvt_pk_bf16_f32 v201, v78, v79
	v_cvt_pk_bf16_f32 v202, v72, v73
	v_cvt_pk_bf16_f32 v203, v74, v75
	v_cvt_pk_bf16_f32 v204, v68, v69
	v_cvt_pk_bf16_f32 v205, v70, v71
	v_cvt_pk_bf16_f32 v206, v64, v65
	v_cvt_pk_bf16_f32 v207, v66, v67
	v_add_u32_e32 v244, 0x18000, v153
	s_nop 0
	global_store_dwordx4 v244, v[200:203], s[66:67]
	global_store_dwordx4 v244, v[204:207], s[66:67] offset:256
	s_waitcnt vmcnt(14)
; __device__ __forceinline__ float bf_lo(unsigned w) { return __uint_as_float(w << 16); }
; __device__ __forceinline__ float bf_hi(unsigned w) { return __uint_as_float(w & 0xffff0000u); }
; __device__ __forceinline__ unsigned pk2(float lo, float hi) { bf16x2_t r = __builtin_convertvector((f32x2_t){lo, hi}, bf16x2_t); return __builtin_bit_cast(unsigned, r); }
; template <bool SRC_F32, bool FINAL, int R> __device__ __forceinline__ void ew_compute(const EwSet<SRC_F32, R>& S, int rb, const f32x4 (&g)[4], bf16* hb_out, float* out32, float scale, float* rs_out, int lane) {
;     ...
; #pragma unroll
;         for (int j = 0; j < 4; ++j) {
;             f32x4 h;
;             if constexpr (SRC_F32) h = S.h32[i][j];
;             else { const v2u hw = S.hb[i][j]; h.x = bf_lo(hw.x); h.y = bf_hi(hw.x); h.z = bf_lo(hw.y); h.w = bf_hi(hw.y); }
;             const v2u fw = S.fw[i][j];
;             f32x4 v; v.x = h.x + bf_lo(fw.x) * rs * g[j].x; v.y = h.y + bf_hi(fw.x) * rs * g[j].y; v.z = h.z + bf_lo(fw.y) * rs * g[j].z; v.w = h.w + bf_hi(fw.y) * rs * g[j].w;
;             if (FINAL) __builtin_nontemporal_store(v, (f32x4*)(out32 + (size_t)(rb + i) * D) + lane + 64 * j);
;             else { v2u o; o.x = pk2(v.x, v.y); o.y = pk2(v.z, v.w); ((v2u*)(hb_out + (size_t)(rb + i) * D) + lane)[64 * j] = o; s2 += (v.x * v.x + v.y * v.y) + (v.z * v.z + v.w * v.w); }
;         }
;         if (!FINAL) { const float tot = wave_sum(s2); if (lane == 0) rs_out[rb + i] = 1.0f / sqrtf(tot * (1.f / D) + EPS); }
	v_lshlrev_b32_e32 v242, 16, v208
	v_and_b32_e32 v243, 0xffff0000, v208
	v_pk_mul_f32 v[60:61], v[60:61], v[164:165] op_sel_hi:[1,0]
	v_pk_fma_f32 v[60:61], v[60:61], v[172:173], v[242:243]
	v_lshlrev_b32_e32 v244, 16, v209
	v_and_b32_e32 v245, 0xffff0000, v209
	v_pk_mul_f32 v[62:63], v[62:63], v[164:165] op_sel_hi:[1,0]
	v_pk_fma_f32 v[62:63], v[62:63], v[174:175], v[244:245]
	v_lshlrev_b32_e32 v242, 16, v210
	v_and_b32_e32 v243, 0xffff0000, v210
	v_pk_mul_f32 v[56:57], v[56:57], v[164:165] op_sel_hi:[1,0]
	v_pk_fma_f32 v[56:57], v[56:57], v[176:177], v[242:243]
	v_lshlrev_b32_e32 v244, 16, v211
	v_and_b32_e32 v245, 0xffff0000, v211
	v_pk_mul_f32 v[58:59], v[58:59], v[164:165] op_sel_hi:[1,0]
	v_pk_fma_f32 v[58:59], v[58:59], v[178:179], v[244:245]
	v_lshlrev_b32_e32 v242, 16, v212
	v_and_b32_e32 v243, 0xffff0000, v212
	v_pk_mul_f32 v[52:53], v[52:53], v[164:165] op_sel_hi:[1,0]
	v_pk_fma_f32 v[52:53], v[52:53], v[180:181], v[242:243]
	v_lshlrev_b32_e32 v244, 16, v213
	v_and_b32_e32 v245, 0xffff0000, v213
	v_pk_mul_f32 v[54:55], v[54:55], v[164:165] op_sel_hi:[1,0]
	v_pk_fma_f32 v[54:55], v[54:55], v[182:183], v[244:245]
	v_lshlrev_b32_e32 v242, 16, v214
	v_and_b32_e32 v243, 0xffff0000, v214
	v_pk_mul_f32 v[48:49], v[48:49], v[164:165] op_sel_hi:[1,0]
	v_pk_fma_f32 v[48:49], v[48:49], v[184:185], v[242:243]
	v_lshlrev_b32_e32 v244, 16, v215
	v_and_b32_e32 v245, 0xffff0000, v215
	v_pk_mul_f32 v[50:51], v[50:51], v[164:165] op_sel_hi:[1,0]
	v_pk_fma_f32 v[50:51], v[50:51], v[186:187], v[244:245]
	v_pk_mul_f32 v[242:243], v[60:61], v[60:61]
	v_pk_fma_f32 v[242:243], v[62:63], v[62:63], v[242:243]
	v_pk_fma_f32 v[242:243], v[56:57], v[56:57], v[242:243]
	v_pk_fma_f32 v[242:243], v[58:59], v[58:59], v[242:243]
	v_pk_fma_f32 v[242:243], v[52:53], v[52:53], v[242:243]
	v_pk_fma_f32 v[242:243], v[54:55], v[54:55], v[242:243]
	v_pk_fma_f32 v[242:243], v[48:49], v[48:49], v[242:243]
	v_pk_fma_f32 v[242:243], v[50:51], v[50:51], v[242:243]
	v_add_f32_e32 v165, v242, v243
	v_cvt_pk_bf16_f32 v208, v60, v61
	v_cvt_pk_bf16_f32 v209, v62, v63
	v_cvt_pk_bf16_f32 v210, v56, v57
	v_cvt_pk_bf16_f32 v211, v58, v59
	v_cvt_pk_bf16_f32 v212, v52, v53
	v_cvt_pk_bf16_f32 v213, v54, v55
	v_cvt_pk_bf16_f32 v214, v48, v49
	v_cvt_pk_bf16_f32 v215, v50, v51
	v_add_u32_e32 v244, 0x40000, v153
	s_nop 0
	global_store_dwordx4 v244, v[208:211], s[66:67]
	global_store_dwordx4 v244, v[212:215], s[66:67] offset:256
	s_waitcnt vmcnt(14)
	v_lshlrev_b32_e32 v242, 16, v216
	v_and_b32_e32 v243, 0xffff0000, v216
	v_pk_mul_f32 v[44:45], v[44:45], v[170:171] op_sel_hi:[1,0]
	v_pk_fma_f32 v[44:45], v[44:45], v[172:173], v[242:243]
	v_lshlrev_b32_e32 v244, 16, v217
	v_and_b32_e32 v245, 0xffff0000, v217
	v_pk_mul_f32 v[46:47], v[46:47], v[170:171] op_sel_hi:[1,0]
	v_pk_fma_f32 v[46:47], v[46:47], v[174:175], v[244:245]
	v_lshlrev_b32_e32 v242, 16, v218
	v_and_b32_e32 v243, 0xffff0000, v218
	v_pk_mul_f32 v[40:41], v[40:41], v[170:171] op_sel_hi:[1,0]
	v_pk_fma_f32 v[40:41], v[40:41], v[176:177], v[242:243]
	v_lshlrev_b32_e32 v244, 16, v219
	v_and_b32_e32 v245, 0xffff0000, v219
	v_pk_mul_f32 v[42:43], v[42:43], v[170:171] op_sel_hi:[1,0]
	v_pk_fma_f32 v[42:43], v[42:43], v[178:179], v[244:245]
	v_lshlrev_b32_e32 v242, 16, v220
	v_and_b32_e32 v243, 0xffff0000, v220
	v_pk_mul_f32 v[36:37], v[36:37], v[170:171] op_sel_hi:[1,0]
	v_pk_fma_f32 v[36:37], v[36:37], v[180:181], v[242:243]
	v_lshlrev_b32_e32 v244, 16, v221
	v_and_b32_e32 v245, 0xffff0000, v221
	v_pk_mul_f32 v[38:39], v[38:39], v[170:171] op_sel_hi:[1,0]
	v_pk_fma_f32 v[38:39], v[38:39], v[182:183], v[244:245]
	v_lshlrev_b32_e32 v242, 16, v222
	v_and_b32_e32 v243, 0xffff0000, v222
	v_pk_mul_f32 v[32:33], v[32:33], v[170:171] op_sel_hi:[1,0]
	v_pk_fma_f32 v[32:33], v[32:33], v[184:185], v[242:243]
	v_lshlrev_b32_e32 v244, 16, v223
	v_and_b32_e32 v245, 0xffff0000, v223
	v_pk_mul_f32 v[34:35], v[34:35], v[170:171] op_sel_hi:[1,0]
	v_pk_fma_f32 v[34:35], v[34:35], v[186:187], v[244:245]
	v_pk_mul_f32 v[242:243], v[44:45], v[44:45]
	v_pk_fma_f32 v[242:243], v[46:47], v[46:47], v[242:243]
	v_pk_fma_f32 v[242:243], v[40:41], v[40:41], v[242:243]
	v_pk_fma_f32 v[242:243], v[42:43], v[42:43], v[242:243]
	v_pk_fma_f32 v[242:243], v[36:37], v[36:37], v[242:243]
	v_pk_fma_f32 v[242:243], v[38:39], v[38:39], v[242:243]
	v_pk_fma_f32 v[242:243], v[32:33], v[32:33], v[242:243]
	v_pk_fma_f32 v[242:243], v[34:35], v[34:35], v[242:243]
	v_add_f32_e32 v171, v242, v243
	v_cvt_pk_bf16_f32 v216, v44, v45
	v_cvt_pk_bf16_f32 v217, v46, v47
	v_cvt_pk_bf16_f32 v218, v40, v41
	v_cvt_pk_bf16_f32 v219, v42, v43
	v_cvt_pk_bf16_f32 v220, v36, v37
	v_cvt_pk_bf16_f32 v221, v38, v39
	v_cvt_pk_bf16_f32 v222, v32, v33
	v_cvt_pk_bf16_f32 v223, v34, v35
	v_add_u32_e32 v244, 0x48000, v153
	s_nop 0
	global_store_dwordx4 v244, v[216:219], s[66:67]
	global_store_dwordx4 v244, v[220:223], s[66:67] offset:256
	s_waitcnt vmcnt(10)
; __device__ __forceinline__ float bf_lo(unsigned w) { return __uint_as_float(w << 16); }
; __device__ __forceinline__ float bf_hi(unsigned w) { return __uint_as_float(w & 0xffff0000u); }
; __device__ __forceinline__ unsigned pk2(float lo, float hi) { bf16x2_t r = __builtin_convertvector((f32x2_t){lo, hi}, bf16x2_t); return __builtin_bit_cast(unsigned, r); }
;     __device__ __forceinline__ void operator()(const pg8::f32x4 (&acc)[2][2][4][2], const pg8::Unit& u, int wr, int wc, int fr, int fq) const {
;     ...
;                     if (PART) {
; #pragma unroll
;                         for (int j = 0; j < 8; ++j) s += r[j] * r[j];
;                     }
;                     v4u w; w.x = pk2(r[0], r[1]); w.y = pk2(r[2], r[3]); w.z = pk2(r[4], r[5]); w.w = pk2(r[6], r[7]);
;                     st16_wt(O + off + bj * 128, w);
;                 }
;                 if (PART) { s += __shfl_xor(s, 16); s += __shfl_xor(s, 32); st4_wt(part + (size_t)row * 16 + u.pn * 4 + wc, s); }
; template <bool SRC_F32, bool FINAL, int R> __device__ __forceinline__ void ew_compute(const EwSet<SRC_F32, R>& S, int rb, const f32x4 (&g)[4], bf16* hb_out, float* out32, float scale, float* rs_out, int lane) {
;     ...
; #pragma unroll
;         for (int j = 0; j < 4; ++j) {
;             f32x4 h;
;             if constexpr (SRC_F32) h = S.h32[i][j];
;             else { const v2u hw = S.hb[i][j]; h.x = bf_lo(hw.x); h.y = bf_hi(hw.x); h.z = bf_lo(hw.y); h.w = bf_hi(hw.y); }
;             const v2u fw = S.fw[i][j];
;             f32x4 v; v.x = h.x + bf_lo(fw.x) * rs * g[j].x; v.y = h.y + bf_hi(fw.x) * rs * g[j].y; v.z = h.z + bf_lo(fw.y) * rs * g[j].z; v.w = h.w + bf_hi(fw.y) * rs * g[j].w;
;             if (FINAL) __builtin_nontemporal_store(v, (f32x4*)(out32 + (size_t)(rb + i) * D) + lane + 64 * j);
;             else { v2u o; o.x = pk2(v.x, v.y); o.y = pk2(v.z, v.w); ((v2u*)(hb_out + (size_t)(rb + i) * D) + lane)[64 * j] = o; s2 += (v.x * v.x + v.y * v.y) + (v.z * v.z + v.w * v.w); }
;         }
;         if (!FINAL) { const float tot = wave_sum(s2); if (lane == 0) rs_out[rb + i] = 1.0f / sqrtf(tot * (1.f / D) + EPS); }
	v_lshlrev_b32_e32 v242, 16, v224
	v_and_b32_e32 v243, 0xffff0000, v224
	v_pk_mul_f32 v[28:29], v[28:29], v[192:193] op_sel_hi:[1,0]
	v_pk_fma_f32 v[28:29], v[28:29], v[172:173], v[242:243]
	v_lshlrev_b32_e32 v244, 16, v225
	v_and_b32_e32 v245, 0xffff0000, v225
	v_pk_mul_f32 v[30:31], v[30:31], v[192:193] op_sel_hi:[1,0]
	v_pk_fma_f32 v[30:31], v[30:31], v[174:175], v[244:245]
	v_lshlrev_b32_e32 v242, 16, v226
	v_and_b32_e32 v243, 0xffff0000, v226
	v_pk_mul_f32 v[24:25], v[24:25], v[192:193] op_sel_hi:[1,0]
	v_pk_fma_f32 v[24:25], v[24:25], v[176:177], v[242:243]
	v_lshlrev_b32_e32 v244, 16, v227
	v_and_b32_e32 v245, 0xffff0000, v227
	v_pk_mul_f32 v[26:27], v[26:27], v[192:193] op_sel_hi:[1,0]
	v_pk_fma_f32 v[26:27], v[26:27], v[178:179], v[244:245]
	v_lshlrev_b32_e32 v242, 16, v228
	v_and_b32_e32 v243, 0xffff0000, v228
	v_pk_mul_f32 v[20:21], v[20:21], v[192:193] op_sel_hi:[1,0]
	v_pk_fma_f32 v[20:21], v[20:21], v[180:181], v[242:243]
	v_lshlrev_b32_e32 v244, 16, v229
	v_and_b32_e32 v245, 0xffff0000, v229
	v_pk_mul_f32 v[22:23], v[22:23], v[192:193] op_sel_hi:[1,0]
	v_pk_fma_f32 v[22:23], v[22:23], v[182:183], v[244:245]
	v_lshlrev_b32_e32 v242, 16, v230
	v_and_b32_e32 v243, 0xffff0000, v230
	v_pk_mul_f32 v[16:17], v[16:17], v[192:193] op_sel_hi:[1,0]
	v_pk_fma_f32 v[16:17], v[16:17], v[184:185], v[242:243]
	v_lshlrev_b32_e32 v244, 16, v231
	v_and_b32_e32 v245, 0xffff0000, v231
	v_pk_mul_f32 v[18:19], v[18:19], v[192:193] op_sel_hi:[1,0]
	v_pk_fma_f32 v[18:19], v[18:19], v[186:187], v[244:245]
	v_pk_mul_f32 v[242:243], v[28:29], v[28:29]
	v_pk_fma_f32 v[242:243], v[30:31], v[30:31], v[242:243]
	v_pk_fma_f32 v[242:243], v[24:25], v[24:25], v[242:243]
	v_pk_fma_f32 v[242:243], v[26:27], v[26:27], v[242:243]
	v_pk_fma_f32 v[242:243], v[20:21], v[20:21], v[242:243]
	v_pk_fma_f32 v[242:243], v[22:23], v[22:23], v[242:243]
	v_pk_fma_f32 v[242:243], v[16:17], v[16:17], v[242:243]
	v_pk_fma_f32 v[242:243], v[18:19], v[18:19], v[242:243]
	v_add_f32_e32 v193, v242, v243
	v_cvt_pk_bf16_f32 v224, v28, v29
	v_cvt_pk_bf16_f32 v225, v30, v31
	v_cvt_pk_bf16_f32 v226, v24, v25
	v_cvt_pk_bf16_f32 v227, v26, v27
	v_cvt_pk_bf16_f32 v228, v20, v21
	v_cvt_pk_bf16_f32 v229, v22, v23
	v_cvt_pk_bf16_f32 v230, v16, v17
	v_cvt_pk_bf16_f32 v231, v18, v19
	v_add_u32_e32 v244, 0x50000, v153
	s_nop 0
	global_store_dwordx4 v244, v[224:227], s[66:67]
	global_store_dwordx4 v244, v[228:231], s[66:67] offset:256
	s_waitcnt vmcnt(10)
	v_lshlrev_b32_e32 v242, 16, v232
	v_and_b32_e32 v243, 0xffff0000, v232
	v_pk_mul_f32 v[12:13], v[12:13], v[240:241] op_sel_hi:[1,0]
	v_pk_fma_f32 v[12:13], v[12:13], v[172:173], v[242:243]
	v_lshlrev_b32_e32 v244, 16, v233
	v_and_b32_e32 v245, 0xffff0000, v233
	v_pk_mul_f32 v[14:15], v[14:15], v[240:241] op_sel_hi:[1,0]
	v_pk_fma_f32 v[14:15], v[14:15], v[174:175], v[244:245]
	v_lshlrev_b32_e32 v242, 16, v234
	v_and_b32_e32 v243, 0xffff0000, v234
	v_pk_mul_f32 v[8:9], v[8:9], v[240:241] op_sel_hi:[1,0]
	v_pk_fma_f32 v[8:9], v[8:9], v[176:177], v[242:243]
	v_lshlrev_b32_e32 v244, 16, v235
	v_and_b32_e32 v245, 0xffff0000, v235
	v_pk_mul_f32 v[10:11], v[10:11], v[240:241] op_sel_hi:[1,0]
	v_pk_fma_f32 v[10:11], v[10:11], v[178:179], v[244:245]
	v_lshlrev_b32_e32 v242, 16, v236
	v_and_b32_e32 v243, 0xffff0000, v236
	v_pk_mul_f32 v[4:5], v[4:5], v[240:241] op_sel_hi:[1,0]
	v_pk_fma_f32 v[4:5], v[4:5], v[180:181], v[242:243]
	v_lshlrev_b32_e32 v244, 16, v237
	v_and_b32_e32 v245, 0xffff0000, v237
	v_pk_mul_f32 v[6:7], v[6:7], v[240:241] op_sel_hi:[1,0]
	v_pk_fma_f32 v[6:7], v[6:7], v[182:183], v[244:245]
	v_lshlrev_b32_e32 v242, 16, v238
	v_and_b32_e32 v243, 0xffff0000, v238
	v_pk_mul_f32 v[0:1], v[0:1], v[240:241] op_sel_hi:[1,0]
	v_pk_fma_f32 v[0:1], v[0:1], v[184:185], v[242:243]
	v_lshlrev_b32_e32 v244, 16, v239
	v_and_b32_e32 v245, 0xffff0000, v239
	v_pk_mul_f32 v[2:3], v[2:3], v[240:241] op_sel_hi:[1,0]
	v_pk_fma_f32 v[2:3], v[2:3], v[186:187], v[244:245]
	v_pk_mul_f32 v[242:243], v[12:13], v[12:13]
	v_pk_fma_f32 v[242:243], v[14:15], v[14:15], v[242:243]
	v_pk_fma_f32 v[242:243], v[8:9], v[8:9], v[242:243]
	v_pk_fma_f32 v[242:243], v[10:11], v[10:11], v[242:243]
	v_pk_fma_f32 v[242:243], v[4:5], v[4:5], v[242:243]
	v_pk_fma_f32 v[242:243], v[6:7], v[6:7], v[242:243]
	v_pk_fma_f32 v[242:243], v[0:1], v[0:1], v[242:243]
	v_pk_fma_f32 v[242:243], v[2:3], v[2:3], v[242:243]
	v_add_f32_e32 v241, v242, v243
	v_cvt_pk_bf16_f32 v232, v12, v13
	v_cvt_pk_bf16_f32 v233, v14, v15
	v_cvt_pk_bf16_f32 v234, v8, v9
	v_cvt_pk_bf16_f32 v235, v10, v11
	v_cvt_pk_bf16_f32 v236, v4, v5
	v_cvt_pk_bf16_f32 v237, v6, v7
	v_cvt_pk_bf16_f32 v238, v0, v1
	v_cvt_pk_bf16_f32 v239, v2, v3
	v_add_u32_e32 v244, 0x58000, v153
	s_nop 0
	global_store_dwordx4 v244, v[232:235], s[66:67]
	global_store_dwordx4 v244, v[236:239], s[66:67] offset:256
	s_nop 1
	ds_bpermute_b32 v172, v166, v145
	ds_bpermute_b32 v173, v166, v155
	ds_bpermute_b32 v174, v166, v159
	ds_bpermute_b32 v175, v166, v163
	ds_bpermute_b32 v176, v166, v165
	ds_bpermute_b32 v177, v166, v171
	ds_bpermute_b32 v178, v166, v193
	ds_bpermute_b32 v179, v166, v241
	s_waitcnt lgkmcnt(0)
	v_add_f32_e32 v145, v145, v172
	v_add_f32_e32 v155, v155, v173
	v_add_f32_e32 v159, v159, v174
	v_add_f32_e32 v163, v163, v175
	v_add_f32_e32 v165, v165, v176
	v_add_f32_e32 v171, v171, v177
	v_add_f32_e32 v193, v193, v178
	v_add_f32_e32 v241, v241, v179
	s_nop 1
	ds_bpermute_b32 v172, v168, v145
	ds_bpermute_b32 v173, v168, v155
	ds_bpermute_b32 v174, v168, v159
	ds_bpermute_b32 v175, v168, v163
	ds_bpermute_b32 v176, v168, v165
	ds_bpermute_b32 v177, v168, v171
	ds_bpermute_b32 v178, v168, v193
	ds_bpermute_b32 v179, v168, v241
	s_waitcnt lgkmcnt(0)
	v_add_f32_e32 v145, v145, v172
	v_add_f32_e32 v155, v155, v173
	v_add_f32_e32 v159, v159, v174
	v_add_f32_e32 v163, v163, v175
	v_add_f32_e32 v165, v165, v176
	v_add_f32_e32 v171, v171, v177
	v_add_f32_e32 v193, v193, v178
	v_add_f32_e32 v241, v241, v179
	global_store_dword v157, v145, s[78:79]
	v_add_u32_e32 v173, 0x400, v157
	global_store_dword v173, v155, s[78:79]
	v_add_u32_e32 v174, 0x800, v157
	global_store_dword v174, v159, s[78:79]
	v_add_u32_e32 v175, 0xc00, v157
	global_store_dword v175, v163, s[78:79]
	v_add_u32_e32 v176, 0x2000, v157
	global_store_dword v176, v165, s[78:79]
	v_add_u32_e32 v177, 0x2400, v157
	global_store_dword v177, v171, s[78:79]
	v_add_u32_e32 v178, 0x2800, v157
	global_store_dword v178, v193, s[78:79]
	v_add_u32_e32 v179, 0x2c00, v157
	global_store_dword v179, v241, s[78:79]
	s_andn2_b64 vcc, exec, s[0:1]
	s_mov_b64 s[0:1], -1
	s_cbranch_vccnz .LBB0_878
	s_andn2_b64 vcc, exec, s[8:9]
	s_cbranch_vccnz .LBB0_877
	s_barrier
	s_branch .LBB0_877

; #define SEAM(k) do { if (IN(k) && IN((k) + 1)) { xcd_barrier(xbar); } } while (0)
; __global__ void __launch_bounds__(NWAVES * 64, 2) mk_fwd(Args a) {
;     ...
;     SEAM(7);
;     if (IN(8)) ew_phase<false, false>(nullptr, HB, HB, nullptr, S3, PART, a.in[I_MIXPOST], 1.0f, RS, gw, NGW, lane);
;     SEAM(8);
.LBB0_893:
	s_cmp_gt_i32 s31, 8
	s_cselect_b64 s[0:1], -1, 0
	s_and_b64 s[4:5], s[4:5], s[0:1]
	s_andn2_b64 vcc, exec, s[4:5]
	s_cbranch_vccnz .LBB0_943
.LBB0_943:
	s_cmp_lt_i32 s30, 9
	s_cselect_b64 s[4:5], -1, 0
	s_and_b64 s[8:9], s[4:5], s[0:1]
	s_andn2_b64 vcc, exec, s[8:9]
	s_cbranch_vccnz .LBB0_989
.LBB0_989:
	s_cmp_gt_i32 s31, 9
	s_cselect_b64 s[0:1], -1, 0
	s_and_b64 s[4:5], s[8:9], s[0:1]
	s_andn2_b64 vcc, exec, s[4:5]
	s_cbranch_vccnz .LBB0_1039
	s_waitcnt vmcnt(0)
	s_barrier
	v_cmp_eq_u32_e32 vcc, 0, v195
	s_and_saveexec_b64 s[4:5], vcc
	s_cbranch_execz .Ltb1039_done
	s_and_b32 s3, s2, 7
	s_lshl_b32 s3, s3, 3
	s_bfe_u32 s13, s2, 0x30003
	s_or_b32 s3, s3, s13
	s_lshl_b32 s3, s3, 5
	s_add_u32 s8, s28, 0x3903600
	s_addc_u32 s9, s29, 0
	v_mov_b32_e32 v0, s3
	v_mov_b32_e32 v1, 1
	v_mov_b32_e32 v2, 24
	s_mov_b32 s15, 0
	s_cmp_eq_u32 s99, 1
	s_cbranch_scc1 .Ltb1039_fast
	buffer_wbl2 sc1
	s_waitcnt vmcnt(0)
	global_atomic_add v0, v1, s[8:9]

; #define SEAM(k) do { if (IN(k) && IN((k) + 1)) { xcd_barrier(xbar); } } while (0)
; __global__ void __launch_bounds__(NWAVES * 64, 2) mk_fwd(Args a) {
;     ...
;     SEAM(8);
.Ltb1039_sgs:
	global_load_dword v5, v4, s[8:9] sc1
	s_waitcnt vmcnt(0)
	v_cmp_gt_u32_e32 vcc, 24, v5
	s_cmp_lg_u64 vcc, 0
	s_cbranch_scc0 .Ltb1039_sgd
	s_sleep 1
	s_add_u32 s15, s15, 1
	s_cmp_lt_u32 s15, 0x400000
	s_cbranch_scc1 .Ltb1039_sgs

; #define LAS __attribute__((address_space(3)))
; __device__ __forceinline__ void rs_table_fill(LAS unsigned char* lds, const pg8::StaticOrder& S, const float* rs) {
;     int k0 = -1, k1 = -1, k2 = -1, k3 = -1;
;     for (int i = 0;; ++i) { pg8::Unit u; if (!S.next(i, u)) break; const int pm = u.pm;
;         if (pm != k0 && pm != k1 && pm != k2 && pm != k3) { if (k0 < 0) k0 = pm; else if (k1 < 0) k1 = pm; else if (k2 < 0) k2 = pm; else if (k3 < 0) k3 = pm; } }
;     const int tid = threadIdx.x;
;     LAS float* tab = (LAS float*)(lds + RS_TAB_OFF); LAS int* keys = (LAS int*)(lds + RS_KEY_OFF);
;     if (tid < 256) {
;         if (k0 >= 0) tab[tid] = rs[k0 * 256 + tid];
;         if (k1 >= 0) tab[256 + tid] = rs[k1 * 256 + tid];
;         if (k2 >= 0) tab[512 + tid] = rs[k2 * 256 + tid];
;         if (k3 >= 0) tab[768 + tid] = rs[k3 * 256 + tid];
;     }
;     if (tid == 0) { keys[0] = k0; keys[1] = k1; keys[2] = k2; keys[3] = k3; }
;     __syncthreads();
; template <bool SRC_F32, bool FINAL, int R> __device__ __forceinline__ void ew_compute(const EwSet<SRC_F32, R>& S, int rb, const f32x4 (&g)[4], bf16* hb_out, float* out32, float scale, float* rs_out, int lane) {
;     ...
;         if (!FINAL) { const float tot = wave_sum(s2); if (lane == 0) rs_out[rb + i] = 1.0f / sqrtf(tot * (1.f / D) + EPS); }
.LBB0_1051:
	s_movk_i32 s0, 0x100
	v_cmp_gt_u32_e32 vcc, s0, v195
	s_and_saveexec_b64 s[0:1], vcc
	s_cbranch_execz .LBB0_1060
	s_cmp_lt_i32 s10, 0
	s_cbranch_scc1 .LBB0_1054
	v_lshl_or_b32 v0, s10, 8, v195
	v_mov_b32_e32 v1, 0
	s_add_u32 s80, s28, 0x4c00000
	s_addc_u32 s81, s29, 0
	v_lshlrev_b32_e32 v2, 6, v0
	v_lshlrev_b32_e32 v3, 2, v0
	global_load_dwordx4 v[4:7], v2, s[80:81]
	global_load_dwordx4 v[8:11], v2, s[80:81] offset:16
	global_load_dwordx4 v[12:15], v2, s[80:81] offset:32
	global_load_dwordx4 v[16:19], v2, s[80:81] offset:48
	v_lshl_add_u32 v1, v195, 2, 0
	v_add_u32_e32 v1, 0x20000, v1
	s_waitcnt vmcnt(0)
	v_add_f32_e32 v0, v4, v5
	v_add_f32_e32 v0, v6, v0
	v_add_f32_e32 v0, v7, v0
	v_add_f32_e32 v0, v8, v0
	v_add_f32_e32 v0, v9, v0
	v_add_f32_e32 v0, v10, v0
	v_add_f32_e32 v0, v11, v0
	v_add_f32_e32 v0, v12, v0
	v_add_f32_e32 v0, v13, v0
	v_add_f32_e32 v0, v14, v0
	v_add_f32_e32 v0, v15, v0
	v_add_f32_e32 v0, v16, v0
	v_add_f32_e32 v0, v17, v0
	v_add_f32_e32 v0, v18, v0
	v_add_f32_e32 v0, v19, v0
	v_mul_f32_e32 v0, 0x3a800000, v0
	v_add_f32_e32 v0, 0x358637bd, v0
	v_rsq_f32_e32 v0, v0
	s_nop 0
	global_store_dword v3, v0, s[92:93]
	ds_write_b32 v1, v0
.LBB0_1054:
	s_cmp_lt_i32 s11, 0
	s_cbranch_scc1 .LBB0_1056
	v_lshl_or_b32 v0, s11, 8, v195
	v_mov_b32_e32 v1, 0
	v_lshlrev_b32_e32 v2, 6, v0
	v_lshlrev_b32_e32 v3, 2, v0
	global_load_dwordx4 v[4:7], v2, s[80:81]
	global_load_dwordx4 v[8:11], v2, s[80:81] offset:16
	global_load_dwordx4 v[12:15], v2, s[80:81] offset:32
	global_load_dwordx4 v[16:19], v2, s[80:81] offset:48
	s_add_i32 s4, 0, 0x20000
	v_lshl_add_u32 v1, v195, 2, s4
	s_waitcnt vmcnt(0)
	v_add_f32_e32 v0, v4, v5
	v_add_f32_e32 v0, v6, v0
	v_add_f32_e32 v0, v7, v0
	v_add_f32_e32 v0, v8, v0
	v_add_f32_e32 v0, v9, v0
	v_add_f32_e32 v0, v10, v0
	v_add_f32_e32 v0, v11, v0
	v_add_f32_e32 v0, v12, v0
	v_add_f32_e32 v0, v13, v0
	v_add_f32_e32 v0, v14, v0
	v_add_f32_e32 v0, v15, v0
	v_add_f32_e32 v0, v16, v0
	v_add_f32_e32 v0, v17, v0
	v_add_f32_e32 v0, v18, v0
	v_add_f32_e32 v0, v19, v0
	v_mul_f32_e32 v0, 0x3a800000, v0
	v_add_f32_e32 v0, 0x358637bd, v0
	v_rsq_f32_e32 v0, v0
	s_nop 0
	global_store_dword v3, v0, s[92:93]
	ds_write_b32 v1, v0 offset:1024
.LBB0_1056:
	s_cmp_lt_i32 s22, 0
	s_cbranch_scc1 .LBB0_1058
	v_lshl_or_b32 v0, s22, 8, v195
	v_mov_b32_e32 v1, 0
	v_lshlrev_b32_e32 v2, 6, v0
	v_lshlrev_b32_e32 v3, 2, v0
	global_load_dwordx4 v[4:7], v2, s[80:81]
	global_load_dwordx4 v[8:11], v2, s[80:81] offset:16
	global_load_dwordx4 v[12:15], v2, s[80:81] offset:32
	global_load_dwordx4 v[16:19], v2, s[80:81] offset:48
	s_add_i32 s4, 0, 0x20000
	v_lshl_add_u32 v1, v195, 2, s4
	s_waitcnt vmcnt(0)
	v_add_f32_e32 v0, v4, v5
	v_add_f32_e32 v0, v6, v0
	v_add_f32_e32 v0, v7, v0
	v_add_f32_e32 v0, v8, v0
	v_add_f32_e32 v0, v9, v0
	v_add_f32_e32 v0, v10, v0
	v_add_f32_e32 v0, v11, v0
	v_add_f32_e32 v0, v12, v0
	v_add_f32_e32 v0, v13, v0
	v_add_f32_e32 v0, v14, v0
	v_add_f32_e32 v0, v15, v0
	v_add_f32_e32 v0, v16, v0
	v_add_f32_e32 v0, v17, v0
	v_add_f32_e32 v0, v18, v0
	v_add_f32_e32 v0, v19, v0
	v_mul_f32_e32 v0, 0x3a800000, v0
	v_add_f32_e32 v0, 0x358637bd, v0
	v_rsq_f32_e32 v0, v0
	s_nop 0
	global_store_dword v3, v0, s[92:93]
	ds_write_b32 v1, v0 offset:2048
.LBB0_1058:
	s_cmp_lt_i32 s8, 0
	s_cbranch_scc1 .LBB0_1060
	v_lshl_or_b32 v0, s8, 8, v195
	v_mov_b32_e32 v1, 0
	v_lshlrev_b32_e32 v2, 6, v0
	v_lshlrev_b32_e32 v3, 2, v0
	global_load_dwordx4 v[4:7], v2, s[80:81]
	global_load_dwordx4 v[8:11], v2, s[80:81] offset:16
	global_load_dwordx4 v[12:15], v2, s[80:81] offset:32
	global_load_dwordx4 v[16:19], v2, s[80:81] offset:48
	s_add_i32 s4, 0, 0x20000
	v_lshl_add_u32 v1, v195, 2, s4
	s_waitcnt vmcnt(0)
	v_add_f32_e32 v0, v4, v5
	v_add_f32_e32 v0, v6, v0
	v_add_f32_e32 v0, v7, v0
	v_add_f32_e32 v0, v8, v0
	v_add_f32_e32 v0, v9, v0
	v_add_f32_e32 v0, v10, v0
	v_add_f32_e32 v0, v11, v0
	v_add_f32_e32 v0, v12, v0
	v_add_f32_e32 v0, v13, v0
	v_add_f32_e32 v0, v14, v0
	v_add_f32_e32 v0, v15, v0
	v_add_f32_e32 v0, v16, v0
	v_add_f32_e32 v0, v17, v0
	v_add_f32_e32 v0, v18, v0
	v_add_f32_e32 v0, v19, v0
	v_mul_f32_e32 v0, 0x3a800000, v0
	v_add_f32_e32 v0, 0x358637bd, v0
	v_rsq_f32_e32 v0, v0
	s_nop 0
	global_store_dword v3, v0, s[92:93]
	ds_write_b32 v1, v0 offset:3072

; __device__ __forceinline__ unsigned xb_ld(unsigned* p)              { return __hip_atomic_load(p, __ATOMIC_RELAXED, __HIP_MEMORY_SCOPE_AGENT); }
; __device__ __forceinline__ unsigned xb_add(unsigned* p, unsigned v) { return __hip_atomic_fetch_add(p, v, __ATOMIC_RELAXED, __HIP_MEMORY_SCOPE_AGENT); }
; #define XB_SPIN(cond, bar) do { unsigned _sp = 0; while (cond) { __builtin_amdgcn_s_sleep(1); \
;     if ((++_sp & 255u) == 0u) { if (xb_ld(&(bar)[XB_TMO])) break; if (_sp > XB_SPIN_CAP) { atomicAdd(&(bar)[XB_TMO], 1u); break; } } } } while (0)
; __device__ __forceinline__ void xcd_barrier(const XcdBarrier& b) {
;     asm volatile("s_waitcnt vmcnt(0)" ::: "memory");
;     __syncthreads();
;     if (threadIdx.x == 0) {
;         unsigned* bar = b.bar;
;         __builtin_amdgcn_s_waitcnt(0);
;         unsigned nloc = b.st[0], nx = b.st[1];
;         if (nloc == 0u) { xcd_barrier_complete(bar, b.x, nloc, nx); b.st[0] = nloc; b.st[1] = nx; }
;         const unsigned old = xb_add(&bar[XB_XSUB(b.x)], 1u);
;         const unsigned gen = old / nloc;
;         if (old + 1u == (gen + 1u) * nloc) {
;             __builtin_amdgcn_fence(__ATOMIC_RELEASE, "agent");
;             asm volatile("s_waitcnt vmcnt(0)" ::: "memory");
;             const unsigned og = xb_add(&bar[XB_TOP], 1u);
;             const unsigned tg = og / nx;
;             if (og + 1u == (tg + 1u) * nx) xb_add(&bar[XB_TOPGEN], 1u);
;             else XB_SPIN(xb_ld(&bar[XB_TOPGEN]) == tg, bar);
;             __builtin_amdgcn_fence(__ATOMIC_ACQUIRE, "agent");
;             xb_add(&bar[XB_XGEN(b.x)], 1u);
;             asm volatile("s_waitcnt vmcnt(0)" ::: "memory");
;         } else {
;             XB_SPIN(xb_ld(&bar[XB_XGEN(b.x)]) == gen, bar);
;             __builtin_amdgcn_fence(__ATOMIC_ACQUIRE, "agent");
;             asm volatile("s_waitcnt vmcnt(0)" ::: "memory");
;         }
;     }
;     __syncthreads();
; }
.LBB0_1084:
	s_cmp_gt_i32 s31, 10
	s_cselect_b64 s[0:1], -1, 0
	s_and_b64 s[4:5], s[6:7], s[0:1]
	s_andn2_b64 vcc, exec, s[4:5]
	s_cbranch_vccnz .LBB0_1134
	s_waitcnt vmcnt(0)
	s_barrier
	v_cmp_eq_u32_e32 vcc, 0, v195
	s_and_saveexec_b64 s[4:5], vcc
	s_cbranch_execz .Ltb1134_done
	s_and_b32 s3, s2, 7
	s_lshl_b32 s3, s3, 3
	s_bfe_u32 s13, s2, 0x30003
	s_or_b32 s3, s3, s13
	s_lshl_b32 s3, s3, 5
	s_add_u32 s8, s28, 0x3903600
	s_addc_u32 s9, s29, 0
	v_mov_b32_e32 v0, s3
	v_mov_b32_e32 v1, 1
	v_mov_b32_e32 v2, 28
	s_mov_b32 s15, 0
	s_cmp_eq_u32 s99, 1
	s_cbranch_scc1 .Ltb1134_fast
	buffer_wbl2 sc1
	s_waitcnt vmcnt(0)
	global_atomic_add v0, v1, s[8:9]

; __device__ __forceinline__ unsigned pk2(float lo, float hi) { bf16x2_t r = __builtin_convertvector((f32x2_t){lo, hi}, bf16x2_t); return __builtin_bit_cast(unsigned, r); }
; __device__ __forceinline__ unsigned xb_ld(unsigned* p)              { return __hip_atomic_load(p, __ATOMIC_RELAXED, __HIP_MEMORY_SCOPE_AGENT); }
;     __device__ __forceinline__ void operator()(const pg8::f32x4 (&acc)[2][2][4][2], const pg8::Unit& u, int wr, int wc, int fr, int fq) const {
;     ...
;                     if (PART) {
; #pragma unroll
;                         for (int j = 0; j < 8; ++j) s += r[j] * r[j];
;                     }
;                     v4u w; w.x = pk2(r[0], r[1]); w.y = pk2(r[2], r[3]); w.z = pk2(r[4], r[5]); w.w = pk2(r[6], r[7]);
;                     st16_wt(O + off + bj * 128, w);
;                 }
;                 if (PART) { s += __shfl_xor(s, 16); s += __shfl_xor(s, 32); st4_wt(part + (size_t)row * 16 + u.pn * 4 + wc, s); }
; __device__ __forceinline__ void xcd_barrier(const XcdBarrier& b) {
;     asm volatile("s_waitcnt vmcnt(0)" ::: "memory");
;     __syncthreads();
;     if (threadIdx.x == 0) {
;         unsigned* bar = b.bar;
;         __builtin_amdgcn_s_waitcnt(0);
;         unsigned nloc = b.st[0], nx = b.st[1];
;         if (nloc == 0u) { xcd_barrier_complete(bar, b.x, nloc, nx); b.st[0] = nloc; b.st[1] = nx; }
;         const unsigned old = xb_add(&bar[XB_XSUB(b.x)], 1u);
;         const unsigned gen = old / nloc;
;         if (old + 1u == (gen + 1u) * nloc) {
;             __builtin_amdgcn_fence(__ATOMIC_RELEASE, "agent");
;             asm volatile("s_waitcnt vmcnt(0)" ::: "memory");
;             const unsigned og = xb_add(&bar[XB_TOP], 1u);
;             const unsigned tg = og / nx;
;             if (og + 1u == (tg + 1u) * nx) xb_add(&bar[XB_TOPGEN], 1u);
;             else XB_SPIN(xb_ld(&bar[XB_TOPGEN]) == tg, bar);
;             __builtin_amdgcn_fence(__ATOMIC_ACQUIRE, "agent");
;             xb_add(&bar[XB_XGEN(b.x)], 1u);
;             asm volatile("s_waitcnt vmcnt(0)" ::: "memory");
;         } else {
;             XB_SPIN(xb_ld(&bar[XB_XGEN(b.x)]) == gen, bar);
;             __builtin_amdgcn_fence(__ATOMIC_ACQUIRE, "agent");
;             asm volatile("s_waitcnt vmcnt(0)" ::: "memory");
;         }
;     }
;     __syncthreads();
; }
.LBB0_1159:
	s_waitcnt lgkmcnt(0)
	v_lshl_or_b32 v238, s52, 8, v148
	v_lshl_add_u32 v239, s51, 8, v146
	v_lshlrev_b32_e32 v243, 2, v238
	v_lshlrev_b32_e32 v153, 1, v238
	v_lshl_add_u32 v153, v239, 11, v153
	v_xor_b32_e32 v194, 16, v152
	v_lshlrev_b32_e32 v194, 2, v194
	v_xor_b32_e32 v242, 32, v152
	v_lshlrev_b32_e32 v242, 2, v242
	v_lshrrev_b32_e32 v168, 4, v152
	v_and_b32_e32 v168, 3, v168
	v_lshlrev_b32_e32 v168, 4, v168
	v_lshl_add_u32 v168, v239, 6, v168
	s_lshl_b32 s95, s52, 4
	s_add_u32 s95, s95, s8
	v_lshl_add_u32 v166, v239, 6, s95
	v_pk_mul_f32 v[238:239], v[124:125], v[124:125]
	v_pk_fma_f32 v[238:239], v[126:127], v[126:127], v[238:239]
	v_pk_fma_f32 v[238:239], v[120:121], v[120:121], v[238:239]
	v_pk_fma_f32 v[238:239], v[122:123], v[122:123], v[238:239]
	v_pk_fma_f32 v[238:239], v[116:117], v[116:117], v[238:239]
	v_pk_fma_f32 v[238:239], v[118:119], v[118:119], v[238:239]
	v_pk_fma_f32 v[238:239], v[112:113], v[112:113], v[238:239]
	v_pk_fma_f32 v[238:239], v[114:115], v[114:115], v[238:239]
	v_add_f32_e32 v145, v238, v239
	v_pk_mul_f32 v[240:241], v[108:109], v[108:109]
	v_pk_fma_f32 v[240:241], v[110:111], v[110:111], v[240:241]
	v_pk_fma_f32 v[240:241], v[104:105], v[104:105], v[240:241]
	v_pk_fma_f32 v[240:241], v[106:107], v[106:107], v[240:241]
	v_pk_fma_f32 v[240:241], v[100:101], v[100:101], v[240:241]
	v_pk_fma_f32 v[240:241], v[102:103], v[102:103], v[240:241]
	v_pk_fma_f32 v[240:241], v[96:97], v[96:97], v[240:241]
	v_pk_fma_f32 v[240:241], v[98:99], v[98:99], v[240:241]
	v_add_f32_e32 v155, v240, v241
	v_pk_mul_f32 v[238:239], v[92:93], v[92:93]
	v_pk_fma_f32 v[238:239], v[94:95], v[94:95], v[238:239]
	v_pk_fma_f32 v[238:239], v[88:89], v[88:89], v[238:239]
	v_pk_fma_f32 v[238:239], v[90:91], v[90:91], v[238:239]
	v_pk_fma_f32 v[238:239], v[84:85], v[84:85], v[238:239]
	v_pk_fma_f32 v[238:239], v[86:87], v[86:87], v[238:239]
	v_pk_fma_f32 v[238:239], v[80:81], v[80:81], v[238:239]
	v_pk_fma_f32 v[238:239], v[82:83], v[82:83], v[238:239]
	v_add_f32_e32 v165, v238, v239
	v_pk_mul_f32 v[240:241], v[76:77], v[76:77]
	v_pk_fma_f32 v[240:241], v[78:79], v[78:79], v[240:241]
	v_pk_fma_f32 v[240:241], v[72:73], v[72:73], v[240:241]
	v_pk_fma_f32 v[240:241], v[74:75], v[74:75], v[240:241]
	v_pk_fma_f32 v[240:241], v[68:69], v[68:69], v[240:241]
	v_pk_fma_f32 v[240:241], v[70:71], v[70:71], v[240:241]
	v_pk_fma_f32 v[240:241], v[64:65], v[64:65], v[240:241]
	v_pk_fma_f32 v[240:241], v[66:67], v[66:67], v[240:241]
	v_add_f32_e32 v171, v240, v241
	v_pk_mul_f32 v[238:239], v[60:61], v[60:61]
	v_pk_fma_f32 v[238:239], v[62:63], v[62:63], v[238:239]
	v_pk_fma_f32 v[238:239], v[56:57], v[56:57], v[238:239]
	v_pk_fma_f32 v[238:239], v[58:59], v[58:59], v[238:239]
	v_pk_fma_f32 v[238:239], v[52:53], v[52:53], v[238:239]
	v_pk_fma_f32 v[238:239], v[54:55], v[54:55], v[238:239]
	v_pk_fma_f32 v[238:239], v[48:49], v[48:49], v[238:239]
	v_pk_fma_f32 v[238:239], v[50:51], v[50:51], v[238:239]
	v_add_f32_e32 v193, v238, v239
	v_pk_mul_f32 v[240:241], v[44:45], v[44:45]
	v_pk_fma_f32 v[240:241], v[46:47], v[46:47], v[240:241]
	v_pk_fma_f32 v[240:241], v[40:41], v[40:41], v[240:241]
	v_pk_fma_f32 v[240:241], v[42:43], v[42:43], v[240:241]
	v_pk_fma_f32 v[240:241], v[36:37], v[36:37], v[240:241]
	v_pk_fma_f32 v[240:241], v[38:39], v[38:39], v[240:241]
	v_pk_fma_f32 v[240:241], v[32:33], v[32:33], v[240:241]
	v_pk_fma_f32 v[240:241], v[34:35], v[34:35], v[240:241]
	v_add_f32_e32 v233, v240, v241
	v_pk_mul_f32 v[238:239], v[28:29], v[28:29]
	v_pk_fma_f32 v[238:239], v[30:31], v[30:31], v[238:239]
	v_pk_fma_f32 v[238:239], v[24:25], v[24:25], v[238:239]
	v_pk_fma_f32 v[238:239], v[26:27], v[26:27], v[238:239]
	v_pk_fma_f32 v[238:239], v[20:21], v[20:21], v[238:239]
	v_pk_fma_f32 v[238:239], v[22:23], v[22:23], v[238:239]
	v_pk_fma_f32 v[238:239], v[16:17], v[16:17], v[238:239]
	v_pk_fma_f32 v[238:239], v[18:19], v[18:19], v[238:239]
	v_add_f32_e32 v235, v238, v239
	v_pk_mul_f32 v[240:241], v[12:13], v[12:13]
	v_pk_fma_f32 v[240:241], v[14:15], v[14:15], v[240:241]
	v_pk_fma_f32 v[240:241], v[8:9], v[8:9], v[240:241]
	v_pk_fma_f32 v[240:241], v[10:11], v[10:11], v[240:241]
	v_pk_fma_f32 v[240:241], v[4:5], v[4:5], v[240:241]
	v_pk_fma_f32 v[240:241], v[6:7], v[6:7], v[240:241]
	v_pk_fma_f32 v[240:241], v[0:1], v[0:1], v[240:241]
	v_pk_fma_f32 v[240:241], v[2:3], v[2:3], v[240:241]
	v_add_f32_e32 v237, v240, v241
	s_nop 1
	ds_bpermute_b32 v180, v194, v145
	ds_bpermute_b32 v184, v194, v155
	ds_bpermute_b32 v188, v194, v165
	ds_bpermute_b32 v196, v194, v171
	ds_bpermute_b32 v200, v194, v193
	ds_bpermute_b32 v204, v194, v233
	ds_bpermute_b32 v208, v194, v235
	ds_bpermute_b32 v212, v194, v237
	s_waitcnt lgkmcnt(0)
	v_add_f32_e32 v145, v145, v180
	v_add_f32_e32 v155, v155, v184
	v_add_f32_e32 v165, v165, v188
	v_add_f32_e32 v171, v171, v196
	v_add_f32_e32 v193, v193, v200
	v_add_f32_e32 v233, v233, v204
	v_add_f32_e32 v235, v235, v208
	v_add_f32_e32 v237, v237, v212
	s_nop 1
	ds_bpermute_b32 v180, v242, v145
	ds_bpermute_b32 v184, v242, v155
	ds_bpermute_b32 v188, v242, v165
	ds_bpermute_b32 v196, v242, v171
	ds_bpermute_b32 v200, v242, v193
	ds_bpermute_b32 v204, v242, v233
	ds_bpermute_b32 v208, v242, v235
	ds_bpermute_b32 v212, v242, v237
	s_waitcnt lgkmcnt(0)
	v_add_f32_e32 v145, v145, v180
	v_add_f32_e32 v155, v155, v184
	v_add_f32_e32 v165, v165, v188
	v_add_f32_e32 v171, v171, v196
	v_add_f32_e32 v193, v193, v200
	v_add_f32_e32 v233, v233, v204
	v_add_f32_e32 v235, v235, v208
	v_add_f32_e32 v237, v237, v212
	global_store_dword v166, v145, s[20:21]
	v_add_u32_e32 v184, 0x400, v166
	global_store_dword v184, v155, s[20:21]
	v_add_u32_e32 v188, 0x800, v166
	global_store_dword v188, v165, s[20:21]
	v_add_u32_e32 v196, 0xc00, v166
	global_store_dword v196, v171, s[20:21]
	v_add_u32_e32 v200, 0x2000, v166
	global_store_dword v200, v193, s[20:21]
	v_add_u32_e32 v204, 0x2400, v166
	global_store_dword v204, v233, s[20:21]
	v_add_u32_e32 v208, 0x2800, v166
	global_store_dword v208, v235, s[20:21]
	v_add_u32_e32 v212, 0x2c00, v166
	global_store_dword v212, v237, s[20:21]
	s_waitcnt vmcnt(0)
	s_barrier
	v_readfirstlane_b32 s94, v195
	s_cmp_lg_u32 s94, 0
	s_cbranch_scc1 .Lfe2_bskip
	s_mov_b64 exec, 1
	s_and_b32 s94, s2, 7
	s_lshl_b32 s94, s94, 3
	s_bfe_u32 s96, s2, 0x30003
	s_or_b32 s94, s94, s96
	s_lshl_b32 s94, s94, 5
	s_add_u32 s62, s28, 0x3903600
	s_addc_u32 s63, s29, 0
	v_mov_b32_e32 v238, s94
	v_mov_b32_e32 v239, 1
	s_cmp_eq_u32 s99, 1
	s_cbranch_scc1 .Lfe2_bfast
	buffer_wbl2 sc1
	s_waitcnt vmcnt(0)
.Lfe2_bfast:
	global_atomic_add v240, v238, v239, s[62:63] offset:8 sc0
	buffer_inv sc1
	s_waitcnt vmcnt(0)
	v_lshrrev_b32_e32 v240, 2, v240
	v_add_u32_e32 v240, 1, v240
	v_lshlrev_b32_e32 v240, 2, v240
	s_mov_b32 s94, 0
.Lfe2_bspin:
	global_load_dword v241, v238, s[62:63] offset:8 sc1
	s_waitcnt vmcnt(0)
	v_cmp_ge_u32_e32 vcc, v241, v240
	s_cbranch_vccnz .Lfe2_bdone
	s_sleep 1
	s_add_u32 s94, s94, 1
	s_cmp_lt_u32 s94, 0x400000
	s_cbranch_scc1 .Lfe2_bspin

; template <bool SRC_F32, int R> __device__ __forceinline__ void ew_load(EwSet<SRC_F32, R>& S, int rb, const float* hsrc32, const bf16* hsrcb, const bf16* f, const float* part, int lane) {
; #pragma unroll
;     for (int i = 0; i < R; ++i) S.p[i] = (lane < 16) ? part[(size_t)(rb + i) * 16 + lane] : 0.f;
; #pragma unroll
;     for (int i = 0; i < R; ++i)
; #pragma unroll
;         for (int j = 0; j < 4; ++j) {
;             S.fw[i][j] = ((const v2u*)(f + (size_t)(rb + i) * D) + lane)[64 * j];
;             if constexpr (SRC_F32) S.h32[i][j] = __builtin_nontemporal_load((const f32x4*)(hsrc32 + (size_t)(rb + i) * D) + lane + 64 * j);
;             else S.hb[i][j] = ((const v2u*)(hsrcb + (size_t)(rb + i) * D) + lane)[64 * j];
;         }
; template <bool SRC_F32, bool FINAL, int R> __device__ __forceinline__ void ew_compute(const EwSet<SRC_F32, R>& S, int rb, const f32x4 (&g)[4], bf16* hb_out, float* out32, float scale, float* rs_out, int lane) {
;     ...
;         float q = S.p[i];
;         q += __shfl_xor(q, 1); q += __shfl_xor(q, 2); q += __shfl_xor(q, 4); q += __shfl_xor(q, 8);
;         const float ss = __shfl(q, 0);
;         const float rs = scale / sqrtf(ss * (1.f / D) + EPS);
.Lfe2_bskip:
	s_barrier
	s_add_u32 s62, s84, 0xffffff10
	s_addc_u32 s63, s85, -1
	s_load_dwordx2 s[64:65], s[62:63], 0xb0
	s_add_u32 s66, s28, 0x5000000
	s_addc_u32 s67, s29, 0
	s_add_u32 s78, s28, 0x4c00000
	s_addc_u32 s79, s29, 0
	global_load_dwordx4 v[180:183], v168, s[20:21]
	v_add_u32_e32 v240, 0x400, v168
	global_load_dwordx4 v[184:187], v240, s[20:21]
	v_add_u32_e32 v240, 0x800, v168
	global_load_dwordx4 v[188:191], v240, s[20:21]
	v_add_u32_e32 v240, 0xc00, v168
	global_load_dwordx4 v[196:199], v240, s[20:21]
	v_add_u32_e32 v240, 0x2000, v168
	global_load_dwordx4 v[200:203], v240, s[20:21]
	v_add_u32_e32 v240, 0x2400, v168
	global_load_dwordx4 v[204:207], v240, s[20:21]
	v_add_u32_e32 v240, 0x2800, v168
	global_load_dwordx4 v[208:211], v240, s[20:21]
	v_add_u32_e32 v240, 0x2c00, v168
	global_load_dwordx4 v[212:215], v240, s[20:21]
	global_load_dwordx4 v[216:219], v153, s[66:67]
	global_load_dwordx4 v[220:223], v153, s[66:67] offset:256
	v_add_u32_e32 v240, 0x8000, v153
	global_load_dwordx4 v[224:227], v240, s[66:67]
	global_load_dwordx4 v[228:231], v240, s[66:67] offset:256
	s_waitcnt lgkmcnt(0)
	global_load_dwordx4 v[156:159], v243, s[64:65]
	global_load_dwordx4 v[160:163], v243, s[64:65] offset:16
	global_load_dwordx4 v[172:175], v243, s[64:65] offset:512
	global_load_dwordx4 v[176:179], v243, s[64:65] offset:528
	s_waitcnt vmcnt(8)
	v_add_f32_e32 v145, v180, v181
	v_add_f32_e32 v145, v182, v145
	v_add_f32_e32 v145, v183, v145
	v_add_f32_e32 v155, v184, v185
	v_add_f32_e32 v155, v186, v155
	v_add_f32_e32 v155, v187, v155
	v_add_f32_e32 v165, v188, v189
	v_add_f32_e32 v165, v190, v165
	v_add_f32_e32 v165, v191, v165
	v_add_f32_e32 v171, v196, v197
	v_add_f32_e32 v171, v198, v171
	v_add_f32_e32 v171, v199, v171
	v_add_f32_e32 v193, v200, v201
	v_add_f32_e32 v193, v202, v193
	v_add_f32_e32 v193, v203, v193
	v_add_f32_e32 v233, v204, v205
	v_add_f32_e32 v233, v206, v233
	v_add_f32_e32 v233, v207, v233
	v_add_f32_e32 v235, v208, v209
	v_add_f32_e32 v235, v210, v235
	v_add_f32_e32 v235, v211, v235
	v_add_f32_e32 v237, v212, v213
	v_add_f32_e32 v237, v214, v237
	v_add_f32_e32 v237, v215, v237
	s_nop 1
	ds_bpermute_b32 v180, v194, v145
	ds_bpermute_b32 v184, v194, v155
	ds_bpermute_b32 v188, v194, v165
	ds_bpermute_b32 v196, v194, v171
	ds_bpermute_b32 v200, v194, v193
	ds_bpermute_b32 v204, v194, v233
	ds_bpermute_b32 v208, v194, v235
	ds_bpermute_b32 v212, v194, v237
	s_waitcnt lgkmcnt(0)
	v_add_f32_e32 v145, v145, v180
	v_add_f32_e32 v155, v155, v184
	v_add_f32_e32 v165, v165, v188
	v_add_f32_e32 v171, v171, v196
	v_add_f32_e32 v193, v193, v200
	v_add_f32_e32 v233, v233, v204
	v_add_f32_e32 v235, v235, v208
	v_add_f32_e32 v237, v237, v212
	s_nop 1
	ds_bpermute_b32 v180, v242, v145
	ds_bpermute_b32 v184, v242, v155
	ds_bpermute_b32 v188, v242, v165
	ds_bpermute_b32 v196, v242, v171
	ds_bpermute_b32 v200, v242, v193
	ds_bpermute_b32 v204, v242, v233
	ds_bpermute_b32 v208, v242, v235
	ds_bpermute_b32 v212, v242, v237
	s_waitcnt lgkmcnt(0)
	v_add_f32_e32 v145, v145, v180
	v_add_f32_e32 v155, v155, v184
	v_add_f32_e32 v165, v165, v188
	v_add_f32_e32 v171, v171, v196
	v_add_f32_e32 v193, v193, v200
	v_add_f32_e32 v233, v233, v204
	v_add_f32_e32 v235, v235, v208
	v_add_f32_e32 v237, v237, v212
	v_mul_f32_e32 v145, 0x3a800000, v145
	v_mul_f32_e32 v155, 0x3a800000, v155
	v_mul_f32_e32 v165, 0x3a800000, v165
	v_mul_f32_e32 v171, 0x3a800000, v171
	v_mul_f32_e32 v193, 0x3a800000, v193
	v_mul_f32_e32 v233, 0x3a800000, v233
	v_mul_f32_e32 v235, 0x3a800000, v235
	v_mul_f32_e32 v237, 0x3a800000, v237
	v_add_f32_e32 v145, 0x358637bd, v145
	v_add_f32_e32 v155, 0x358637bd, v155
	v_add_f32_e32 v165, 0x358637bd, v165
	v_add_f32_e32 v171, 0x358637bd, v171
	v_add_f32_e32 v193, 0x358637bd, v193
	v_add_f32_e32 v233, 0x358637bd, v233
	v_add_f32_e32 v235, 0x358637bd, v235
	v_add_f32_e32 v237, 0x358637bd, v237
	v_rsq_f32_e32 v144, v145
	v_rsq_f32_e32 v154, v155
	v_rsq_f32_e32 v164, v165
	v_rsq_f32_e32 v170, v171
	v_rsq_f32_e32 v192, v193
	v_rsq_f32_e32 v232, v233
	v_rsq_f32_e32 v234, v235
	v_rsq_f32_e32 v236, v237
	s_nop 0
	v_mul_f32_e32 v144, 0x3f000000, v144
	v_mul_f32_e32 v154, 0x3f000000, v154
	v_mul_f32_e32 v164, 0x3f000000, v164
	v_mul_f32_e32 v170, 0x3f000000, v170
	v_mul_f32_e32 v192, 0x3f000000, v192
	v_mul_f32_e32 v232, 0x3f000000, v232
	v_mul_f32_e32 v234, 0x3f000000, v234
	v_mul_f32_e32 v236, 0x3f000000, v236
	v_add_u32_e32 v240, 0x10000, v153
	global_load_dwordx4 v[180:183], v240, s[66:67]
	global_load_dwordx4 v[184:187], v240, s[66:67] offset:256
	v_add_u32_e32 v240, 0x18000, v153
	global_load_dwordx4 v[188:191], v240, s[66:67]
	global_load_dwordx4 v[196:199], v240, s[66:67] offset:256
	v_add_u32_e32 v240, 0x40000, v153
	global_load_dwordx4 v[200:203], v240, s[66:67]
	global_load_dwordx4 v[204:207], v240, s[66:67] offset:256
	v_add_u32_e32 v240, 0x48000, v153
	global_load_dwordx4 v[208:211], v240, s[66:67]
	global_load_dwordx4 v[212:215], v240, s[66:67] offset:256
	s_waitcnt vmcnt(8)
; __device__ __forceinline__ float bf_lo(unsigned w) { return __uint_as_float(w << 16); }
; __device__ __forceinline__ float bf_hi(unsigned w) { return __uint_as_float(w & 0xffff0000u); }
; __device__ __forceinline__ unsigned pk2(float lo, float hi) { bf16x2_t r = __builtin_convertvector((f32x2_t){lo, hi}, bf16x2_t); return __builtin_bit_cast(unsigned, r); }
; template <bool SRC_F32, bool FINAL, int R> __device__ __forceinline__ void ew_compute(const EwSet<SRC_F32, R>& S, int rb, const f32x4 (&g)[4], bf16* hb_out, float* out32, float scale, float* rs_out, int lane) {
;     ...
;         float s2 = 0.f;
; #pragma unroll
;         for (int j = 0; j < 4; ++j) {
;             f32x4 h;
;             if constexpr (SRC_F32) h = S.h32[i][j];
;             else { const v2u hw = S.hb[i][j]; h.x = bf_lo(hw.x); h.y = bf_hi(hw.x); h.z = bf_lo(hw.y); h.w = bf_hi(hw.y); }
;             const v2u fw = S.fw[i][j];
;             f32x4 v; v.x = h.x + bf_lo(fw.x) * rs * g[j].x; v.y = h.y + bf_hi(fw.x) * rs * g[j].y; v.z = h.z + bf_lo(fw.y) * rs * g[j].z; v.w = h.w + bf_hi(fw.y) * rs * g[j].w;
;             if (FINAL) __builtin_nontemporal_store(v, (f32x4*)(out32 + (size_t)(rb + i) * D) + lane + 64 * j);
;             else { v2u o; o.x = pk2(v.x, v.y); o.y = pk2(v.z, v.w); ((v2u*)(hb_out + (size_t)(rb + i) * D) + lane)[64 * j] = o; s2 += (v.x * v.x + v.y * v.y) + (v.z * v.z + v.w * v.w); }
;         }
;         if (!FINAL) { const float tot = wave_sum(s2); if (lane == 0) rs_out[rb + i] = 1.0f / sqrtf(tot * (1.f / D) + EPS); }
	v_lshlrev_b32_e32 v238, 16, v216
	v_and_b32_e32 v239, 0xffff0000, v216
	v_pk_mul_f32 v[124:125], v[124:125], v[144:145] op_sel_hi:[1,0]
	v_pk_fma_f32 v[124:125], v[124:125], v[156:157], v[238:239]
	v_lshlrev_b32_e32 v240, 16, v217
	v_and_b32_e32 v241, 0xffff0000, v217
	v_pk_mul_f32 v[126:127], v[126:127], v[144:145] op_sel_hi:[1,0]
	v_pk_fma_f32 v[126:127], v[126:127], v[158:159], v[240:241]
	v_lshlrev_b32_e32 v238, 16, v218
	v_and_b32_e32 v239, 0xffff0000, v218
	v_pk_mul_f32 v[120:121], v[120:121], v[144:145] op_sel_hi:[1,0]
	v_pk_fma_f32 v[120:121], v[120:121], v[160:161], v[238:239]
	v_lshlrev_b32_e32 v240, 16, v219
	v_and_b32_e32 v241, 0xffff0000, v219
	v_pk_mul_f32 v[122:123], v[122:123], v[144:145] op_sel_hi:[1,0]
	v_pk_fma_f32 v[122:123], v[122:123], v[162:163], v[240:241]
	v_lshlrev_b32_e32 v238, 16, v220
	v_and_b32_e32 v239, 0xffff0000, v220
	v_pk_mul_f32 v[116:117], v[116:117], v[144:145] op_sel_hi:[1,0]
	v_pk_fma_f32 v[116:117], v[116:117], v[172:173], v[238:239]
	v_lshlrev_b32_e32 v240, 16, v221
	v_and_b32_e32 v241, 0xffff0000, v221
	v_pk_mul_f32 v[118:119], v[118:119], v[144:145] op_sel_hi:[1,0]
	v_pk_fma_f32 v[118:119], v[118:119], v[174:175], v[240:241]
	v_lshlrev_b32_e32 v238, 16, v222
	v_and_b32_e32 v239, 0xffff0000, v222
	v_pk_mul_f32 v[112:113], v[112:113], v[144:145] op_sel_hi:[1,0]
	v_pk_fma_f32 v[112:113], v[112:113], v[176:177], v[238:239]
	v_lshlrev_b32_e32 v240, 16, v223
	v_and_b32_e32 v241, 0xffff0000, v223
	v_pk_mul_f32 v[114:115], v[114:115], v[144:145] op_sel_hi:[1,0]
	v_pk_fma_f32 v[114:115], v[114:115], v[178:179], v[240:241]
	v_pk_mul_f32 v[238:239], v[124:125], v[124:125]
	v_pk_fma_f32 v[238:239], v[126:127], v[126:127], v[238:239]
	v_pk_fma_f32 v[238:239], v[120:121], v[120:121], v[238:239]
	v_pk_fma_f32 v[238:239], v[122:123], v[122:123], v[238:239]
	v_pk_fma_f32 v[238:239], v[116:117], v[116:117], v[238:239]
	v_pk_fma_f32 v[238:239], v[118:119], v[118:119], v[238:239]
	v_pk_fma_f32 v[238:239], v[112:113], v[112:113], v[238:239]
	v_pk_fma_f32 v[238:239], v[114:115], v[114:115], v[238:239]
	v_add_f32_e32 v145, v238, v239
	v_cvt_pk_bf16_f32 v216, v124, v125
	v_cvt_pk_bf16_f32 v217, v126, v127
	v_cvt_pk_bf16_f32 v218, v120, v121
	v_cvt_pk_bf16_f32 v219, v122, v123
	v_cvt_pk_bf16_f32 v220, v116, v117
	v_cvt_pk_bf16_f32 v221, v118, v119
	v_cvt_pk_bf16_f32 v222, v112, v113
	v_cvt_pk_bf16_f32 v223, v114, v115
	s_nop 0
	global_store_dwordx4 v153, v[216:219], s[66:67]
	global_store_dwordx4 v153, v[220:223], s[66:67] offset:256
	s_waitcnt vmcnt(10)
	v_lshlrev_b32_e32 v238, 16, v224
	v_and_b32_e32 v239, 0xffff0000, v224
	v_pk_mul_f32 v[108:109], v[108:109], v[154:155] op_sel_hi:[1,0]
	v_pk_fma_f32 v[108:109], v[108:109], v[156:157], v[238:239]
	v_lshlrev_b32_e32 v240, 16, v225
	v_and_b32_e32 v241, 0xffff0000, v225
	v_pk_mul_f32 v[110:111], v[110:111], v[154:155] op_sel_hi:[1,0]
	v_pk_fma_f32 v[110:111], v[110:111], v[158:159], v[240:241]
	v_lshlrev_b32_e32 v238, 16, v226
	v_and_b32_e32 v239, 0xffff0000, v226
	v_pk_mul_f32 v[104:105], v[104:105], v[154:155] op_sel_hi:[1,0]
	v_pk_fma_f32 v[104:105], v[104:105], v[160:161], v[238:239]
	v_lshlrev_b32_e32 v240, 16, v227
	v_and_b32_e32 v241, 0xffff0000, v227
	v_pk_mul_f32 v[106:107], v[106:107], v[154:155] op_sel_hi:[1,0]
	v_pk_fma_f32 v[106:107], v[106:107], v[162:163], v[240:241]
	v_lshlrev_b32_e32 v238, 16, v228
	v_and_b32_e32 v239, 0xffff0000, v228
	v_pk_mul_f32 v[100:101], v[100:101], v[154:155] op_sel_hi:[1,0]
	v_pk_fma_f32 v[100:101], v[100:101], v[172:173], v[238:239]
	v_lshlrev_b32_e32 v240, 16, v229
	v_and_b32_e32 v241, 0xffff0000, v229
	v_pk_mul_f32 v[102:103], v[102:103], v[154:155] op_sel_hi:[1,0]
	v_pk_fma_f32 v[102:103], v[102:103], v[174:175], v[240:241]
	v_lshlrev_b32_e32 v238, 16, v230
	v_and_b32_e32 v239, 0xffff0000, v230
	v_pk_mul_f32 v[96:97], v[96:97], v[154:155] op_sel_hi:[1,0]
	v_pk_fma_f32 v[96:97], v[96:97], v[176:177], v[238:239]
	v_lshlrev_b32_e32 v240, 16, v231
	v_and_b32_e32 v241, 0xffff0000, v231
	v_pk_mul_f32 v[98:99], v[98:99], v[154:155] op_sel_hi:[1,0]
	v_pk_fma_f32 v[98:99], v[98:99], v[178:179], v[240:241]
	v_pk_mul_f32 v[238:239], v[108:109], v[108:109]
	v_pk_fma_f32 v[238:239], v[110:111], v[110:111], v[238:239]
	v_pk_fma_f32 v[238:239], v[104:105], v[104:105], v[238:239]
	v_pk_fma_f32 v[238:239], v[106:107], v[106:107], v[238:239]
	v_pk_fma_f32 v[238:239], v[100:101], v[100:101], v[238:239]
	v_pk_fma_f32 v[238:239], v[102:103], v[102:103], v[238:239]
	v_pk_fma_f32 v[238:239], v[96:97], v[96:97], v[238:239]
	v_pk_fma_f32 v[238:239], v[98:99], v[98:99], v[238:239]
	v_add_f32_e32 v155, v238, v239
	v_cvt_pk_bf16_f32 v224, v108, v109
	v_cvt_pk_bf16_f32 v225, v110, v111
	v_cvt_pk_bf16_f32 v226, v104, v105
	v_cvt_pk_bf16_f32 v227, v106, v107
	v_cvt_pk_bf16_f32 v228, v100, v101
	v_cvt_pk_bf16_f32 v229, v102, v103
	v_cvt_pk_bf16_f32 v230, v96, v97
	v_cvt_pk_bf16_f32 v231, v98, v99
	v_add_u32_e32 v240, 0x8000, v153
	s_nop 0
	global_store_dwordx4 v240, v[224:227], s[66:67]
	global_store_dwordx4 v240, v[228:231], s[66:67] offset:256
	s_nop 1
	v_add_u32_e32 v240, 0x50000, v153
	global_load_dwordx4 v[216:219], v240, s[66:67]
	global_load_dwordx4 v[220:223], v240, s[66:67] offset:256
	v_add_u32_e32 v240, 0x58000, v153
	global_load_dwordx4 v[224:227], v240, s[66:67]
	global_load_dwordx4 v[228:231], v240, s[66:67] offset:256
	s_waitcnt vmcnt(14)
; __device__ __forceinline__ float bf_lo(unsigned w) { return __uint_as_float(w << 16); }
; __device__ __forceinline__ float bf_hi(unsigned w) { return __uint_as_float(w & 0xffff0000u); }
; __device__ __forceinline__ unsigned pk2(float lo, float hi) { bf16x2_t r = __builtin_convertvector((f32x2_t){lo, hi}, bf16x2_t); return __builtin_bit_cast(unsigned, r); }
; template <bool SRC_F32, bool FINAL, int R> __device__ __forceinline__ void ew_compute(const EwSet<SRC_F32, R>& S, int rb, const f32x4 (&g)[4], bf16* hb_out, float* out32, float scale, float* rs_out, int lane) {
;     ...
;         float s2 = 0.f;
; #pragma unroll
;         for (int j = 0; j < 4; ++j) {
;             f32x4 h;
;             if constexpr (SRC_F32) h = S.h32[i][j];
;             else { const v2u hw = S.hb[i][j]; h.x = bf_lo(hw.x); h.y = bf_hi(hw.x); h.z = bf_lo(hw.y); h.w = bf_hi(hw.y); }
;             const v2u fw = S.fw[i][j];
;             f32x4 v; v.x = h.x + bf_lo(fw.x) * rs * g[j].x; v.y = h.y + bf_hi(fw.x) * rs * g[j].y; v.z = h.z + bf_lo(fw.y) * rs * g[j].z; v.w = h.w + bf_hi(fw.y) * rs * g[j].w;
;             if (FINAL) __builtin_nontemporal_store(v, (f32x4*)(out32 + (size_t)(rb + i) * D) + lane + 64 * j);
;             else { v2u o; o.x = pk2(v.x, v.y); o.y = pk2(v.z, v.w); ((v2u*)(hb_out + (size_t)(rb + i) * D) + lane)[64 * j] = o; s2 += (v.x * v.x + v.y * v.y) + (v.z * v.z + v.w * v.w); }
;         }
;         if (!FINAL) { const float tot = wave_sum(s2); if (lane == 0) rs_out[rb + i] = 1.0f / sqrtf(tot * (1.f / D) + EPS); }
	v_lshlrev_b32_e32 v238, 16, v180
	v_and_b32_e32 v239, 0xffff0000, v180
	v_pk_mul_f32 v[92:93], v[92:93], v[164:165] op_sel_hi:[1,0]
	v_pk_fma_f32 v[92:93], v[92:93], v[156:157], v[238:239]
	v_lshlrev_b32_e32 v240, 16, v181
	v_and_b32_e32 v241, 0xffff0000, v181
	v_pk_mul_f32 v[94:95], v[94:95], v[164:165] op_sel_hi:[1,0]
	v_pk_fma_f32 v[94:95], v[94:95], v[158:159], v[240:241]
	v_lshlrev_b32_e32 v238, 16, v182
	v_and_b32_e32 v239, 0xffff0000, v182
	v_pk_mul_f32 v[88:89], v[88:89], v[164:165] op_sel_hi:[1,0]
	v_pk_fma_f32 v[88:89], v[88:89], v[160:161], v[238:239]
	v_lshlrev_b32_e32 v240, 16, v183
	v_and_b32_e32 v241, 0xffff0000, v183
	v_pk_mul_f32 v[90:91], v[90:91], v[164:165] op_sel_hi:[1,0]
	v_pk_fma_f32 v[90:91], v[90:91], v[162:163], v[240:241]
	v_lshlrev_b32_e32 v238, 16, v184
	v_and_b32_e32 v239, 0xffff0000, v184
	v_pk_mul_f32 v[84:85], v[84:85], v[164:165] op_sel_hi:[1,0]
	v_pk_fma_f32 v[84:85], v[84:85], v[172:173], v[238:239]
	v_lshlrev_b32_e32 v240, 16, v185
	v_and_b32_e32 v241, 0xffff0000, v185
	v_pk_mul_f32 v[86:87], v[86:87], v[164:165] op_sel_hi:[1,0]
	v_pk_fma_f32 v[86:87], v[86:87], v[174:175], v[240:241]
	v_lshlrev_b32_e32 v238, 16, v186
	v_and_b32_e32 v239, 0xffff0000, v186
	v_pk_mul_f32 v[80:81], v[80:81], v[164:165] op_sel_hi:[1,0]
	v_pk_fma_f32 v[80:81], v[80:81], v[176:177], v[238:239]
	v_lshlrev_b32_e32 v240, 16, v187
	v_and_b32_e32 v241, 0xffff0000, v187
	v_pk_mul_f32 v[82:83], v[82:83], v[164:165] op_sel_hi:[1,0]
	v_pk_fma_f32 v[82:83], v[82:83], v[178:179], v[240:241]
	v_pk_mul_f32 v[238:239], v[92:93], v[92:93]
	v_pk_fma_f32 v[238:239], v[94:95], v[94:95], v[238:239]
	v_pk_fma_f32 v[238:239], v[88:89], v[88:89], v[238:239]
	v_pk_fma_f32 v[238:239], v[90:91], v[90:91], v[238:239]
	v_pk_fma_f32 v[238:239], v[84:85], v[84:85], v[238:239]
	v_pk_fma_f32 v[238:239], v[86:87], v[86:87], v[238:239]
	v_pk_fma_f32 v[238:239], v[80:81], v[80:81], v[238:239]
	v_pk_fma_f32 v[238:239], v[82:83], v[82:83], v[238:239]
	v_add_f32_e32 v165, v238, v239
	v_cvt_pk_bf16_f32 v180, v92, v93
	v_cvt_pk_bf16_f32 v181, v94, v95
	v_cvt_pk_bf16_f32 v182, v88, v89
	v_cvt_pk_bf16_f32 v183, v90, v91
	v_cvt_pk_bf16_f32 v184, v84, v85
	v_cvt_pk_bf16_f32 v185, v86, v87
	v_cvt_pk_bf16_f32 v186, v80, v81
	v_cvt_pk_bf16_f32 v187, v82, v83
	v_add_u32_e32 v240, 0x10000, v153
	s_nop 0
	global_store_dwordx4 v240, v[180:183], s[66:67]
	global_store_dwordx4 v240, v[184:187], s[66:67] offset:256
	s_waitcnt vmcnt(14)
	v_lshlrev_b32_e32 v238, 16, v188
	v_and_b32_e32 v239, 0xffff0000, v188
	v_pk_mul_f32 v[76:77], v[76:77], v[170:171] op_sel_hi:[1,0]
	v_pk_fma_f32 v[76:77], v[76:77], v[156:157], v[238:239]
	v_lshlrev_b32_e32 v240, 16, v189
	v_and_b32_e32 v241, 0xffff0000, v189
	v_pk_mul_f32 v[78:79], v[78:79], v[170:171] op_sel_hi:[1,0]
	v_pk_fma_f32 v[78:79], v[78:79], v[158:159], v[240:241]
	v_lshlrev_b32_e32 v238, 16, v190
	v_and_b32_e32 v239, 0xffff0000, v190
	v_pk_mul_f32 v[72:73], v[72:73], v[170:171] op_sel_hi:[1,0]
	v_pk_fma_f32 v[72:73], v[72:73], v[160:161], v[238:239]
	v_lshlrev_b32_e32 v240, 16, v191
	v_and_b32_e32 v241, 0xffff0000, v191
	v_pk_mul_f32 v[74:75], v[74:75], v[170:171] op_sel_hi:[1,0]
	v_pk_fma_f32 v[74:75], v[74:75], v[162:163], v[240:241]
	v_lshlrev_b32_e32 v238, 16, v196
	v_and_b32_e32 v239, 0xffff0000, v196
	v_pk_mul_f32 v[68:69], v[68:69], v[170:171] op_sel_hi:[1,0]
	v_pk_fma_f32 v[68:69], v[68:69], v[172:173], v[238:239]
	v_lshlrev_b32_e32 v240, 16, v197
	v_and_b32_e32 v241, 0xffff0000, v197
	v_pk_mul_f32 v[70:71], v[70:71], v[170:171] op_sel_hi:[1,0]
	v_pk_fma_f32 v[70:71], v[70:71], v[174:175], v[240:241]
	v_lshlrev_b32_e32 v238, 16, v198
	v_and_b32_e32 v239, 0xffff0000, v198
	v_pk_mul_f32 v[64:65], v[64:65], v[170:171] op_sel_hi:[1,0]
	v_pk_fma_f32 v[64:65], v[64:65], v[176:177], v[238:239]
	v_lshlrev_b32_e32 v240, 16, v199
	v_and_b32_e32 v241, 0xffff0000, v199
	v_pk_mul_f32 v[66:67], v[66:67], v[170:171] op_sel_hi:[1,0]
	v_pk_fma_f32 v[66:67], v[66:67], v[178:179], v[240:241]
	v_pk_mul_f32 v[238:239], v[76:77], v[76:77]
	v_pk_fma_f32 v[238:239], v[78:79], v[78:79], v[238:239]
	v_pk_fma_f32 v[238:239], v[72:73], v[72:73], v[238:239]
	v_pk_fma_f32 v[238:239], v[74:75], v[74:75], v[238:239]
	v_pk_fma_f32 v[238:239], v[68:69], v[68:69], v[238:239]
	v_pk_fma_f32 v[238:239], v[70:71], v[70:71], v[238:239]
	v_pk_fma_f32 v[238:239], v[64:65], v[64:65], v[238:239]
	v_pk_fma_f32 v[238:239], v[66:67], v[66:67], v[238:239]
	v_add_f32_e32 v171, v238, v239
	v_cvt_pk_bf16_f32 v188, v76, v77
	v_cvt_pk_bf16_f32 v189, v78, v79
	v_cvt_pk_bf16_f32 v190, v72, v73
	v_cvt_pk_bf16_f32 v191, v74, v75
	v_cvt_pk_bf16_f32 v196, v68, v69
	v_cvt_pk_bf16_f32 v197, v70, v71
	v_cvt_pk_bf16_f32 v198, v64, v65
	v_cvt_pk_bf16_f32 v199, v66, v67
	v_add_u32_e32 v240, 0x18000, v153
	s_nop 0
	global_store_dwordx4 v240, v[188:191], s[66:67]
	global_store_dwordx4 v240, v[196:199], s[66:67] offset:256
	s_waitcnt vmcnt(14)
; __device__ __forceinline__ float bf_lo(unsigned w) { return __uint_as_float(w << 16); }
; __device__ __forceinline__ float bf_hi(unsigned w) { return __uint_as_float(w & 0xffff0000u); }
; __device__ __forceinline__ unsigned pk2(float lo, float hi) { bf16x2_t r = __builtin_convertvector((f32x2_t){lo, hi}, bf16x2_t); return __builtin_bit_cast(unsigned, r); }
; template <bool SRC_F32, bool FINAL, int R> __device__ __forceinline__ void ew_compute(const EwSet<SRC_F32, R>& S, int rb, const f32x4 (&g)[4], bf16* hb_out, float* out32, float scale, float* rs_out, int lane) {
;     ...
;         float s2 = 0.f;
; #pragma unroll
;         for (int j = 0; j < 4; ++j) {
;             f32x4 h;
;             if constexpr (SRC_F32) h = S.h32[i][j];
;             else { const v2u hw = S.hb[i][j]; h.x = bf_lo(hw.x); h.y = bf_hi(hw.x); h.z = bf_lo(hw.y); h.w = bf_hi(hw.y); }
;             const v2u fw = S.fw[i][j];
;             f32x4 v; v.x = h.x + bf_lo(fw.x) * rs * g[j].x; v.y = h.y + bf_hi(fw.x) * rs * g[j].y; v.z = h.z + bf_lo(fw.y) * rs * g[j].z; v.w = h.w + bf_hi(fw.y) * rs * g[j].w;
;             if (FINAL) __builtin_nontemporal_store(v, (f32x4*)(out32 + (size_t)(rb + i) * D) + lane + 64 * j);
;             else { v2u o; o.x = pk2(v.x, v.y); o.y = pk2(v.z, v.w); ((v2u*)(hb_out + (size_t)(rb + i) * D) + lane)[64 * j] = o; s2 += (v.x * v.x + v.y * v.y) + (v.z * v.z + v.w * v.w); }
;         }
;         if (!FINAL) { const float tot = wave_sum(s2); if (lane == 0) rs_out[rb + i] = 1.0f / sqrtf(tot * (1.f / D) + EPS); }
	v_lshlrev_b32_e32 v238, 16, v200
	v_and_b32_e32 v239, 0xffff0000, v200
	v_pk_mul_f32 v[60:61], v[60:61], v[192:193] op_sel_hi:[1,0]
	v_pk_fma_f32 v[60:61], v[60:61], v[156:157], v[238:239]
	v_lshlrev_b32_e32 v240, 16, v201
	v_and_b32_e32 v241, 0xffff0000, v201
	v_pk_mul_f32 v[62:63], v[62:63], v[192:193] op_sel_hi:[1,0]
	v_pk_fma_f32 v[62:63], v[62:63], v[158:159], v[240:241]
	v_lshlrev_b32_e32 v238, 16, v202
	v_and_b32_e32 v239, 0xffff0000, v202
	v_pk_mul_f32 v[56:57], v[56:57], v[192:193] op_sel_hi:[1,0]
	v_pk_fma_f32 v[56:57], v[56:57], v[160:161], v[238:239]
	v_lshlrev_b32_e32 v240, 16, v203
	v_and_b32_e32 v241, 0xffff0000, v203
	v_pk_mul_f32 v[58:59], v[58:59], v[192:193] op_sel_hi:[1,0]
	v_pk_fma_f32 v[58:59], v[58:59], v[162:163], v[240:241]
	v_lshlrev_b32_e32 v238, 16, v204
	v_and_b32_e32 v239, 0xffff0000, v204
	v_pk_mul_f32 v[52:53], v[52:53], v[192:193] op_sel_hi:[1,0]
	v_pk_fma_f32 v[52:53], v[52:53], v[172:173], v[238:239]
	v_lshlrev_b32_e32 v240, 16, v205
	v_and_b32_e32 v241, 0xffff0000, v205
	v_pk_mul_f32 v[54:55], v[54:55], v[192:193] op_sel_hi:[1,0]
	v_pk_fma_f32 v[54:55], v[54:55], v[174:175], v[240:241]
	v_lshlrev_b32_e32 v238, 16, v206
	v_and_b32_e32 v239, 0xffff0000, v206
	v_pk_mul_f32 v[48:49], v[48:49], v[192:193] op_sel_hi:[1,0]
	v_pk_fma_f32 v[48:49], v[48:49], v[176:177], v[238:239]
	v_lshlrev_b32_e32 v240, 16, v207
	v_and_b32_e32 v241, 0xffff0000, v207
	v_pk_mul_f32 v[50:51], v[50:51], v[192:193] op_sel_hi:[1,0]
	v_pk_fma_f32 v[50:51], v[50:51], v[178:179], v[240:241]
	v_pk_mul_f32 v[238:239], v[60:61], v[60:61]
	v_pk_fma_f32 v[238:239], v[62:63], v[62:63], v[238:239]
	v_pk_fma_f32 v[238:239], v[56:57], v[56:57], v[238:239]
	v_pk_fma_f32 v[238:239], v[58:59], v[58:59], v[238:239]
	v_pk_fma_f32 v[238:239], v[52:53], v[52:53], v[238:239]
	v_pk_fma_f32 v[238:239], v[54:55], v[54:55], v[238:239]
	v_pk_fma_f32 v[238:239], v[48:49], v[48:49], v[238:239]
	v_pk_fma_f32 v[238:239], v[50:51], v[50:51], v[238:239]
	v_add_f32_e32 v193, v238, v239
	v_cvt_pk_bf16_f32 v200, v60, v61
	v_cvt_pk_bf16_f32 v201, v62, v63
	v_cvt_pk_bf16_f32 v202, v56, v57
	v_cvt_pk_bf16_f32 v203, v58, v59
	v_cvt_pk_bf16_f32 v204, v52, v53
	v_cvt_pk_bf16_f32 v205, v54, v55
	v_cvt_pk_bf16_f32 v206, v48, v49
	v_cvt_pk_bf16_f32 v207, v50, v51
	v_add_u32_e32 v240, 0x40000, v153
	s_nop 0
	global_store_dwordx4 v240, v[200:203], s[66:67]
	global_store_dwordx4 v240, v[204:207], s[66:67] offset:256
	s_waitcnt vmcnt(14)
	v_lshlrev_b32_e32 v238, 16, v208
	v_and_b32_e32 v239, 0xffff0000, v208
	v_pk_mul_f32 v[44:45], v[44:45], v[232:233] op_sel_hi:[1,0]
	v_pk_fma_f32 v[44:45], v[44:45], v[156:157], v[238:239]
	v_lshlrev_b32_e32 v240, 16, v209
	v_and_b32_e32 v241, 0xffff0000, v209
	v_pk_mul_f32 v[46:47], v[46:47], v[232:233] op_sel_hi:[1,0]
	v_pk_fma_f32 v[46:47], v[46:47], v[158:159], v[240:241]
	v_lshlrev_b32_e32 v238, 16, v210
	v_and_b32_e32 v239, 0xffff0000, v210
	v_pk_mul_f32 v[40:41], v[40:41], v[232:233] op_sel_hi:[1,0]
	v_pk_fma_f32 v[40:41], v[40:41], v[160:161], v[238:239]
	v_lshlrev_b32_e32 v240, 16, v211
	v_and_b32_e32 v241, 0xffff0000, v211
	v_pk_mul_f32 v[42:43], v[42:43], v[232:233] op_sel_hi:[1,0]
	v_pk_fma_f32 v[42:43], v[42:43], v[162:163], v[240:241]
	v_lshlrev_b32_e32 v238, 16, v212
	v_and_b32_e32 v239, 0xffff0000, v212
	v_pk_mul_f32 v[36:37], v[36:37], v[232:233] op_sel_hi:[1,0]
	v_pk_fma_f32 v[36:37], v[36:37], v[172:173], v[238:239]
	v_lshlrev_b32_e32 v240, 16, v213
	v_and_b32_e32 v241, 0xffff0000, v213
	v_pk_mul_f32 v[38:39], v[38:39], v[232:233] op_sel_hi:[1,0]
	v_pk_fma_f32 v[38:39], v[38:39], v[174:175], v[240:241]
	v_lshlrev_b32_e32 v238, 16, v214
	v_and_b32_e32 v239, 0xffff0000, v214
	v_pk_mul_f32 v[32:33], v[32:33], v[232:233] op_sel_hi:[1,0]
	v_pk_fma_f32 v[32:33], v[32:33], v[176:177], v[238:239]
	v_lshlrev_b32_e32 v240, 16, v215
	v_and_b32_e32 v241, 0xffff0000, v215
	v_pk_mul_f32 v[34:35], v[34:35], v[232:233] op_sel_hi:[1,0]
	v_pk_fma_f32 v[34:35], v[34:35], v[178:179], v[240:241]
	v_pk_mul_f32 v[238:239], v[44:45], v[44:45]
	v_pk_fma_f32 v[238:239], v[46:47], v[46:47], v[238:239]
	v_pk_fma_f32 v[238:239], v[40:41], v[40:41], v[238:239]
	v_pk_fma_f32 v[238:239], v[42:43], v[42:43], v[238:239]
	v_pk_fma_f32 v[238:239], v[36:37], v[36:37], v[238:239]
	v_pk_fma_f32 v[238:239], v[38:39], v[38:39], v[238:239]
	v_pk_fma_f32 v[238:239], v[32:33], v[32:33], v[238:239]
	v_pk_fma_f32 v[238:239], v[34:35], v[34:35], v[238:239]
	v_add_f32_e32 v233, v238, v239
	v_cvt_pk_bf16_f32 v208, v44, v45
	v_cvt_pk_bf16_f32 v209, v46, v47
	v_cvt_pk_bf16_f32 v210, v40, v41
	v_cvt_pk_bf16_f32 v211, v42, v43
	v_cvt_pk_bf16_f32 v212, v36, v37
	v_cvt_pk_bf16_f32 v213, v38, v39
	v_cvt_pk_bf16_f32 v214, v32, v33
	v_cvt_pk_bf16_f32 v215, v34, v35
	v_add_u32_e32 v240, 0x48000, v153
	s_nop 0
	global_store_dwordx4 v240, v[208:211], s[66:67]
	global_store_dwordx4 v240, v[212:215], s[66:67] offset:256
	s_waitcnt vmcnt(10)
; __device__ __forceinline__ float bf_lo(unsigned w) { return __uint_as_float(w << 16); }
; __device__ __forceinline__ float bf_hi(unsigned w) { return __uint_as_float(w & 0xffff0000u); }
; __device__ __forceinline__ unsigned pk2(float lo, float hi) { bf16x2_t r = __builtin_convertvector((f32x2_t){lo, hi}, bf16x2_t); return __builtin_bit_cast(unsigned, r); }
;     __device__ __forceinline__ void operator()(const pg8::f32x4 (&acc)[2][2][4][2], const pg8::Unit& u, int wr, int wc, int fr, int fq) const {
;     ...
;                     if (PART) {
; #pragma unroll
;                         for (int j = 0; j < 8; ++j) s += r[j] * r[j];
;                     }
;                     v4u w; w.x = pk2(r[0], r[1]); w.y = pk2(r[2], r[3]); w.z = pk2(r[4], r[5]); w.w = pk2(r[6], r[7]);
;                     st16_wt(O + off + bj * 128, w);
;                 }
;                 if (PART) { s += __shfl_xor(s, 16); s += __shfl_xor(s, 32); st4_wt(part + (size_t)row * 16 + u.pn * 4 + wc, s); }
; template <bool SRC_F32, bool FINAL, int R> __device__ __forceinline__ void ew_compute(const EwSet<SRC_F32, R>& S, int rb, const f32x4 (&g)[4], bf16* hb_out, float* out32, float scale, float* rs_out, int lane) {
;     ...
;         float s2 = 0.f;
; #pragma unroll
;         for (int j = 0; j < 4; ++j) {
;             f32x4 h;
;             if constexpr (SRC_F32) h = S.h32[i][j];
;             else { const v2u hw = S.hb[i][j]; h.x = bf_lo(hw.x); h.y = bf_hi(hw.x); h.z = bf_lo(hw.y); h.w = bf_hi(hw.y); }
;             const v2u fw = S.fw[i][j];
;             f32x4 v; v.x = h.x + bf_lo(fw.x) * rs * g[j].x; v.y = h.y + bf_hi(fw.x) * rs * g[j].y; v.z = h.z + bf_lo(fw.y) * rs * g[j].z; v.w = h.w + bf_hi(fw.y) * rs * g[j].w;
;             if (FINAL) __builtin_nontemporal_store(v, (f32x4*)(out32 + (size_t)(rb + i) * D) + lane + 64 * j);
;             else { v2u o; o.x = pk2(v.x, v.y); o.y = pk2(v.z, v.w); ((v2u*)(hb_out + (size_t)(rb + i) * D) + lane)[64 * j] = o; s2 += (v.x * v.x + v.y * v.y) + (v.z * v.z + v.w * v.w); }
;         }
;         if (!FINAL) { const float tot = wave_sum(s2); if (lane == 0) rs_out[rb + i] = 1.0f / sqrtf(tot * (1.f / D) + EPS); }
;     }
	v_lshlrev_b32_e32 v238, 16, v216
	v_and_b32_e32 v239, 0xffff0000, v216
	v_pk_mul_f32 v[28:29], v[28:29], v[234:235] op_sel_hi:[1,0]
	v_pk_fma_f32 v[28:29], v[28:29], v[156:157], v[238:239]
	v_lshlrev_b32_e32 v240, 16, v217
	v_and_b32_e32 v241, 0xffff0000, v217
	v_pk_mul_f32 v[30:31], v[30:31], v[234:235] op_sel_hi:[1,0]
	v_pk_fma_f32 v[30:31], v[30:31], v[158:159], v[240:241]
	v_lshlrev_b32_e32 v238, 16, v218
	v_and_b32_e32 v239, 0xffff0000, v218
	v_pk_mul_f32 v[24:25], v[24:25], v[234:235] op_sel_hi:[1,0]
	v_pk_fma_f32 v[24:25], v[24:25], v[160:161], v[238:239]
	v_lshlrev_b32_e32 v240, 16, v219
	v_and_b32_e32 v241, 0xffff0000, v219
	v_pk_mul_f32 v[26:27], v[26:27], v[234:235] op_sel_hi:[1,0]
	v_pk_fma_f32 v[26:27], v[26:27], v[162:163], v[240:241]
	v_lshlrev_b32_e32 v238, 16, v220
	v_and_b32_e32 v239, 0xffff0000, v220
	v_pk_mul_f32 v[20:21], v[20:21], v[234:235] op_sel_hi:[1,0]
	v_pk_fma_f32 v[20:21], v[20:21], v[172:173], v[238:239]
	v_lshlrev_b32_e32 v240, 16, v221
	v_and_b32_e32 v241, 0xffff0000, v221
	v_pk_mul_f32 v[22:23], v[22:23], v[234:235] op_sel_hi:[1,0]
	v_pk_fma_f32 v[22:23], v[22:23], v[174:175], v[240:241]
	v_lshlrev_b32_e32 v238, 16, v222
	v_and_b32_e32 v239, 0xffff0000, v222
	v_pk_mul_f32 v[16:17], v[16:17], v[234:235] op_sel_hi:[1,0]
	v_pk_fma_f32 v[16:17], v[16:17], v[176:177], v[238:239]
	v_lshlrev_b32_e32 v240, 16, v223
	v_and_b32_e32 v241, 0xffff0000, v223
	v_pk_mul_f32 v[18:19], v[18:19], v[234:235] op_sel_hi:[1,0]
	v_pk_fma_f32 v[18:19], v[18:19], v[178:179], v[240:241]
	v_pk_mul_f32 v[238:239], v[28:29], v[28:29]
	v_pk_fma_f32 v[238:239], v[30:31], v[30:31], v[238:239]
	v_pk_fma_f32 v[238:239], v[24:25], v[24:25], v[238:239]
	v_pk_fma_f32 v[238:239], v[26:27], v[26:27], v[238:239]
	v_pk_fma_f32 v[238:239], v[20:21], v[20:21], v[238:239]
	v_pk_fma_f32 v[238:239], v[22:23], v[22:23], v[238:239]
	v_pk_fma_f32 v[238:239], v[16:17], v[16:17], v[238:239]
	v_pk_fma_f32 v[238:239], v[18:19], v[18:19], v[238:239]
	v_add_f32_e32 v235, v238, v239
	v_cvt_pk_bf16_f32 v216, v28, v29
	v_cvt_pk_bf16_f32 v217, v30, v31
	v_cvt_pk_bf16_f32 v218, v24, v25
	v_cvt_pk_bf16_f32 v219, v26, v27
	v_cvt_pk_bf16_f32 v220, v20, v21
	v_cvt_pk_bf16_f32 v221, v22, v23
	v_cvt_pk_bf16_f32 v222, v16, v17
	v_cvt_pk_bf16_f32 v223, v18, v19
	v_add_u32_e32 v240, 0x50000, v153
	s_nop 0
	global_store_dwordx4 v240, v[216:219], s[66:67]
	global_store_dwordx4 v240, v[220:223], s[66:67] offset:256
	s_waitcnt vmcnt(10)
	v_lshlrev_b32_e32 v238, 16, v224
	v_and_b32_e32 v239, 0xffff0000, v224
	v_pk_mul_f32 v[12:13], v[12:13], v[236:237] op_sel_hi:[1,0]
	v_pk_fma_f32 v[12:13], v[12:13], v[156:157], v[238:239]
	v_lshlrev_b32_e32 v240, 16, v225
	v_and_b32_e32 v241, 0xffff0000, v225
	v_pk_mul_f32 v[14:15], v[14:15], v[236:237] op_sel_hi:[1,0]
	v_pk_fma_f32 v[14:15], v[14:15], v[158:159], v[240:241]
	v_lshlrev_b32_e32 v238, 16, v226
	v_and_b32_e32 v239, 0xffff0000, v226
	v_pk_mul_f32 v[8:9], v[8:9], v[236:237] op_sel_hi:[1,0]
	v_pk_fma_f32 v[8:9], v[8:9], v[160:161], v[238:239]
	v_lshlrev_b32_e32 v240, 16, v227
	v_and_b32_e32 v241, 0xffff0000, v227
	v_pk_mul_f32 v[10:11], v[10:11], v[236:237] op_sel_hi:[1,0]
	v_pk_fma_f32 v[10:11], v[10:11], v[162:163], v[240:241]
	v_lshlrev_b32_e32 v238, 16, v228
	v_and_b32_e32 v239, 0xffff0000, v228
	v_pk_mul_f32 v[4:5], v[4:5], v[236:237] op_sel_hi:[1,0]
	v_pk_fma_f32 v[4:5], v[4:5], v[172:173], v[238:239]
	v_lshlrev_b32_e32 v240, 16, v229
	v_and_b32_e32 v241, 0xffff0000, v229
	v_pk_mul_f32 v[6:7], v[6:7], v[236:237] op_sel_hi:[1,0]
	v_pk_fma_f32 v[6:7], v[6:7], v[174:175], v[240:241]
	v_lshlrev_b32_e32 v238, 16, v230
	v_and_b32_e32 v239, 0xffff0000, v230
	v_pk_mul_f32 v[0:1], v[0:1], v[236:237] op_sel_hi:[1,0]
	v_pk_fma_f32 v[0:1], v[0:1], v[176:177], v[238:239]
	v_lshlrev_b32_e32 v240, 16, v231
	v_and_b32_e32 v241, 0xffff0000, v231
	v_pk_mul_f32 v[2:3], v[2:3], v[236:237] op_sel_hi:[1,0]
	v_pk_fma_f32 v[2:3], v[2:3], v[178:179], v[240:241]
	v_pk_mul_f32 v[238:239], v[12:13], v[12:13]
	v_pk_fma_f32 v[238:239], v[14:15], v[14:15], v[238:239]
	v_pk_fma_f32 v[238:239], v[8:9], v[8:9], v[238:239]
	v_pk_fma_f32 v[238:239], v[10:11], v[10:11], v[238:239]
	v_pk_fma_f32 v[238:239], v[4:5], v[4:5], v[238:239]
	v_pk_fma_f32 v[238:239], v[6:7], v[6:7], v[238:239]
	v_pk_fma_f32 v[238:239], v[0:1], v[0:1], v[238:239]
	v_pk_fma_f32 v[238:239], v[2:3], v[2:3], v[238:239]
	v_add_f32_e32 v237, v238, v239
	v_cvt_pk_bf16_f32 v224, v12, v13
	v_cvt_pk_bf16_f32 v225, v14, v15
	v_cvt_pk_bf16_f32 v226, v8, v9
	v_cvt_pk_bf16_f32 v227, v10, v11
	v_cvt_pk_bf16_f32 v228, v4, v5
	v_cvt_pk_bf16_f32 v229, v6, v7
	v_cvt_pk_bf16_f32 v230, v0, v1
	v_cvt_pk_bf16_f32 v231, v2, v3
	v_add_u32_e32 v240, 0x58000, v153
	s_nop 0
	global_store_dwordx4 v240, v[224:227], s[66:67]
	global_store_dwordx4 v240, v[228:231], s[66:67] offset:256
	s_nop 1
	ds_bpermute_b32 v156, v194, v145
	ds_bpermute_b32 v157, v194, v155
	ds_bpermute_b32 v158, v194, v165
	ds_bpermute_b32 v159, v194, v171
	ds_bpermute_b32 v160, v194, v193
	ds_bpermute_b32 v161, v194, v233
	ds_bpermute_b32 v162, v194, v235
	ds_bpermute_b32 v163, v194, v237
	s_waitcnt lgkmcnt(0)
	v_add_f32_e32 v145, v145, v156
	v_add_f32_e32 v155, v155, v157
	v_add_f32_e32 v165, v165, v158
	v_add_f32_e32 v171, v171, v159
	v_add_f32_e32 v193, v193, v160
	v_add_f32_e32 v233, v233, v161
	v_add_f32_e32 v235, v235, v162
	v_add_f32_e32 v237, v237, v163
	s_nop 1
	ds_bpermute_b32 v156, v242, v145
	ds_bpermute_b32 v157, v242, v155
	ds_bpermute_b32 v158, v242, v165
	ds_bpermute_b32 v159, v242, v171
	ds_bpermute_b32 v160, v242, v193
	ds_bpermute_b32 v161, v242, v233
	ds_bpermute_b32 v162, v242, v235
	ds_bpermute_b32 v163, v242, v237
	s_waitcnt lgkmcnt(0)
	v_add_f32_e32 v145, v145, v156
	v_add_f32_e32 v155, v155, v157
	v_add_f32_e32 v165, v165, v158
	v_add_f32_e32 v171, v171, v159
	v_add_f32_e32 v193, v193, v160
	v_add_f32_e32 v233, v233, v161
	v_add_f32_e32 v235, v235, v162
	v_add_f32_e32 v237, v237, v163
	global_store_dword v166, v145, s[78:79]
	v_add_u32_e32 v157, 0x400, v166
	global_store_dword v157, v155, s[78:79]
	v_add_u32_e32 v158, 0x800, v166
	global_store_dword v158, v165, s[78:79]
	v_add_u32_e32 v159, 0xc00, v166
	global_store_dword v159, v171, s[78:79]
	v_add_u32_e32 v160, 0x2000, v166
	global_store_dword v160, v193, s[78:79]
	v_add_u32_e32 v161, 0x2400, v166
	global_store_dword v161, v233, s[78:79]
	v_add_u32_e32 v162, 0x2800, v166
	global_store_dword v162, v235, s[78:79]
	v_add_u32_e32 v163, 0x2c00, v166
	global_store_dword v163, v237, s[78:79]
	s_and_b64 vcc, exec, s[0:1]
	s_mov_b64 s[0:1], -1
	s_cbranch_vccnz .LBB0_1144
	s_andn2_b64 vcc, exec, s[10:11]
	s_cbranch_vccnz .LBB0_1143
	s_barrier
	s_branch .LBB0_1143

; __device__ __forceinline__ unsigned xb_ld(unsigned* p)              { return __hip_atomic_load(p, __ATOMIC_RELAXED, __HIP_MEMORY_SCOPE_AGENT); }
; __device__ __forceinline__ unsigned xb_add(unsigned* p, unsigned v) { return __hip_atomic_fetch_add(p, v, __ATOMIC_RELAXED, __HIP_MEMORY_SCOPE_AGENT); }
; #define XB_SPIN(cond, bar) do { unsigned _sp = 0; while (cond) { __builtin_amdgcn_s_sleep(1); \
;     if ((++_sp & 255u) == 0u) { if (xb_ld(&(bar)[XB_TMO])) break; if (_sp > XB_SPIN_CAP) { atomicAdd(&(bar)[XB_TMO], 1u); break; } } } } while (0)
; #define SEAM(k) do { if (IN(k) && IN((k) + 1)) { xcd_barrier(xbar); } } while (0)
; __device__ __forceinline__ void xcd_barrier(const XcdBarrier& b) {
;     asm volatile("s_waitcnt vmcnt(0)" ::: "memory");
;     __syncthreads();
;     if (threadIdx.x == 0) {
;         unsigned* bar = b.bar;
;         __builtin_amdgcn_s_waitcnt(0);
;         unsigned nloc = b.st[0], nx = b.st[1];
;         if (nloc == 0u) { xcd_barrier_complete(bar, b.x, nloc, nx); b.st[0] = nloc; b.st[1] = nx; }
;         const unsigned old = xb_add(&bar[XB_XSUB(b.x)], 1u);
;         const unsigned gen = old / nloc;
;         if (old + 1u == (gen + 1u) * nloc) {
;             __builtin_amdgcn_fence(__ATOMIC_RELEASE, "agent");
;             asm volatile("s_waitcnt vmcnt(0)" ::: "memory");
;             const unsigned og = xb_add(&bar[XB_TOP], 1u);
;             const unsigned tg = og / nx;
;             if (og + 1u == (tg + 1u) * nx) xb_add(&bar[XB_TOPGEN], 1u);
;             else XB_SPIN(xb_ld(&bar[XB_TOPGEN]) == tg, bar);
;             __builtin_amdgcn_fence(__ATOMIC_ACQUIRE, "agent");
;             xb_add(&bar[XB_XGEN(b.x)], 1u);
;             asm volatile("s_waitcnt vmcnt(0)" ::: "memory");
;         } else {
;             XB_SPIN(xb_ld(&bar[XB_XGEN(b.x)]) == gen, bar);
;             __builtin_amdgcn_fence(__ATOMIC_ACQUIRE, "agent");
;             asm volatile("s_waitcnt vmcnt(0)" ::: "memory");
;         }
;     }
;     __syncthreads();
; }
; __global__ void __launch_bounds__(NWAVES * 64, 2) mk_fwd(Args a) {
;     ...
;     SEAM(10);
;     if (IN(11)) ew_phase<false, false>(nullptr, HB, HB, nullptr, FB, PART, a.in[I_F2POST], 0.5f, RS, gw, NGW, lane);
;     SEAM(11);
.LBB0_1163:
	s_cmp_gt_i32 s31, 11
	s_cselect_b64 s[0:1], -1, 0
	s_and_b64 s[4:5], s[6:7], s[0:1]
	s_andn2_b64 vcc, exec, s[4:5]
	s_cbranch_vccnz .LBB0_1213
.LBB0_1213:
	s_cmp_lt_i32 s30, 12
	s_cselect_b64 s[4:5], -1, 0
	s_and_b64 s[8:9], s[4:5], s[0:1]
	s_andn2_b64 vcc, exec, s[8:9]
	s_cbranch_vccnz .LBB0_1259
.LBB0_1259:
	s_cmp_gt_i32 s31, 12
	s_cselect_b64 s[0:1], -1, 0
	s_and_b64 s[4:5], s[8:9], s[0:1]
	s_andn2_b64 vcc, exec, s[4:5]
	s_cbranch_vccnz .LBB0_1309
	s_waitcnt vmcnt(0)
	s_barrier
	v_cmp_eq_u32_e32 vcc, 0, v195
	s_and_saveexec_b64 s[4:5], vcc
	s_cbranch_execz .Ltb1309_done
	s_and_b32 s3, s2, 7
	s_lshl_b32 s3, s3, 3
	s_bfe_u32 s13, s2, 0x30003
	s_or_b32 s3, s3, s13
	s_lshl_b32 s3, s3, 5
	s_add_u32 s8, s28, 0x3903600
	s_addc_u32 s9, s29, 0
	v_mov_b32_e32 v0, s3
	v_mov_b32_e32 v1, 1
	v_mov_b32_e32 v2, 32
	s_mov_b32 s15, 0
	s_cmp_eq_u32 s99, 1
	s_cbranch_scc1 .Ltb1309_fast
	buffer_wbl2 sc1
	s_waitcnt vmcnt(0)
	global_atomic_add v0, v1, s[8:9]

; __device__ __forceinline__ unsigned xb_ld(unsigned* p)              { return __hip_atomic_load(p, __ATOMIC_RELAXED, __HIP_MEMORY_SCOPE_AGENT); }
; __device__ __forceinline__ unsigned xb_add(unsigned* p, unsigned v) { return __hip_atomic_fetch_add(p, v, __ATOMIC_RELAXED, __HIP_MEMORY_SCOPE_AGENT); }
; #define XB_SPIN(cond, bar) do { unsigned _sp = 0; while (cond) { __builtin_amdgcn_s_sleep(1); \
;     if ((++_sp & 255u) == 0u) { if (xb_ld(&(bar)[XB_TMO])) break; if (_sp > XB_SPIN_CAP) { atomicAdd(&(bar)[XB_TMO], 1u); break; } } } } while (0)
; __device__ __forceinline__ void xcd_barrier(const XcdBarrier& b) {
;     asm volatile("s_waitcnt vmcnt(0)" ::: "memory");
;     __syncthreads();
;     if (threadIdx.x == 0) {
;         unsigned* bar = b.bar;
;         __builtin_amdgcn_s_waitcnt(0);
;         unsigned nloc = b.st[0], nx = b.st[1];
;         if (nloc == 0u) { xcd_barrier_complete(bar, b.x, nloc, nx); b.st[0] = nloc; b.st[1] = nx; }
;         const unsigned old = xb_add(&bar[XB_XSUB(b.x)], 1u);
;         const unsigned gen = old / nloc;
;         if (old + 1u == (gen + 1u) * nloc) {
;             __builtin_amdgcn_fence(__ATOMIC_RELEASE, "agent");
;             asm volatile("s_waitcnt vmcnt(0)" ::: "memory");
;             const unsigned og = xb_add(&bar[XB_TOP], 1u);
;             const unsigned tg = og / nx;
;             if (og + 1u == (tg + 1u) * nx) xb_add(&bar[XB_TOPGEN], 1u);
;             else XB_SPIN(xb_ld(&bar[XB_TOPGEN]) == tg, bar);
;             __builtin_amdgcn_fence(__ATOMIC_ACQUIRE, "agent");
;             xb_add(&bar[XB_XGEN(b.x)], 1u);
;             asm volatile("s_waitcnt vmcnt(0)" ::: "memory");
;         } else {
;             XB_SPIN(xb_ld(&bar[XB_XGEN(b.x)]) == gen, bar);
;             __builtin_amdgcn_fence(__ATOMIC_ACQUIRE, "agent");
;             asm volatile("s_waitcnt vmcnt(0)" ::: "memory");
;         }
;     }
;     __syncthreads();
; }
.Ltb1309_sgs:
	global_load_dword v5, v4, s[8:9] sc1
	s_waitcnt vmcnt(0)
	v_cmp_gt_u32_e32 vcc, 32, v5
	s_cmp_lg_u64 vcc, 0
	s_cbranch_scc0 .Ltb1309_sgd
	s_sleep 1
	s_add_u32 s15, s15, 1
	s_cmp_lt_u32 s15, 0x400000
	s_cbranch_scc1 .Ltb1309_sgs

; #define LAS __attribute__((address_space(3)))
; __device__ __forceinline__ void rs_table_fill(LAS unsigned char* lds, const pg8::StaticOrder& S, const float* rs) {
;     int k0 = -1, k1 = -1, k2 = -1, k3 = -1;
;     for (int i = 0;; ++i) { pg8::Unit u; if (!S.next(i, u)) break; const int pm = u.pm;
;         if (pm != k0 && pm != k1 && pm != k2 && pm != k3) { if (k0 < 0) k0 = pm; else if (k1 < 0) k1 = pm; else if (k2 < 0) k2 = pm; else if (k3 < 0) k3 = pm; } }
;     const int tid = threadIdx.x;
;     LAS float* tab = (LAS float*)(lds + RS_TAB_OFF); LAS int* keys = (LAS int*)(lds + RS_KEY_OFF);
;     if (tid < 256) {
;         if (k0 >= 0) tab[tid] = rs[k0 * 256 + tid];
;         if (k1 >= 0) tab[256 + tid] = rs[k1 * 256 + tid];
;         if (k2 >= 0) tab[512 + tid] = rs[k2 * 256 + tid];
;         if (k3 >= 0) tab[768 + tid] = rs[k3 * 256 + tid];
;     }
;     if (tid == 0) { keys[0] = k0; keys[1] = k1; keys[2] = k2; keys[3] = k3; }
;     __syncthreads();
; template <bool SRC_F32, bool FINAL, int R> __device__ __forceinline__ void ew_compute(const EwSet<SRC_F32, R>& S, int rb, const f32x4 (&g)[4], bf16* hb_out, float* out32, float scale, float* rs_out, int lane) {
;     ...
;         if (!FINAL) { const float tot = wave_sum(s2); if (lane == 0) rs_out[rb + i] = 1.0f / sqrtf(tot * (1.f / D) + EPS); }
.LBB0_1325:
	s_movk_i32 s0, 0x100
	v_cmp_gt_u32_e32 vcc, s0, v195
	s_and_saveexec_b64 s[0:1], vcc
	s_cbranch_execz .LBB0_1334
	s_cmp_lt_i32 s8, 0
	s_cbranch_scc1 .LBB0_1328
	v_lshl_or_b32 v0, s8, 8, v195
	v_mov_b32_e32 v1, 0
	s_add_u32 s80, s28, 0x4c00000
	s_addc_u32 s81, s29, 0
	v_lshlrev_b32_e32 v2, 6, v0
	v_lshlrev_b32_e32 v3, 2, v0
	global_load_dwordx4 v[4:7], v2, s[80:81]
	global_load_dwordx4 v[8:11], v2, s[80:81] offset:16
	global_load_dwordx4 v[12:15], v2, s[80:81] offset:32
	global_load_dwordx4 v[16:19], v2, s[80:81] offset:48
	v_lshl_add_u32 v1, v195, 2, 0
	v_add_u32_e32 v1, 0x20000, v1
	s_waitcnt vmcnt(0)
	v_add_f32_e32 v0, v4, v5
	v_add_f32_e32 v0, v6, v0
	v_add_f32_e32 v0, v7, v0
	v_add_f32_e32 v0, v8, v0
	v_add_f32_e32 v0, v9, v0
	v_add_f32_e32 v0, v10, v0
	v_add_f32_e32 v0, v11, v0
	v_add_f32_e32 v0, v12, v0
	v_add_f32_e32 v0, v13, v0
	v_add_f32_e32 v0, v14, v0
	v_add_f32_e32 v0, v15, v0
	v_add_f32_e32 v0, v16, v0
	v_add_f32_e32 v0, v17, v0
	v_add_f32_e32 v0, v18, v0
	v_add_f32_e32 v0, v19, v0
	v_mul_f32_e32 v0, 0x3a800000, v0
	v_add_f32_e32 v0, 0x358637bd, v0
	v_rsq_f32_e32 v0, v0
	s_nop 0
	global_store_dword v3, v0, s[92:93]
	ds_write_b32 v1, v0
.LBB0_1328:
	s_cmp_lt_i32 s9, 0
	s_cbranch_scc1 .LBB0_1330
	v_lshl_or_b32 v0, s9, 8, v195
	v_mov_b32_e32 v1, 0
	v_lshlrev_b32_e32 v2, 6, v0
	v_lshlrev_b32_e32 v3, 2, v0
	global_load_dwordx4 v[4:7], v2, s[80:81]
	global_load_dwordx4 v[8:11], v2, s[80:81] offset:16
	global_load_dwordx4 v[12:15], v2, s[80:81] offset:32
	global_load_dwordx4 v[16:19], v2, s[80:81] offset:48
	s_add_i32 s4, 0, 0x20000
	v_lshl_add_u32 v1, v195, 2, s4
	s_waitcnt vmcnt(0)
	v_add_f32_e32 v0, v4, v5
	v_add_f32_e32 v0, v6, v0
	v_add_f32_e32 v0, v7, v0
	v_add_f32_e32 v0, v8, v0
	v_add_f32_e32 v0, v9, v0
	v_add_f32_e32 v0, v10, v0
	v_add_f32_e32 v0, v11, v0
	v_add_f32_e32 v0, v12, v0
	v_add_f32_e32 v0, v13, v0
	v_add_f32_e32 v0, v14, v0
	v_add_f32_e32 v0, v15, v0
	v_add_f32_e32 v0, v16, v0
	v_add_f32_e32 v0, v17, v0
	v_add_f32_e32 v0, v18, v0
	v_add_f32_e32 v0, v19, v0
	v_mul_f32_e32 v0, 0x3a800000, v0
	v_add_f32_e32 v0, 0x358637bd, v0
	v_rsq_f32_e32 v0, v0
	s_nop 0
	global_store_dword v3, v0, s[92:93]
	ds_write_b32 v1, v0 offset:1024
.LBB0_1330:
	s_cmp_lt_i32 s14, 0
	s_cbranch_scc1 .LBB0_1332
	v_lshl_or_b32 v0, s14, 8, v195
	v_mov_b32_e32 v1, 0
	v_lshlrev_b32_e32 v2, 6, v0
	v_lshlrev_b32_e32 v3, 2, v0
	global_load_dwordx4 v[4:7], v2, s[80:81]
	global_load_dwordx4 v[8:11], v2, s[80:81] offset:16
	global_load_dwordx4 v[12:15], v2, s[80:81] offset:32
	global_load_dwordx4 v[16:19], v2, s[80:81] offset:48
	s_add_i32 s4, 0, 0x20000
	v_lshl_add_u32 v1, v195, 2, s4
	s_waitcnt vmcnt(0)
	v_add_f32_e32 v0, v4, v5
	v_add_f32_e32 v0, v6, v0
	v_add_f32_e32 v0, v7, v0
	v_add_f32_e32 v0, v8, v0
	v_add_f32_e32 v0, v9, v0
	v_add_f32_e32 v0, v10, v0
	v_add_f32_e32 v0, v11, v0
	v_add_f32_e32 v0, v12, v0
	v_add_f32_e32 v0, v13, v0
	v_add_f32_e32 v0, v14, v0
	v_add_f32_e32 v0, v15, v0
	v_add_f32_e32 v0, v16, v0
	v_add_f32_e32 v0, v17, v0
	v_add_f32_e32 v0, v18, v0
	v_add_f32_e32 v0, v19, v0
	v_mul_f32_e32 v0, 0x3a800000, v0
	v_add_f32_e32 v0, 0x358637bd, v0
	v_rsq_f32_e32 v0, v0
	s_nop 0
	global_store_dword v3, v0, s[92:93]
	ds_write_b32 v1, v0 offset:2048
